# speedup vs baseline: 1.0078x; 1.0061x over previous
; #define PG8_STAGE(bufoff, gbase, voff) do { _Pragma("unroll") for (int _i = 0; _i < 2; ++_i) \
;         __builtin_amdgcn_global_load_lds((const unsigned*)((const char*)(gbase) + (voff)[_i]), (LAS unsigned*)(lds + (bufoff) + ldsw + _i * 8192), 16, 0, 0); } while (0)
; #define PG8_LDA(dst, b, h) do { _Pragma("unroll") for (int m = 0; m < 4; ++m) _Pragma("unroll") for (int k = 0; k < 2; ++k) dst[m][k] = *(const LAS bf16x8*)(lds + PG8_SA(b, h) + aoff + m * 2048 + k * 1024); } while (0)
; #define PG8_LDB(dst, b, h) do { _Pragma("unroll") for (int n = 0; n < 2; ++n) _Pragma("unroll") for (int k = 0; k < 2; ++k) dst[n][k] = *(const LAS bf16x8*)(lds + PG8_SB(b, h) + boff + n * 2048 + k * 1024); } while (0)
; #define PG8_MMA(ai, bj, At, Bt) do { __builtin_amdgcn_s_setprio(1); _Pragma("unroll") for (int m = 0; m < 4; ++m) _Pragma("unroll") for (int n = 0; n < 2; ++n) _Pragma("unroll") for (int k = 0; k < 2; ++k) \
;         acc[ai][bj][m][n] = __builtin_amdgcn_mfma_f32_16x16x32_bf16(Bt[n][k], At[m][k], acc[ai][bj][m][n], 0, 0, 0); __builtin_amdgcn_s_setprio(0); } while (0)
; #define PG8_WAIT_V(n) asm volatile("s_waitcnt vmcnt(" #n ")" ::: "memory")
; #define PG8_WAIT_L(n) asm volatile("s_waitcnt lgkmcnt(" #n ")" ::: "memory")
; #define PG8_BAR __builtin_amdgcn_s_barrier()
; #define PG8_SCHED __builtin_amdgcn_sched_barrier(0)
;     ...
;             const char* a1 = cA + (size_t)(t + 1) * kstep;
;             const char* a2 = last ? nA : cA + (size_t)(t + 2) * kstep; const char* b2 = last ? nB : cB + (size_t)(t + 2) * kstep;
;             const char* a3 = a2 + kstep; const char* b3 = b2 + kstep;
;             PG8_LDB(B0, 0, 0); PG8_SCHED; PG8_LDA(At, 0, 0); PG8_STAGE(PG8_SA(1, 1), a1 + hstep, voffA);
;             PG8_WAIT_L(8); PG8_BAR; PG8_WAIT_L(0); PG8_MMA(0, 0, At, B0); PG8_BAR; PG8_SCHED;
;             PG8_LDB(B1, 0, 1); PG8_STAGE(PG8_SB(0, 0), b2, voffB);
;             PG8_BAR; PG8_WAIT_L(0); PG8_MMA(0, 1, At, B1); PG8_BAR;
;             PG8_LDA(At, 0, 1); PG8_STAGE(PG8_SA(0, 0), a2, voffA);
;             PG8_BAR; PG8_WAIT_L(0); PG8_MMA(1, 0, At, B0); PG8_BAR; PG8_SCHED;
;             PG8_STAGE(PG8_SB(0, 1), b2 + hstep, voffB);
;             PG8_WAIT_V(6); PG8_BAR; PG8_MMA(1, 1, At, B1); PG8_BAR;
.LBB0_120:
	s_add_i32 s44, s2, 2
	s_add_u32 s10, s8, 0x100
	s_addc_u32 s11, s9, 0
	s_add_i32 s35, 0, 0x10000
	v_add_u32_e32 v156, s35, v145
	ds_read_b128 v[140:143], v156
	ds_read_b128 v[148:151], v156 offset:1024
	ds_read_b128 v[152:155], v156 offset:2048
	ds_read_b128 v[156:159], v156 offset:3072
	s_cmp_eq_u32 s41, s2
	s_cselect_b32 s2, s6, s10
	s_cselect_b32 s3, s7, s11
	s_cselect_b32 s13, s19, s43
	s_cselect_b32 s12, s18, s42
	v_lshl_add_u64 v[192:193], s[8:9], 0, v[136:137]
	s_add_i32 m0, s21, 0xc000
	ds_read_b128 v[160:163], v147
	ds_read_b128 v[164:167], v147 offset:1024
	ds_read_b128 v[168:171], v147 offset:2048
	ds_read_b128 v[172:175], v147 offset:3072
	ds_read_b128 v[176:179], v147 offset:4096
	ds_read_b128 v[180:183], v147 offset:5120
	ds_read_b128 v[184:187], v147 offset:6144
	ds_read_b128 v[188:191], v147 offset:7168
	global_load_lds_dwordx4 v[192:193], off
	v_lshl_add_u64 v[192:193], s[8:9], 0, v[138:139]
	s_add_i32 m0, s21, 0xe000
	s_nop 0
	global_load_lds_dwordx4 v[192:193], off
	s_waitcnt lgkmcnt(8)
	s_barrier
	s_waitcnt lgkmcnt(0)
	s_setprio 0
	s_waitcnt lgkmcnt(0)
	v_mfma_f32_16x16x32_bf16 v[126:129], v[140:143], v[160:163], v[126:129]
	v_mfma_f32_16x16x32_bf16 v[122:125], v[152:155], v[160:163], v[122:125]
	v_mfma_f32_16x16x32_bf16 v[110:113], v[140:143], v[168:171], v[110:113]
	v_mfma_f32_16x16x32_bf16 v[106:109], v[152:155], v[168:171], v[106:109]
	v_mfma_f32_16x16x32_bf16 v[94:97], v[140:143], v[176:179], v[94:97]
	v_mfma_f32_16x16x32_bf16 v[90:93], v[152:155], v[176:179], v[90:93]
	v_mfma_f32_16x16x32_bf16 v[78:81], v[140:143], v[184:187], v[78:81]
	v_mfma_f32_16x16x32_bf16 v[74:77], v[152:155], v[184:187], v[74:77]
	v_mfma_f32_16x16x32_bf16 v[126:129], v[148:151], v[164:167], v[126:129]
	v_mfma_f32_16x16x32_bf16 v[122:125], v[156:159], v[164:167], v[122:125]
	v_mfma_f32_16x16x32_bf16 v[110:113], v[148:151], v[172:175], v[110:113]
	v_mfma_f32_16x16x32_bf16 v[106:109], v[156:159], v[172:175], v[106:109]
	v_mfma_f32_16x16x32_bf16 v[94:97], v[148:151], v[180:183], v[94:97]
	v_mfma_f32_16x16x32_bf16 v[90:93], v[156:159], v[180:183], v[90:93]
	v_mfma_f32_16x16x32_bf16 v[78:81], v[148:151], v[188:191], v[78:81]
	v_mfma_f32_16x16x32_bf16 v[74:77], v[156:159], v[188:191], v[74:77]
	s_setprio 1
	s_barrier
	s_add_i32 s45, 0, 0x14000
	v_add_u32_e32 v208, s45, v145
	s_add_i32 s8, s35, s20
	ds_read_b128 v[192:195], v208
	ds_read_b128 v[196:199], v208 offset:1024
	ds_read_b128 v[220:223], v208 offset:2048
	ds_read_b128 v[224:227], v208 offset:3072
	v_lshl_add_u64 v[208:209], s[12:13], 0, v[64:65]
	s_mov_b32 m0, s8
	v_lshl_add_u64 v[210:211], s[12:13], 0, v[134:135]
	global_load_lds_dwordx4 v[208:209], off
	s_add_i32 m0, s8, 0x2000
	s_nop 0
	global_load_lds_dwordx4 v[210:211], off
	s_barrier
	s_waitcnt lgkmcnt(0)
	s_setprio 0
	s_waitcnt lgkmcnt(0)
	v_mfma_f32_16x16x32_bf16 v[118:121], v[192:195], v[160:163], v[118:121]
	v_mfma_f32_16x16x32_bf16 v[114:117], v[220:223], v[160:163], v[114:117]
	v_mfma_f32_16x16x32_bf16 v[102:105], v[192:195], v[168:171], v[102:105]
	v_mfma_f32_16x16x32_bf16 v[98:101], v[220:223], v[168:171], v[98:101]
	v_mfma_f32_16x16x32_bf16 v[86:89], v[192:195], v[176:179], v[86:89]
	v_mfma_f32_16x16x32_bf16 v[82:85], v[220:223], v[176:179], v[82:85]
	v_mfma_f32_16x16x32_bf16 v[70:73], v[192:195], v[184:187], v[70:73]
	v_mfma_f32_16x16x32_bf16 v[66:69], v[220:223], v[184:187], v[66:69]
	v_mfma_f32_16x16x32_bf16 v[118:121], v[196:199], v[164:167], v[118:121]
	v_mfma_f32_16x16x32_bf16 v[114:117], v[224:227], v[164:167], v[114:117]
	v_mfma_f32_16x16x32_bf16 v[102:105], v[196:199], v[172:175], v[102:105]
	v_mfma_f32_16x16x32_bf16 v[98:101], v[224:227], v[172:175], v[98:101]
	v_mfma_f32_16x16x32_bf16 v[86:89], v[196:199], v[180:183], v[86:89]
	v_mfma_f32_16x16x32_bf16 v[82:85], v[224:227], v[180:183], v[82:85]
	v_mfma_f32_16x16x32_bf16 v[70:73], v[196:199], v[188:191], v[70:73]
	v_mfma_f32_16x16x32_bf16 v[66:69], v[224:227], v[188:191], v[66:69]
	s_setprio 1
	s_mov_b32 m0, s21
	v_lshl_add_u64 v[212:213], s[2:3], 0, v[130:131]
	s_barrier
	ds_read_b128 v[160:163], v147 offset:16384
	ds_read_b128 v[164:167], v147 offset:17408
	ds_read_b128 v[168:171], v147 offset:18432
	ds_read_b128 v[172:175], v147 offset:19456
	ds_read_b128 v[176:179], v147 offset:20480
	ds_read_b128 v[180:183], v147 offset:21504
	ds_read_b128 v[184:187], v147 offset:22528
	ds_read_b128 v[188:191], v147 offset:23552
	global_load_lds_dwordx4 v[212:213], off
	v_lshl_add_u64 v[214:215], s[2:3], 0, v[132:133]
	s_mov_b32 m0, s22
	s_nop 0
	global_load_lds_dwordx4 v[214:215], off
	s_barrier
	s_waitcnt lgkmcnt(0)
	s_setprio 0
	s_waitcnt lgkmcnt(0)
	v_mfma_f32_16x16x32_bf16 v[60:63], v[140:143], v[160:163], v[60:63]
	v_mfma_f32_16x16x32_bf16 v[56:59], v[152:155], v[160:163], v[56:59]
	v_mfma_f32_16x16x32_bf16 v[44:47], v[140:143], v[168:171], v[44:47]
	v_mfma_f32_16x16x32_bf16 v[40:43], v[152:155], v[168:171], v[40:43]
	v_mfma_f32_16x16x32_bf16 v[28:31], v[140:143], v[176:179], v[28:31]
	v_mfma_f32_16x16x32_bf16 v[24:27], v[152:155], v[176:179], v[24:27]
	v_mfma_f32_16x16x32_bf16 v[12:15], v[140:143], v[184:187], v[12:15]
	v_mfma_f32_16x16x32_bf16 v[8:11], v[152:155], v[184:187], v[8:11]
	v_mfma_f32_16x16x32_bf16 v[60:63], v[148:151], v[164:167], v[60:63]
	v_mfma_f32_16x16x32_bf16 v[56:59], v[156:159], v[164:167], v[56:59]
	v_mfma_f32_16x16x32_bf16 v[44:47], v[148:151], v[172:175], v[44:47]
	v_mfma_f32_16x16x32_bf16 v[40:43], v[156:159], v[172:175], v[40:43]
	v_mfma_f32_16x16x32_bf16 v[28:31], v[148:151], v[180:183], v[28:31]
	v_mfma_f32_16x16x32_bf16 v[24:27], v[156:159], v[180:183], v[24:27]
	v_mfma_f32_16x16x32_bf16 v[12:15], v[148:151], v[188:191], v[12:15]
	v_mfma_f32_16x16x32_bf16 v[8:11], v[156:159], v[188:191], v[8:11]
	s_setprio 1
	s_barrier
; #define PG8_STAGE(bufoff, gbase, voff) do { _Pragma("unroll") for (int _i = 0; _i < 2; ++_i) \
;         __builtin_amdgcn_global_load_lds((const unsigned*)((const char*)(gbase) + (voff)[_i]), (LAS unsigned*)(lds + (bufoff) + ldsw + _i * 8192), 16, 0, 0); } while (0)
; #define PG8_LDA(dst, b, h) do { _Pragma("unroll") for (int m = 0; m < 4; ++m) _Pragma("unroll") for (int k = 0; k < 2; ++k) dst[m][k] = *(const LAS bf16x8*)(lds + PG8_SA(b, h) + aoff + m * 2048 + k * 1024); } while (0)
; #define PG8_LDB(dst, b, h) do { _Pragma("unroll") for (int n = 0; n < 2; ++n) _Pragma("unroll") for (int k = 0; k < 2; ++k) dst[n][k] = *(const LAS bf16x8*)(lds + PG8_SB(b, h) + boff + n * 2048 + k * 1024); } while (0)
; #define PG8_MMA(ai, bj, At, Bt) do { __builtin_amdgcn_s_setprio(1); _Pragma("unroll") for (int m = 0; m < 4; ++m) _Pragma("unroll") for (int n = 0; n < 2; ++n) _Pragma("unroll") for (int k = 0; k < 2; ++k) \
;         acc[ai][bj][m][n] = __builtin_amdgcn_mfma_f32_16x16x32_bf16(Bt[n][k], At[m][k], acc[ai][bj][m][n], 0, 0, 0); __builtin_amdgcn_s_setprio(0); } while (0)
; #define PG8_WAIT_V(n) asm volatile("s_waitcnt vmcnt(" #n ")" ::: "memory")
; #define PG8_WAIT_L(n) asm volatile("s_waitcnt lgkmcnt(" #n ")" ::: "memory")
; #define PG8_BAR __builtin_amdgcn_s_barrier()
; #define PG8_SCHED __builtin_amdgcn_sched_barrier(0)
;     ...
;             PG8_STAGE(PG8_SB(0, 1), b2 + hstep, voffB);
;             PG8_WAIT_V(6); PG8_BAR; PG8_MMA(1, 1, At, B1); PG8_BAR;
;             PG8_LDB(B0, 1, 0); PG8_SCHED; PG8_LDA(At, 1, 0); PG8_STAGE(PG8_SA(0, 1), a2 + hstep, voffA);
;             PG8_WAIT_L(8); PG8_BAR; PG8_WAIT_L(0); PG8_MMA(0, 0, At, B0); PG8_BAR; PG8_SCHED;
;             PG8_LDB(B1, 1, 1); PG8_STAGE(PG8_SB(1, 0), b3, voffB);
;             PG8_BAR; PG8_WAIT_L(0); PG8_MMA(0, 1, At, B1); PG8_BAR;
;             PG8_LDA(At, 1, 1); PG8_STAGE(PG8_SA(1, 0), a3, voffA);
;             PG8_BAR; PG8_WAIT_L(0); PG8_MMA(1, 0, At, B0); PG8_BAR; PG8_SCHED;
;             PG8_STAGE(PG8_SB(1, 1), b3 + hstep, voffB);
	s_add_u32 s8, s12, 0x84000
	s_addc_u32 s9, s13, 0
	s_add_i32 s35, s45, s20
	v_lshl_add_u64 v[140:141], s[8:9], 0, v[64:65]
	s_mov_b32 m0, s35
	s_nop 0
	global_load_lds_dwordx4 v[140:141], off
	v_lshl_add_u64 v[140:141], s[8:9], 0, v[134:135]
	s_add_i32 m0, s35, 0x2000
	s_nop 0
	global_load_lds_dwordx4 v[140:141], off
	s_waitcnt vmcnt(6)
	s_barrier
	s_setprio 0
	v_mfma_f32_16x16x32_bf16 v[52:55], v[192:195], v[160:163], v[52:55]
	v_mfma_f32_16x16x32_bf16 v[48:51], v[220:223], v[160:163], v[48:51]
	v_mfma_f32_16x16x32_bf16 v[36:39], v[192:195], v[168:171], v[36:39]
	v_mfma_f32_16x16x32_bf16 v[32:35], v[220:223], v[168:171], v[32:35]
	v_mfma_f32_16x16x32_bf16 v[20:23], v[192:195], v[176:179], v[20:23]
	v_mfma_f32_16x16x32_bf16 v[16:19], v[220:223], v[176:179], v[16:19]
	v_mfma_f32_16x16x32_bf16 v[4:7], v[192:195], v[184:187], v[4:7]
	v_mfma_f32_16x16x32_bf16 v[0:3], v[220:223], v[184:187], v[0:3]
	v_mfma_f32_16x16x32_bf16 v[52:55], v[196:199], v[164:167], v[52:55]
	v_mfma_f32_16x16x32_bf16 v[48:51], v[224:227], v[164:167], v[48:51]
	v_mfma_f32_16x16x32_bf16 v[36:39], v[196:199], v[172:175], v[36:39]
	v_mfma_f32_16x16x32_bf16 v[32:35], v[224:227], v[172:175], v[32:35]
	v_mfma_f32_16x16x32_bf16 v[20:23], v[196:199], v[180:183], v[20:23]
	v_mfma_f32_16x16x32_bf16 v[16:19], v[224:227], v[180:183], v[16:19]
	v_mfma_f32_16x16x32_bf16 v[4:7], v[196:199], v[188:191], v[4:7]
	v_mfma_f32_16x16x32_bf16 v[0:3], v[224:227], v[188:191], v[0:3]
	s_setprio 1
	s_add_i32 s8, 0, 0x18000
	v_add_u32_e32 v156, s8, v145
	s_barrier
	ds_read_b128 v[140:143], v156
	ds_read_b128 v[148:151], v156 offset:1024
	ds_read_b128 v[152:155], v156 offset:2048
	ds_read_b128 v[156:159], v156 offset:3072
	s_add_u32 s2, s2, 0x84000
	s_addc_u32 s3, s3, 0
	s_mov_b32 m0, s23
	v_lshl_add_u64 v[192:193], s[2:3], 0, v[130:131]
	ds_read_b128 v[160:163], v147 offset:32768
	ds_read_b128 v[164:167], v147 offset:33792
	ds_read_b128 v[168:171], v147 offset:34816
	ds_read_b128 v[172:175], v147 offset:35840
	ds_read_b128 v[176:179], v147 offset:36864
	ds_read_b128 v[180:183], v147 offset:37888
	ds_read_b128 v[184:187], v147 offset:38912
	ds_read_b128 v[188:191], v147 offset:39936
	global_load_lds_dwordx4 v[192:193], off
	v_lshl_add_u64 v[192:193], s[2:3], 0, v[132:133]
	s_mov_b32 m0, s24
	s_nop 0
	global_load_lds_dwordx4 v[192:193], off
	s_waitcnt lgkmcnt(8)
	s_barrier
	s_waitcnt lgkmcnt(0)
	s_setprio 0
	s_waitcnt lgkmcnt(0)
	v_mfma_f32_16x16x32_bf16 v[126:129], v[140:143], v[160:163], v[126:129]
	v_mfma_f32_16x16x32_bf16 v[122:125], v[152:155], v[160:163], v[122:125]
	v_mfma_f32_16x16x32_bf16 v[110:113], v[140:143], v[168:171], v[110:113]
	v_mfma_f32_16x16x32_bf16 v[106:109], v[152:155], v[168:171], v[106:109]
	v_mfma_f32_16x16x32_bf16 v[94:97], v[140:143], v[176:179], v[94:97]
	v_mfma_f32_16x16x32_bf16 v[90:93], v[152:155], v[176:179], v[90:93]
	v_mfma_f32_16x16x32_bf16 v[78:81], v[140:143], v[184:187], v[78:81]
	v_mfma_f32_16x16x32_bf16 v[74:77], v[152:155], v[184:187], v[74:77]
	v_mfma_f32_16x16x32_bf16 v[126:129], v[148:151], v[164:167], v[126:129]
	v_mfma_f32_16x16x32_bf16 v[122:125], v[156:159], v[164:167], v[122:125]
	v_mfma_f32_16x16x32_bf16 v[110:113], v[148:151], v[172:175], v[110:113]
	v_mfma_f32_16x16x32_bf16 v[106:109], v[156:159], v[172:175], v[106:109]
	v_mfma_f32_16x16x32_bf16 v[94:97], v[148:151], v[180:183], v[94:97]
	v_mfma_f32_16x16x32_bf16 v[90:93], v[156:159], v[180:183], v[90:93]
	v_mfma_f32_16x16x32_bf16 v[78:81], v[148:151], v[188:191], v[78:81]
	v_mfma_f32_16x16x32_bf16 v[74:77], v[156:159], v[188:191], v[74:77]
	s_setprio 1
	s_barrier
	s_add_i32 s9, 0, 0x1c000
	s_add_i32 s2, s8, s20
	v_add_u32_e32 v219, s9, v145
	v_lshl_add_u64 v[208:209], v[208:209], 0, s[16:17]
	s_mov_b32 m0, s2
	ds_read_b128 v[192:195], v219
	ds_read_b128 v[196:199], v219 offset:1024
	ds_read_b128 v[220:223], v219 offset:2048
	ds_read_b128 v[224:227], v219 offset:3072
	global_load_lds_dwordx4 v[208:209], off
	v_lshl_add_u64 v[208:209], v[210:211], 0, s[16:17]
	s_add_i32 m0, s2, 0x2000
	s_nop 0
	global_load_lds_dwordx4 v[208:209], off
	s_barrier
	s_waitcnt lgkmcnt(0)
	s_setprio 0
	s_waitcnt lgkmcnt(0)
	v_mfma_f32_16x16x32_bf16 v[118:121], v[192:195], v[160:163], v[118:121]
	v_mfma_f32_16x16x32_bf16 v[114:117], v[220:223], v[160:163], v[114:117]
	v_mfma_f32_16x16x32_bf16 v[102:105], v[192:195], v[168:171], v[102:105]
	v_mfma_f32_16x16x32_bf16 v[98:101], v[220:223], v[168:171], v[98:101]
	v_mfma_f32_16x16x32_bf16 v[86:89], v[192:195], v[176:179], v[86:89]
	v_mfma_f32_16x16x32_bf16 v[82:85], v[220:223], v[176:179], v[82:85]
	v_mfma_f32_16x16x32_bf16 v[70:73], v[192:195], v[184:187], v[70:73]
	v_mfma_f32_16x16x32_bf16 v[66:69], v[220:223], v[184:187], v[66:69]
	v_mfma_f32_16x16x32_bf16 v[118:121], v[196:199], v[164:167], v[118:121]
	v_mfma_f32_16x16x32_bf16 v[114:117], v[224:227], v[164:167], v[114:117]
	v_mfma_f32_16x16x32_bf16 v[102:105], v[196:199], v[172:175], v[102:105]
	v_mfma_f32_16x16x32_bf16 v[98:101], v[224:227], v[172:175], v[98:101]
	v_mfma_f32_16x16x32_bf16 v[86:89], v[196:199], v[180:183], v[86:89]
	v_mfma_f32_16x16x32_bf16 v[82:85], v[224:227], v[180:183], v[82:85]
	v_mfma_f32_16x16x32_bf16 v[70:73], v[196:199], v[188:191], v[70:73]
	v_mfma_f32_16x16x32_bf16 v[66:69], v[224:227], v[188:191], v[66:69]
	s_setprio 1
	s_mov_b32 m0, s25
	v_lshl_add_u64 v[208:209], v[212:213], 0, s[16:17]
	s_barrier
	ds_read_b128 v[160:163], v147 offset:49152
	ds_read_b128 v[164:167], v147 offset:50176
	ds_read_b128 v[168:171], v147 offset:51200
	ds_read_b128 v[172:175], v147 offset:52224
	ds_read_b128 v[176:179], v147 offset:53248
	ds_read_b128 v[180:183], v147 offset:54272
	ds_read_b128 v[184:187], v147 offset:55296
	ds_read_b128 v[188:191], v147 offset:56320
	global_load_lds_dwordx4 v[208:209], off
	v_lshl_add_u64 v[208:209], v[214:215], 0, s[16:17]
	s_mov_b32 m0, s26
	s_nop 0
	global_load_lds_dwordx4 v[208:209], off
	s_barrier
; __device__ __forceinline__ unsigned cvt_pk_bf16(float lo, float hi) { unsigned r; asm volatile("v_cvt_pk_bf16_f32 %0, %1, %2" : "=v"(r) : "v"(lo), "v"(hi)); return r; }
; #define PG8_STAGE(bufoff, gbase, voff) do { _Pragma("unroll") for (int _i = 0; _i < 2; ++_i) \
;         __builtin_amdgcn_global_load_lds((const unsigned*)((const char*)(gbase) + (voff)[_i]), (LAS unsigned*)(lds + (bufoff) + ldsw + _i * 8192), 16, 0, 0); } while (0)
; #define PG8_LDA(dst, b, h) do { _Pragma("unroll") for (int m = 0; m < 4; ++m) _Pragma("unroll") for (int k = 0; k < 2; ++k) dst[m][k] = *(const LAS bf16x8*)(lds + PG8_SA(b, h) + aoff + m * 2048 + k * 1024); } while (0)
; #define PG8_MMA(ai, bj, At, Bt) do { __builtin_amdgcn_s_setprio(1); _Pragma("unroll") for (int m = 0; m < 4; ++m) _Pragma("unroll") for (int n = 0; n < 2; ++n) _Pragma("unroll") for (int k = 0; k < 2; ++k) \
;         acc[ai][bj][m][n] = __builtin_amdgcn_mfma_f32_16x16x32_bf16(Bt[n][k], At[m][k], acc[ai][bj][m][n], 0, 0, 0); __builtin_amdgcn_s_setprio(0); } while (0)
; #define PG8_WAIT_V(n) asm volatile("s_waitcnt vmcnt(" #n ")" ::: "memory")
; #define PG8_WAIT_L(n) asm volatile("s_waitcnt lgkmcnt(" #n ")" ::: "memory")
;     __device__ __forceinline__ void operator()(const f32x4 (&acc)[2][2][4][2], const Unit& u, int wr, int wc, int fr, int fq) const {
;         const int row0 = u.pm * BM + wr * 64 + fr, col0 = u.pn * BM + wc * 32 + 8 * fq;
; #pragma unroll
;         for (int ai = 0; ai < 2; ++ai)
; #pragma unroll
;             for (int m = 0; m < 4; ++m) { bf16_t* rowp = O + (size_t)(row0 + ai * HALF + m * 16) * LDF + col0;
; #pragma unroll
;                 for (int bj = 0; bj < 2; ++bj) { f32x4 v0 = acc[ai][bj][m][0], v1 = acc[ai][bj][m][1];
; #pragma unroll
;                     for (int j = 0; j < 4; ++j) { const float a = fmaxf(v0[j], 0.f), b = fmaxf(v1[j], 0.f); v0[j] = a * a; v1[j] = b * b; }
;                     u32x4 w; w.x = cvt_pk_bf16(v0[0], v0[1]); w.y = cvt_pk_bf16(v0[2], v0[3]); w.z = cvt_pk_bf16(v1[0], v1[1]); w.w = cvt_pk_bf16(v1[2], v1[3]);
;                     *(u32x4*)(rowp + bj * HALF) = w; } }
;     ...
;             PG8_LDA(At, 1, 1); PG8_STAGE(PG8_SA(1, 0), a3, voffA);
;             PG8_BAR; PG8_WAIT_L(0); PG8_MMA(1, 0, At, B0); PG8_BAR; PG8_SCHED;
;             PG8_STAGE(PG8_SB(1, 1), b3 + hstep, voffB);
;             PG8_WAIT_V(6); PG8_BAR; PG8_MMA(1, 1, At, B1); PG8_BAR;
	s_waitcnt lgkmcnt(0)
	s_setprio 0
	s_waitcnt lgkmcnt(0)
	v_mfma_f32_16x16x32_bf16 v[60:63], v[140:143], v[160:163], v[60:63]
	v_mfma_f32_16x16x32_bf16 v[56:59], v[152:155], v[160:163], v[56:59]
	v_mfma_f32_16x16x32_bf16 v[44:47], v[140:143], v[168:171], v[44:47]
	v_mfma_f32_16x16x32_bf16 v[40:43], v[152:155], v[168:171], v[40:43]
	v_mfma_f32_16x16x32_bf16 v[28:31], v[140:143], v[176:179], v[28:31]
	v_mfma_f32_16x16x32_bf16 v[24:27], v[152:155], v[176:179], v[24:27]
	v_mfma_f32_16x16x32_bf16 v[12:15], v[140:143], v[184:187], v[12:15]
	v_mfma_f32_16x16x32_bf16 v[8:11], v[152:155], v[184:187], v[8:11]
	v_mfma_f32_16x16x32_bf16 v[60:63], v[148:151], v[164:167], v[60:63]
	v_mfma_f32_16x16x32_bf16 v[56:59], v[156:159], v[164:167], v[56:59]
	v_mfma_f32_16x16x32_bf16 v[44:47], v[148:151], v[172:175], v[44:47]
	v_mfma_f32_16x16x32_bf16 v[40:43], v[156:159], v[172:175], v[40:43]
	v_mfma_f32_16x16x32_bf16 v[28:31], v[148:151], v[180:183], v[28:31]
	v_mfma_f32_16x16x32_bf16 v[24:27], v[156:159], v[180:183], v[24:27]
	v_mfma_f32_16x16x32_bf16 v[12:15], v[148:151], v[188:191], v[12:15]
	v_mfma_f32_16x16x32_bf16 v[8:11], v[156:159], v[188:191], v[8:11]
	s_setprio 1
	s_barrier
	s_add_u32 s2, s12, 0x84080
	s_addc_u32 s3, s13, 0
	s_add_i32 s8, s9, s20
	v_lshl_add_u64 v[140:141], s[2:3], 0, v[64:65]
	s_mov_b32 m0, s8
	s_nop 0
	global_load_lds_dwordx4 v[140:141], off
	v_lshl_add_u64 v[140:141], s[2:3], 0, v[134:135]
	s_add_i32 m0, s8, 0x2000
	s_nop 0
	global_load_lds_dwordx4 v[140:141], off
	s_waitcnt vmcnt(6)
	s_barrier
	s_setprio 0
	v_mfma_f32_16x16x32_bf16 v[52:55], v[192:195], v[160:163], v[52:55]
	v_mfma_f32_16x16x32_bf16 v[48:51], v[220:223], v[160:163], v[48:51]
	v_mfma_f32_16x16x32_bf16 v[36:39], v[192:195], v[168:171], v[36:39]
	v_mfma_f32_16x16x32_bf16 v[32:35], v[220:223], v[168:171], v[32:35]
	v_mfma_f32_16x16x32_bf16 v[20:23], v[192:195], v[176:179], v[20:23]
	v_mfma_f32_16x16x32_bf16 v[16:19], v[220:223], v[176:179], v[16:19]
	v_mfma_f32_16x16x32_bf16 v[4:7], v[192:195], v[184:187], v[4:7]
	v_mfma_f32_16x16x32_bf16 v[0:3], v[220:223], v[184:187], v[0:3]
	v_mfma_f32_16x16x32_bf16 v[52:55], v[196:199], v[164:167], v[52:55]
	v_mfma_f32_16x16x32_bf16 v[48:51], v[224:227], v[164:167], v[48:51]
	v_mfma_f32_16x16x32_bf16 v[36:39], v[196:199], v[172:175], v[36:39]
	v_mfma_f32_16x16x32_bf16 v[32:35], v[224:227], v[172:175], v[32:35]
	v_mfma_f32_16x16x32_bf16 v[20:23], v[196:199], v[180:183], v[20:23]
	v_mfma_f32_16x16x32_bf16 v[16:19], v[224:227], v[180:183], v[16:19]
	v_mfma_f32_16x16x32_bf16 v[4:7], v[196:199], v[188:191], v[4:7]
	v_mfma_f32_16x16x32_bf16 v[0:3], v[224:227], v[188:191], v[0:3]
	s_setprio 1
	s_add_u32 s42, s42, 0x100
	s_addc_u32 s43, s43, 0
	s_cmp_ge_u32 s44, s40
	s_mov_b64 s[8:9], s[10:11]
	s_mov_b32 s2, s44
	s_barrier
	s_cbranch_scc0 .LBB0_120
	v_max_f32_e32 v122, 0, v122
	v_lshl_or_b32 v142, s37, 8, v146
	v_mul_f32_e32 v151, v122, v122
	v_max_f32_e32 v122, v127, v127
	v_max_f32_e32 v123, 0, v123
	v_max_f32_e32 v124, 0, v124
	v_lshl_add_u32 v150, s38, 8, v144
	v_ashrrev_i32_e32 v143, 31, v142
	v_mov_b64_e32 v[140:141], s[80:81]
	s_movk_i32 s8, 0x4080
	v_max_f32_e32 v122, 0, v122
	v_mul_f32_e32 v127, v123, v123
	v_max_f32_e32 v123, v128, v128
	v_mul_f32_e32 v128, v124, v124
	v_max_f32_e32 v124, v129, v129
	v_mad_i64_i32 v[148:149], s[2:3], v150, s8, v[140:141]
	v_lshlrev_b64 v[142:143], 1, v[142:143]
	v_max_f32_e32 v126, 0, v126
	v_mul_f32_e32 v122, v122, v122
	v_max_f32_e32 v123, 0, v123
	v_max_f32_e32 v124, 0, v124
	v_max_f32_e32 v125, 0, v125
	v_lshl_add_u64 v[148:149], v[148:149], 0, v[142:143]
	v_mul_f32_e32 v126, v126, v126
	v_mul_f32_e32 v123, v123, v123
	v_mul_f32_e32 v124, v124, v124
	v_mul_f32_e32 v125, v125, v125
	v_cvt_pk_bf16_f32 v122, v126, v122
	v_max_f32_e32 v114, 0, v114
	v_max_f32_e32 v115, 0, v115
	v_max_f32_e32 v116, 0, v116
	v_cvt_pk_bf16_f32 v123, v123, v124
	v_cvt_pk_bf16_f32 v124, v151, v127
	v_cvt_pk_bf16_f32 v125, v128, v125
	global_store_dwordx4 v[148:149], v[122:125], off
	s_nop 1
	v_mul_f32_e32 v122, v114, v114
	v_max_f32_e32 v114, v119, v119
	v_mul_f32_e32 v119, v115, v115
	v_max_f32_e32 v115, v120, v120
	v_mul_f32_e32 v120, v116, v116
	v_max_f32_e32 v116, v121, v121
	v_max_f32_e32 v114, 0, v114
	v_max_f32_e32 v115, 0, v115
	v_max_f32_e32 v116, 0, v116
	v_max_f32_e32 v118, 0, v118
	v_mul_f32_e32 v114, v114, v114
	v_mul_f32_e32 v115, v115, v115
	v_max_f32_e32 v117, 0, v117
	v_mul_f32_e32 v116, v116, v116
	v_mul_f32_e32 v118, v118, v118
	v_mul_f32_e32 v117, v117, v117
	v_cvt_pk_bf16_f32 v114, v118, v114
	v_cvt_pk_bf16_f32 v115, v115, v116
	v_cvt_pk_bf16_f32 v116, v122, v119
	v_max_f32_e32 v106, 0, v106
	v_cvt_pk_bf16_f32 v117, v120, v117
	global_store_dwordx4 v[148:149], v[114:117], off offset:256
	s_nop 1
	v_max_f32_e32 v107, 0, v107
	v_max_f32_e32 v108, 0, v108
	v_mul_f32_e32 v116, v106, v106
	v_max_f32_e32 v106, v111, v111
	v_or_b32_e32 v114, 16, v150
	v_max_f32_e32 v106, 0, v106
	v_mul_f32_e32 v111, v107, v107
	v_max_f32_e32 v107, v112, v112
	v_mul_f32_e32 v112, v108, v108
	v_max_f32_e32 v108, v113, v113
	v_mad_i64_i32 v[114:115], s[2:3], v114, s8, v[140:141]
	v_max_f32_e32 v110, 0, v110
	v_mul_f32_e32 v106, v106, v106
	v_max_f32_e32 v107, 0, v107
	v_max_f32_e32 v108, 0, v108
	v_max_f32_e32 v109, 0, v109
	v_lshl_add_u64 v[114:115], v[114:115], 0, v[142:143]
	v_mul_f32_e32 v110, v110, v110
	v_mul_f32_e32 v107, v107, v107
	v_mul_f32_e32 v108, v108, v108
	v_mul_f32_e32 v109, v109, v109
	v_cvt_pk_bf16_f32 v106, v110, v106
	v_max_f32_e32 v98, 0, v98
	v_max_f32_e32 v99, 0, v99
	v_max_f32_e32 v100, 0, v100
	v_cvt_pk_bf16_f32 v107, v107, v108
	v_cvt_pk_bf16_f32 v108, v116, v111
	v_cvt_pk_bf16_f32 v109, v112, v109
; __device__ __forceinline__ unsigned cvt_pk_bf16(float lo, float hi) { unsigned r; asm volatile("v_cvt_pk_bf16_f32 %0, %1, %2" : "=v"(r) : "v"(lo), "v"(hi)); return r; }
;     __device__ __forceinline__ void operator()(const f32x4 (&acc)[2][2][4][2], const Unit& u, int wr, int wc, int fr, int fq) const {
;     ...
;         for (int ai = 0; ai < 2; ++ai)
; #pragma unroll
;             for (int m = 0; m < 4; ++m) { bf16_t* rowp = O + (size_t)(row0 + ai * HALF + m * 16) * LDF + col0;
; #pragma unroll
;                 for (int bj = 0; bj < 2; ++bj) { f32x4 v0 = acc[ai][bj][m][0], v1 = acc[ai][bj][m][1];
; #pragma unroll
;                     for (int j = 0; j < 4; ++j) { const float a = fmaxf(v0[j], 0.f), b = fmaxf(v1[j], 0.f); v0[j] = a * a; v1[j] = b * b; }
;                     u32x4 w; w.x = cvt_pk_bf16(v0[0], v0[1]); w.y = cvt_pk_bf16(v0[2], v0[3]); w.z = cvt_pk_bf16(v1[0], v1[1]); w.w = cvt_pk_bf16(v1[2], v1[3]);
;                     *(u32x4*)(rowp + bj * HALF) = w; } }
	global_store_dwordx4 v[114:115], v[106:109], off
	s_nop 1
	v_mul_f32_e32 v106, v98, v98
	v_max_f32_e32 v98, v103, v103
	v_mul_f32_e32 v103, v99, v99
	v_max_f32_e32 v99, v104, v104
	v_mul_f32_e32 v104, v100, v100
	v_max_f32_e32 v100, v105, v105
	v_max_f32_e32 v98, 0, v98
	v_max_f32_e32 v99, 0, v99
	v_max_f32_e32 v100, 0, v100
	v_max_f32_e32 v102, 0, v102
	v_mul_f32_e32 v98, v98, v98
	v_mul_f32_e32 v99, v99, v99
	v_max_f32_e32 v101, 0, v101
	v_mul_f32_e32 v100, v100, v100
	v_mul_f32_e32 v102, v102, v102
	v_mul_f32_e32 v101, v101, v101
	v_cvt_pk_bf16_f32 v98, v102, v98
	v_cvt_pk_bf16_f32 v99, v99, v100
	v_cvt_pk_bf16_f32 v100, v106, v103
	v_max_f32_e32 v90, 0, v90
	v_cvt_pk_bf16_f32 v101, v104, v101
	global_store_dwordx4 v[114:115], v[98:101], off offset:256
	s_nop 1
	v_max_f32_e32 v91, 0, v91
	v_max_f32_e32 v92, 0, v92
	v_mul_f32_e32 v100, v90, v90
	v_max_f32_e32 v90, v95, v95
	v_or_b32_e32 v98, 32, v150
	v_max_f32_e32 v90, 0, v90
	v_mul_f32_e32 v95, v91, v91
	v_max_f32_e32 v91, v96, v96
	v_mul_f32_e32 v96, v92, v92
	v_max_f32_e32 v92, v97, v97
	v_mad_i64_i32 v[98:99], s[2:3], v98, s8, v[140:141]
	v_max_f32_e32 v94, 0, v94
	v_mul_f32_e32 v90, v90, v90
	v_max_f32_e32 v91, 0, v91
	v_max_f32_e32 v92, 0, v92
	v_max_f32_e32 v93, 0, v93
	v_lshl_add_u64 v[98:99], v[98:99], 0, v[142:143]
	v_mul_f32_e32 v94, v94, v94
	v_mul_f32_e32 v91, v91, v91
	v_mul_f32_e32 v92, v92, v92
	v_mul_f32_e32 v93, v93, v93
	v_cvt_pk_bf16_f32 v90, v94, v90
	v_max_f32_e32 v82, 0, v82
	v_max_f32_e32 v83, 0, v83
	v_max_f32_e32 v84, 0, v84
	v_cvt_pk_bf16_f32 v91, v91, v92
	v_cvt_pk_bf16_f32 v92, v100, v95
	v_cvt_pk_bf16_f32 v93, v96, v93
	global_store_dwordx4 v[98:99], v[90:93], off
	s_nop 1
	v_mul_f32_e32 v90, v82, v82
	v_max_f32_e32 v82, v87, v87
	v_mul_f32_e32 v87, v83, v83
	v_max_f32_e32 v83, v88, v88
	v_mul_f32_e32 v88, v84, v84
	v_max_f32_e32 v84, v89, v89
	v_max_f32_e32 v82, 0, v82
	v_max_f32_e32 v83, 0, v83
	v_max_f32_e32 v84, 0, v84
	v_max_f32_e32 v86, 0, v86
	v_mul_f32_e32 v82, v82, v82
	v_mul_f32_e32 v83, v83, v83
	v_max_f32_e32 v85, 0, v85
	v_mul_f32_e32 v84, v84, v84
	v_mul_f32_e32 v86, v86, v86
	v_mul_f32_e32 v85, v85, v85
	v_cvt_pk_bf16_f32 v82, v86, v82
	v_cvt_pk_bf16_f32 v83, v83, v84
	v_cvt_pk_bf16_f32 v84, v90, v87
	v_max_f32_e32 v74, 0, v74
	v_cvt_pk_bf16_f32 v85, v88, v85
	global_store_dwordx4 v[98:99], v[82:85], off offset:256
	s_nop 1
	v_max_f32_e32 v75, 0, v75
	v_max_f32_e32 v76, 0, v76
	v_mul_f32_e32 v84, v74, v74
	v_max_f32_e32 v74, v79, v79
	v_or_b32_e32 v82, 48, v150
	v_max_f32_e32 v74, 0, v74
	v_mul_f32_e32 v79, v75, v75
	v_max_f32_e32 v75, v80, v80
	v_mul_f32_e32 v80, v76, v76
	v_max_f32_e32 v76, v81, v81
	v_mad_i64_i32 v[82:83], s[2:3], v82, s8, v[140:141]
	v_max_f32_e32 v78, 0, v78
	v_mul_f32_e32 v74, v74, v74
	v_max_f32_e32 v75, 0, v75
	v_max_f32_e32 v76, 0, v76
	v_max_f32_e32 v77, 0, v77
	v_lshl_add_u64 v[82:83], v[82:83], 0, v[142:143]
	v_mul_f32_e32 v78, v78, v78
	v_mul_f32_e32 v75, v75, v75
	v_mul_f32_e32 v76, v76, v76
	v_mul_f32_e32 v77, v77, v77
	v_cvt_pk_bf16_f32 v74, v78, v74
	v_max_f32_e32 v66, 0, v66
	v_max_f32_e32 v67, 0, v67
	v_max_f32_e32 v68, 0, v68
	v_cvt_pk_bf16_f32 v75, v75, v76
	v_cvt_pk_bf16_f32 v76, v84, v79
	v_cvt_pk_bf16_f32 v77, v80, v77
	global_store_dwordx4 v[82:83], v[74:77], off
	s_nop 1
	v_mul_f32_e32 v74, v66, v66
	v_max_f32_e32 v66, v71, v71
	v_mul_f32_e32 v71, v67, v67
	v_max_f32_e32 v67, v72, v72
	v_mul_f32_e32 v72, v68, v68
	v_max_f32_e32 v68, v73, v73
	v_max_f32_e32 v66, 0, v66
	v_max_f32_e32 v67, 0, v67
	v_max_f32_e32 v68, 0, v68
	v_max_f32_e32 v70, 0, v70
	v_mul_f32_e32 v66, v66, v66
	v_mul_f32_e32 v67, v67, v67
	v_max_f32_e32 v69, 0, v69
	v_mul_f32_e32 v68, v68, v68
	v_mul_f32_e32 v70, v70, v70
	v_mul_f32_e32 v69, v69, v69
	v_cvt_pk_bf16_f32 v66, v70, v66
	v_cvt_pk_bf16_f32 v67, v67, v68
	v_cvt_pk_bf16_f32 v68, v74, v71
	v_max_f32_e32 v56, 0, v56
	v_cvt_pk_bf16_f32 v69, v72, v69
	global_store_dwordx4 v[82:83], v[66:69], off offset:256
	s_nop 1
	v_max_f32_e32 v57, 0, v57
	v_max_f32_e32 v58, 0, v58
	v_mul_f32_e32 v68, v56, v56
	v_max_f32_e32 v56, v61, v61
	v_add_u32_e32 v66, 0x80, v150
	v_max_f32_e32 v56, 0, v56
	v_mul_f32_e32 v61, v57, v57
	v_max_f32_e32 v57, v62, v62
	v_mul_f32_e32 v62, v58, v58
	v_max_f32_e32 v58, v63, v63
	v_mad_i64_i32 v[66:67], s[2:3], v66, s8, v[140:141]
	v_max_f32_e32 v60, 0, v60
	v_mul_f32_e32 v56, v56, v56
	v_max_f32_e32 v57, 0, v57
	v_max_f32_e32 v58, 0, v58
	v_max_f32_e32 v59, 0, v59
	v_lshl_add_u64 v[66:67], v[66:67], 0, v[142:143]
	v_mul_f32_e32 v60, v60, v60
	v_mul_f32_e32 v57, v57, v57
	v_mul_f32_e32 v58, v58, v58
	v_mul_f32_e32 v59, v59, v59
	v_cvt_pk_bf16_f32 v56, v60, v56
	v_max_f32_e32 v48, 0, v48
	v_max_f32_e32 v49, 0, v49
	v_max_f32_e32 v50, 0, v50
	v_cvt_pk_bf16_f32 v57, v57, v58
	v_cvt_pk_bf16_f32 v58, v68, v61
	v_cvt_pk_bf16_f32 v59, v62, v59
	global_store_dwordx4 v[66:67], v[56:59], off
	s_nop 1
	v_mul_f32_e32 v56, v48, v48
	v_max_f32_e32 v48, v53, v53
	v_mul_f32_e32 v53, v49, v49
	v_max_f32_e32 v49, v54, v54
	v_mul_f32_e32 v54, v50, v50
	v_max_f32_e32 v50, v55, v55
	v_max_f32_e32 v48, 0, v48
	v_max_f32_e32 v49, 0, v49
	v_max_f32_e32 v50, 0, v50
	v_max_f32_e32 v52, 0, v52
	v_mul_f32_e32 v48, v48, v48
	v_mul_f32_e32 v49, v49, v49
	v_max_f32_e32 v51, 0, v51
	v_mul_f32_e32 v50, v50, v50
	v_mul_f32_e32 v52, v52, v52
	v_mul_f32_e32 v51, v51, v51
; __device__ __forceinline__ unsigned cvt_pk_bf16(float lo, float hi) { unsigned r; asm volatile("v_cvt_pk_bf16_f32 %0, %1, %2" : "=v"(r) : "v"(lo), "v"(hi)); return r; }
; #define PG8_WAIT_V(n) asm volatile("s_waitcnt vmcnt(" #n ")" ::: "memory")
; #define PG8_BAR __builtin_amdgcn_s_barrier()
;     __device__ __forceinline__ void operator()(const f32x4 (&acc)[2][2][4][2], const Unit& u, int wr, int wc, int fr, int fq) const {
;     ...
;         for (int ai = 0; ai < 2; ++ai)
; #pragma unroll
;             for (int m = 0; m < 4; ++m) { bf16_t* rowp = O + (size_t)(row0 + ai * HALF + m * 16) * LDF + col0;
; #pragma unroll
;                 for (int bj = 0; bj < 2; ++bj) { f32x4 v0 = acc[ai][bj][m][0], v1 = acc[ai][bj][m][1];
; #pragma unroll
;                     for (int j = 0; j < 4; ++j) { const float a = fmaxf(v0[j], 0.f), b = fmaxf(v1[j], 0.f); v0[j] = a * a; v1[j] = b * b; }
;                     u32x4 w; w.x = cvt_pk_bf16(v0[0], v0[1]); w.y = cvt_pk_bf16(v0[2], v0[3]); w.z = cvt_pk_bf16(v1[0], v1[1]); w.w = cvt_pk_bf16(v1[2], v1[3]);
;                     *(u32x4*)(rowp + bj * HALF) = w; } }
;     ...
;         if (!has_next) break;
; #pragma unroll
;         for (int a = 0; a < 2; ++a)
; #pragma unroll
;             for (int b = 0; b < 2; ++b)
; #pragma unroll
;                 for (int m = 0; m < 4; ++m)
; #pragma unroll
;                     for (int n = 0; n < 2; ++n) acc[a][b][m][n] = (f32x4){0.f, 0.f, 0.f, 0.f};
;         cur = nxt; cA = nA; cB = nB; ++ui;
;     }
;     PG8_WAIT_V(0);
;     if (wr == 0) PG8_BAR;
;     PG8_BAR;
	v_cvt_pk_bf16_f32 v48, v52, v48
	v_cvt_pk_bf16_f32 v49, v49, v50
	v_cvt_pk_bf16_f32 v50, v56, v53
	v_max_f32_e32 v40, 0, v40
	v_cvt_pk_bf16_f32 v51, v54, v51
	global_store_dwordx4 v[66:67], v[48:51], off offset:256
	s_nop 1
	v_max_f32_e32 v41, 0, v41
	v_max_f32_e32 v42, 0, v42
	v_mul_f32_e32 v50, v40, v40
	v_max_f32_e32 v40, v45, v45
	v_add_u32_e32 v48, 0x90, v150
	v_max_f32_e32 v40, 0, v40
	v_mul_f32_e32 v45, v41, v41
	v_max_f32_e32 v41, v46, v46
	v_mul_f32_e32 v46, v42, v42
	v_max_f32_e32 v42, v47, v47
	v_mad_i64_i32 v[48:49], s[2:3], v48, s8, v[140:141]
	v_max_f32_e32 v44, 0, v44
	v_mul_f32_e32 v40, v40, v40
	v_max_f32_e32 v41, 0, v41
	v_max_f32_e32 v42, 0, v42
	v_max_f32_e32 v43, 0, v43
	v_lshl_add_u64 v[48:49], v[48:49], 0, v[142:143]
	v_mul_f32_e32 v44, v44, v44
	v_mul_f32_e32 v41, v41, v41
	v_mul_f32_e32 v42, v42, v42
	v_mul_f32_e32 v43, v43, v43
	v_cvt_pk_bf16_f32 v40, v44, v40
	v_max_f32_e32 v32, 0, v32
	v_max_f32_e32 v33, 0, v33
	v_max_f32_e32 v34, 0, v34
	v_cvt_pk_bf16_f32 v41, v41, v42
	v_cvt_pk_bf16_f32 v42, v50, v45
	v_cvt_pk_bf16_f32 v43, v46, v43
	global_store_dwordx4 v[48:49], v[40:43], off
	s_nop 1
	v_mul_f32_e32 v40, v32, v32
	v_max_f32_e32 v32, v37, v37
	v_mul_f32_e32 v37, v33, v33
	v_max_f32_e32 v33, v38, v38
	v_mul_f32_e32 v38, v34, v34
	v_max_f32_e32 v34, v39, v39
	v_max_f32_e32 v32, 0, v32
	v_max_f32_e32 v33, 0, v33
	v_max_f32_e32 v34, 0, v34
	v_max_f32_e32 v36, 0, v36
	v_mul_f32_e32 v32, v32, v32
	v_mul_f32_e32 v33, v33, v33
	v_max_f32_e32 v35, 0, v35
	v_mul_f32_e32 v34, v34, v34
	v_mul_f32_e32 v36, v36, v36
	v_mul_f32_e32 v35, v35, v35
	v_cvt_pk_bf16_f32 v32, v36, v32
	v_cvt_pk_bf16_f32 v33, v33, v34
	v_cvt_pk_bf16_f32 v34, v40, v37
	v_max_f32_e32 v24, 0, v24
	v_cvt_pk_bf16_f32 v35, v38, v35
	global_store_dwordx4 v[48:49], v[32:35], off offset:256
	s_nop 1
	v_max_f32_e32 v25, 0, v25
	v_max_f32_e32 v26, 0, v26
	v_mul_f32_e32 v34, v24, v24
	v_max_f32_e32 v24, v29, v29
	v_add_u32_e32 v32, 0xa0, v150
	v_max_f32_e32 v24, 0, v24
	v_mul_f32_e32 v29, v25, v25
	v_max_f32_e32 v25, v30, v30
	v_mul_f32_e32 v30, v26, v26
	v_max_f32_e32 v26, v31, v31
	v_mad_i64_i32 v[32:33], s[2:3], v32, s8, v[140:141]
	v_max_f32_e32 v28, 0, v28
	v_mul_f32_e32 v24, v24, v24
	v_max_f32_e32 v25, 0, v25
	v_max_f32_e32 v26, 0, v26
	v_max_f32_e32 v27, 0, v27
	v_lshl_add_u64 v[32:33], v[32:33], 0, v[142:143]
	v_mul_f32_e32 v28, v28, v28
	v_mul_f32_e32 v25, v25, v25
	v_mul_f32_e32 v26, v26, v26
	v_mul_f32_e32 v27, v27, v27
	v_cvt_pk_bf16_f32 v24, v28, v24
	v_max_f32_e32 v16, 0, v16
	v_max_f32_e32 v17, 0, v17
	v_max_f32_e32 v18, 0, v18
	v_cvt_pk_bf16_f32 v25, v25, v26
	v_cvt_pk_bf16_f32 v26, v34, v29
	v_cvt_pk_bf16_f32 v27, v30, v27
	global_store_dwordx4 v[32:33], v[24:27], off
	s_nop 1
	v_mul_f32_e32 v24, v16, v16
	v_max_f32_e32 v16, v21, v21
	v_mul_f32_e32 v21, v17, v17
	v_max_f32_e32 v17, v22, v22
	v_mul_f32_e32 v22, v18, v18
	v_max_f32_e32 v18, v23, v23
	v_max_f32_e32 v16, 0, v16
	v_max_f32_e32 v17, 0, v17
	v_max_f32_e32 v18, 0, v18
	v_max_f32_e32 v20, 0, v20
	v_mul_f32_e32 v16, v16, v16
	v_mul_f32_e32 v17, v17, v17
	v_max_f32_e32 v19, 0, v19
	v_mul_f32_e32 v18, v18, v18
	v_mul_f32_e32 v20, v20, v20
	v_mul_f32_e32 v19, v19, v19
	v_cvt_pk_bf16_f32 v16, v20, v16
	v_cvt_pk_bf16_f32 v17, v17, v18
	v_cvt_pk_bf16_f32 v18, v24, v21
	v_max_f32_e32 v8, 0, v8
	v_cvt_pk_bf16_f32 v19, v22, v19
	global_store_dwordx4 v[32:33], v[16:19], off offset:256
	s_nop 1
	v_max_f32_e32 v9, 0, v9
	v_max_f32_e32 v10, 0, v10
	v_mul_f32_e32 v18, v8, v8
	v_max_f32_e32 v8, v13, v13
	v_add_u32_e32 v16, 0xb0, v150
	v_max_f32_e32 v8, 0, v8
	v_mul_f32_e32 v13, v9, v9
	v_max_f32_e32 v9, v14, v14
	v_mul_f32_e32 v14, v10, v10
	v_max_f32_e32 v10, v15, v15
	v_mad_i64_i32 v[16:17], s[2:3], v16, s8, v[140:141]
	v_max_f32_e32 v12, 0, v12
	v_mul_f32_e32 v8, v8, v8
	v_max_f32_e32 v9, 0, v9
	v_max_f32_e32 v10, 0, v10
	v_max_f32_e32 v11, 0, v11
	v_lshl_add_u64 v[16:17], v[16:17], 0, v[142:143]
	v_mul_f32_e32 v12, v12, v12
	v_mul_f32_e32 v9, v9, v9
	v_mul_f32_e32 v10, v10, v10
	v_mul_f32_e32 v11, v11, v11
	v_cvt_pk_bf16_f32 v8, v12, v8
	v_max_f32_e32 v0, 0, v0
	v_max_f32_e32 v1, 0, v1
	v_max_f32_e32 v2, 0, v2
	v_cvt_pk_bf16_f32 v9, v9, v10
	v_cvt_pk_bf16_f32 v10, v18, v13
	v_cvt_pk_bf16_f32 v11, v14, v11
	global_store_dwordx4 v[16:17], v[8:11], off
	s_nop 1
	v_mul_f32_e32 v8, v0, v0
	v_max_f32_e32 v0, v5, v5
	v_mul_f32_e32 v5, v1, v1
	v_max_f32_e32 v1, v6, v6
	v_mul_f32_e32 v6, v2, v2
	v_max_f32_e32 v2, v7, v7
	v_max_f32_e32 v0, 0, v0
	v_max_f32_e32 v1, 0, v1
	v_max_f32_e32 v2, 0, v2
	v_max_f32_e32 v3, 0, v3
	v_max_f32_e32 v4, 0, v4
	v_mul_f32_e32 v0, v0, v0
	v_mul_f32_e32 v1, v1, v1
	v_mul_f32_e32 v2, v2, v2
	v_mul_f32_e32 v3, v3, v3
	s_and_b64 vcc, exec, s[4:5]
	s_mov_b32 s38, s34
	s_mov_b32 s37, s36
	s_mov_b32 s40, s39
	s_mov_b64 s[10:11], s[18:19]
	s_mov_b64 s[8:9], s[6:7]
	s_mov_b32 s18, s33
	v_readlane_b32 s35, v251, 41
	v_mul_f32_e32 v4, v4, v4
	v_cvt_pk_bf16_f32 v0, v4, v0
	v_cvt_pk_bf16_f32 v1, v1, v2
	v_cvt_pk_bf16_f32 v2, v8, v5
	v_cvt_pk_bf16_f32 v3, v6, v3
	global_store_dwordx4 v[16:17], v[0:3], off offset:256
	s_nop 1
	s_cbranch_vccz .LBB0_96
	s_waitcnt vmcnt(0)
	v_readlane_b32 s40, v251, 24
	v_readlane_b32 s28, v252, 58
	s_cmpk_gt_u32 s15, 0xff
	s_movk_i32 s27, 0x1000
	v_readlane_b32 s41, v251, 25
	v_readlane_b32 s29, v252, 59
	s_cbranch_scc1 .LBB0_124
	s_barrier

; #define PG8_STAGE(bufoff, gbase, voff) do { _Pragma("unroll") for (int _i = 0; _i < 2; ++_i) \
;         __builtin_amdgcn_global_load_lds((const unsigned*)((const char*)(gbase) + (voff)[_i]), (LAS unsigned*)(lds + (bufoff) + ldsw + _i * 8192), 16, 0, 0); } while (0)
; #define PG8_LDA(dst, b, h) do { _Pragma("unroll") for (int m = 0; m < 4; ++m) _Pragma("unroll") for (int k = 0; k < 2; ++k) dst[m][k] = *(const LAS bf16x8*)(lds + PG8_SA(b, h) + aoff + m * 2048 + k * 1024); } while (0)
; #define PG8_LDB(dst, b, h) do { _Pragma("unroll") for (int n = 0; n < 2; ++n) _Pragma("unroll") for (int k = 0; k < 2; ++k) dst[n][k] = *(const LAS bf16x8*)(lds + PG8_SB(b, h) + boff + n * 2048 + k * 1024); } while (0)
; #define PG8_MMA(ai, bj, At, Bt) do { __builtin_amdgcn_s_setprio(1); _Pragma("unroll") for (int m = 0; m < 4; ++m) _Pragma("unroll") for (int n = 0; n < 2; ++n) _Pragma("unroll") for (int k = 0; k < 2; ++k) \
;         acc[ai][bj][m][n] = __builtin_amdgcn_mfma_f32_16x16x32_bf16(Bt[n][k], At[m][k], acc[ai][bj][m][n], 0, 0, 0); __builtin_amdgcn_s_setprio(0); } while (0)
; #define PG8_WAIT_V(n) asm volatile("s_waitcnt vmcnt(" #n ")" ::: "memory")
; #define PG8_WAIT_L(n) asm volatile("s_waitcnt lgkmcnt(" #n ")" ::: "memory")
; #define PG8_BAR __builtin_amdgcn_s_barrier()
; #define PG8_SCHED __builtin_amdgcn_sched_barrier(0)
;     ...
;             const char* a1 = cA + (size_t)(t + 1) * kstep;
;             const char* a2 = last ? nA : cA + (size_t)(t + 2) * kstep; const char* b2 = last ? nB : cB + (size_t)(t + 2) * kstep;
;             const char* a3 = a2 + kstep; const char* b3 = b2 + kstep;
;             PG8_LDB(B0, 0, 0); PG8_SCHED; PG8_LDA(At, 0, 0); PG8_STAGE(PG8_SA(1, 1), a1 + hstep, voffA);
;             PG8_WAIT_L(8); PG8_BAR; PG8_WAIT_L(0); PG8_MMA(0, 0, At, B0); PG8_BAR; PG8_SCHED;
;             PG8_LDB(B1, 0, 1); PG8_STAGE(PG8_SB(0, 0), b2, voffB);
;             PG8_BAR; PG8_WAIT_L(0); PG8_MMA(0, 1, At, B1); PG8_BAR;
;             PG8_LDA(At, 0, 1); PG8_STAGE(PG8_SA(0, 0), a2, voffA);
;             PG8_BAR; PG8_WAIT_L(0); PG8_MMA(1, 0, At, B0); PG8_BAR; PG8_SCHED;
;             PG8_STAGE(PG8_SB(0, 1), b2 + hstep, voffB);
;             PG8_WAIT_V(6); PG8_BAR; PG8_MMA(1, 1, At, B1); PG8_BAR;
.LBB0_146:
	s_add_u32 s2, s8, 0xe515c080
	s_addc_u32 s3, s9, -1
	s_cmp_lg_u32 s27, 28
	s_cselect_b32 s10, s2, 0
	s_cselect_b32 s11, s3, 0
	s_add_u32 s2, s6, s10
	s_addc_u32 s3, s7, s11
	s_add_i32 s28, 0, 0x10000
	v_add_u32_e32 v156, s28, v142
	ds_read_b128 v[144:147], v156
	ds_read_b128 v[148:151], v156 offset:1024
	ds_read_b128 v[152:155], v156 offset:2048
	ds_read_b128 v[156:159], v156 offset:3072
	s_add_u32 s10, s4, s10
	s_addc_u32 s11, s5, s11
	v_lshl_add_u64 v[192:193], v[136:137], 0, s[8:9]
	s_add_i32 m0, s20, 0xc000
	ds_read_b128 v[160:163], v143
	ds_read_b128 v[164:167], v143 offset:1024
	ds_read_b128 v[168:171], v143 offset:2048
	ds_read_b128 v[172:175], v143 offset:3072
	ds_read_b128 v[176:179], v143 offset:4096
	ds_read_b128 v[180:183], v143 offset:5120
	ds_read_b128 v[184:187], v143 offset:6144
	ds_read_b128 v[188:191], v143 offset:7168
	global_load_lds_dwordx4 v[192:193], off
	v_lshl_add_u64 v[192:193], v[138:139], 0, s[8:9]
	s_add_i32 m0, s20, 0xe000
	s_nop 0
	global_load_lds_dwordx4 v[192:193], off
	s_waitcnt lgkmcnt(8)
	s_barrier
	s_waitcnt lgkmcnt(0)
	s_setprio 0
	s_waitcnt lgkmcnt(0)
	v_mfma_f32_16x16x32_bf16 v[126:129], v[144:147], v[160:163], v[126:129]
	v_mfma_f32_16x16x32_bf16 v[122:125], v[152:155], v[160:163], v[122:125]
	v_mfma_f32_16x16x32_bf16 v[110:113], v[144:147], v[168:171], v[110:113]
	v_mfma_f32_16x16x32_bf16 v[106:109], v[152:155], v[168:171], v[106:109]
	v_mfma_f32_16x16x32_bf16 v[94:97], v[144:147], v[176:179], v[94:97]
	v_mfma_f32_16x16x32_bf16 v[90:93], v[152:155], v[176:179], v[90:93]
	v_mfma_f32_16x16x32_bf16 v[78:81], v[144:147], v[184:187], v[78:81]
	v_mfma_f32_16x16x32_bf16 v[74:77], v[152:155], v[184:187], v[74:77]
	v_mfma_f32_16x16x32_bf16 v[126:129], v[148:151], v[164:167], v[126:129]
	v_mfma_f32_16x16x32_bf16 v[122:125], v[156:159], v[164:167], v[122:125]
	v_mfma_f32_16x16x32_bf16 v[110:113], v[148:151], v[172:175], v[110:113]
	v_mfma_f32_16x16x32_bf16 v[106:109], v[156:159], v[172:175], v[106:109]
	v_mfma_f32_16x16x32_bf16 v[94:97], v[148:151], v[180:183], v[94:97]
	v_mfma_f32_16x16x32_bf16 v[90:93], v[156:159], v[180:183], v[90:93]
	v_mfma_f32_16x16x32_bf16 v[78:81], v[148:151], v[188:191], v[78:81]
	v_mfma_f32_16x16x32_bf16 v[74:77], v[156:159], v[188:191], v[74:77]
	s_setprio 1
	s_barrier
	s_add_i32 s31, 0, 0x14000
	s_add_i32 s28, s28, s15
	v_add_u32_e32 v208, s31, v142
	v_lshl_add_u64 v[228:229], s[10:11], 0, v[64:65]
	s_mov_b32 m0, s28
	ds_read_b128 v[192:195], v208
	ds_read_b128 v[196:199], v208 offset:1024
	ds_read_b128 v[220:223], v208 offset:2048
	ds_read_b128 v[224:227], v208 offset:3072
	global_load_lds_dwordx4 v[228:229], off
	v_lshl_add_u64 v[230:231], s[10:11], 0, v[130:131]
	s_add_i32 m0, s28, 0x2000
	s_nop 0
	global_load_lds_dwordx4 v[230:231], off
	s_barrier
	s_waitcnt lgkmcnt(0)
	s_setprio 0
	s_waitcnt lgkmcnt(0)
	v_mfma_f32_16x16x32_bf16 v[118:121], v[192:195], v[160:163], v[118:121]
	v_mfma_f32_16x16x32_bf16 v[114:117], v[220:223], v[160:163], v[114:117]
	v_mfma_f32_16x16x32_bf16 v[102:105], v[192:195], v[168:171], v[102:105]
	v_mfma_f32_16x16x32_bf16 v[98:101], v[220:223], v[168:171], v[98:101]
	v_mfma_f32_16x16x32_bf16 v[86:89], v[192:195], v[176:179], v[86:89]
	v_mfma_f32_16x16x32_bf16 v[82:85], v[220:223], v[176:179], v[82:85]
	v_mfma_f32_16x16x32_bf16 v[70:73], v[192:195], v[184:187], v[70:73]
	v_mfma_f32_16x16x32_bf16 v[66:69], v[220:223], v[184:187], v[66:69]
	v_mfma_f32_16x16x32_bf16 v[118:121], v[196:199], v[164:167], v[118:121]
	v_mfma_f32_16x16x32_bf16 v[114:117], v[224:227], v[164:167], v[114:117]
	v_mfma_f32_16x16x32_bf16 v[102:105], v[196:199], v[172:175], v[102:105]
	v_mfma_f32_16x16x32_bf16 v[98:101], v[224:227], v[172:175], v[98:101]
	v_mfma_f32_16x16x32_bf16 v[86:89], v[196:199], v[180:183], v[86:89]
	v_mfma_f32_16x16x32_bf16 v[82:85], v[224:227], v[180:183], v[82:85]
	v_mfma_f32_16x16x32_bf16 v[70:73], v[196:199], v[188:191], v[70:73]
	v_mfma_f32_16x16x32_bf16 v[66:69], v[224:227], v[188:191], v[66:69]
	s_setprio 1
	s_mov_b32 m0, s20
	v_lshl_add_u64 v[232:233], s[2:3], 0, v[134:135]
	s_barrier
	ds_read_b128 v[160:163], v143 offset:16384
	ds_read_b128 v[164:167], v143 offset:17408
	ds_read_b128 v[168:171], v143 offset:18432
	ds_read_b128 v[172:175], v143 offset:19456
	ds_read_b128 v[176:179], v143 offset:20480
	ds_read_b128 v[180:183], v143 offset:21504
	ds_read_b128 v[184:187], v143 offset:22528
	ds_read_b128 v[188:191], v143 offset:23552
	global_load_lds_dwordx4 v[232:233], off
	v_lshl_add_u64 v[234:235], s[2:3], 0, v[132:133]
	s_mov_b32 m0, s21
	s_nop 0
	global_load_lds_dwordx4 v[234:235], off
	s_barrier
	s_waitcnt lgkmcnt(0)
	s_setprio 0
	s_waitcnt lgkmcnt(0)
	v_mfma_f32_16x16x32_bf16 v[60:63], v[144:147], v[160:163], v[60:63]
	v_mfma_f32_16x16x32_bf16 v[56:59], v[152:155], v[160:163], v[56:59]
	v_mfma_f32_16x16x32_bf16 v[44:47], v[144:147], v[168:171], v[44:47]
	v_mfma_f32_16x16x32_bf16 v[40:43], v[152:155], v[168:171], v[40:43]
	v_mfma_f32_16x16x32_bf16 v[28:31], v[144:147], v[176:179], v[28:31]
	v_mfma_f32_16x16x32_bf16 v[24:27], v[152:155], v[176:179], v[24:27]
	v_mfma_f32_16x16x32_bf16 v[12:15], v[144:147], v[184:187], v[12:15]
	v_mfma_f32_16x16x32_bf16 v[8:11], v[152:155], v[184:187], v[8:11]
	v_mfma_f32_16x16x32_bf16 v[60:63], v[148:151], v[164:167], v[60:63]
	v_mfma_f32_16x16x32_bf16 v[56:59], v[156:159], v[164:167], v[56:59]
	v_mfma_f32_16x16x32_bf16 v[44:47], v[148:151], v[172:175], v[44:47]
	v_mfma_f32_16x16x32_bf16 v[40:43], v[156:159], v[172:175], v[40:43]
	v_mfma_f32_16x16x32_bf16 v[28:31], v[148:151], v[180:183], v[28:31]
	v_mfma_f32_16x16x32_bf16 v[24:27], v[156:159], v[180:183], v[24:27]
	v_mfma_f32_16x16x32_bf16 v[12:15], v[148:151], v[188:191], v[12:15]
	v_mfma_f32_16x16x32_bf16 v[8:11], v[156:159], v[188:191], v[8:11]
	s_setprio 1
	s_barrier
; #define PG8_STAGE(bufoff, gbase, voff) do { _Pragma("unroll") for (int _i = 0; _i < 2; ++_i) \
;         __builtin_amdgcn_global_load_lds((const unsigned*)((const char*)(gbase) + (voff)[_i]), (LAS unsigned*)(lds + (bufoff) + ldsw + _i * 8192), 16, 0, 0); } while (0)
; #define PG8_LDA(dst, b, h) do { _Pragma("unroll") for (int m = 0; m < 4; ++m) _Pragma("unroll") for (int k = 0; k < 2; ++k) dst[m][k] = *(const LAS bf16x8*)(lds + PG8_SA(b, h) + aoff + m * 2048 + k * 1024); } while (0)
; #define PG8_LDB(dst, b, h) do { _Pragma("unroll") for (int n = 0; n < 2; ++n) _Pragma("unroll") for (int k = 0; k < 2; ++k) dst[n][k] = *(const LAS bf16x8*)(lds + PG8_SB(b, h) + boff + n * 2048 + k * 1024); } while (0)
; #define PG8_MMA(ai, bj, At, Bt) do { __builtin_amdgcn_s_setprio(1); _Pragma("unroll") for (int m = 0; m < 4; ++m) _Pragma("unroll") for (int n = 0; n < 2; ++n) _Pragma("unroll") for (int k = 0; k < 2; ++k) \
;         acc[ai][bj][m][n] = __builtin_amdgcn_mfma_f32_16x16x32_bf16(Bt[n][k], At[m][k], acc[ai][bj][m][n], 0, 0, 0); __builtin_amdgcn_s_setprio(0); } while (0)
; #define PG8_WAIT_V(n) asm volatile("s_waitcnt vmcnt(" #n ")" ::: "memory")
; #define PG8_WAIT_L(n) asm volatile("s_waitcnt lgkmcnt(" #n ")" ::: "memory")
; #define PG8_BAR __builtin_amdgcn_s_barrier()
; #define PG8_SCHED __builtin_amdgcn_sched_barrier(0)
;     ...
;             PG8_STAGE(PG8_SB(0, 1), b2 + hstep, voffB);
;             PG8_WAIT_V(6); PG8_BAR; PG8_MMA(1, 1, At, B1); PG8_BAR;
;             PG8_LDB(B0, 1, 0); PG8_SCHED; PG8_LDA(At, 1, 0); PG8_STAGE(PG8_SA(0, 1), a2 + hstep, voffA);
;             PG8_WAIT_L(8); PG8_BAR; PG8_WAIT_L(0); PG8_MMA(0, 0, At, B0); PG8_BAR; PG8_SCHED;
;             PG8_LDB(B1, 1, 1); PG8_STAGE(PG8_SB(1, 0), b3, voffB);
;             PG8_BAR; PG8_WAIT_L(0); PG8_MMA(0, 1, At, B1); PG8_BAR;
;             PG8_LDA(At, 1, 1); PG8_STAGE(PG8_SA(1, 0), a3, voffA);
;             PG8_BAR; PG8_WAIT_L(0); PG8_MMA(1, 0, At, B0); PG8_BAR; PG8_SCHED;
;             PG8_STAGE(PG8_SB(1, 1), b3 + hstep, voffB);
	s_add_u32 s28, s10, 0x84000
	s_addc_u32 s29, s11, 0
	s_add_i32 s31, s31, s15
	v_lshl_add_u64 v[144:145], s[28:29], 0, v[64:65]
	s_mov_b32 m0, s31
	s_nop 0
	global_load_lds_dwordx4 v[144:145], off
	v_lshl_add_u64 v[144:145], s[28:29], 0, v[130:131]
	s_add_i32 m0, s31, 0x2000
	s_nop 0
	global_load_lds_dwordx4 v[144:145], off
	s_waitcnt vmcnt(6)
	s_barrier
	s_setprio 0
	v_mfma_f32_16x16x32_bf16 v[52:55], v[192:195], v[160:163], v[52:55]
	v_mfma_f32_16x16x32_bf16 v[48:51], v[220:223], v[160:163], v[48:51]
	v_mfma_f32_16x16x32_bf16 v[36:39], v[192:195], v[168:171], v[36:39]
	v_mfma_f32_16x16x32_bf16 v[32:35], v[220:223], v[168:171], v[32:35]
	v_mfma_f32_16x16x32_bf16 v[20:23], v[192:195], v[176:179], v[20:23]
	v_mfma_f32_16x16x32_bf16 v[16:19], v[220:223], v[176:179], v[16:19]
	v_mfma_f32_16x16x32_bf16 v[4:7], v[192:195], v[184:187], v[4:7]
	v_mfma_f32_16x16x32_bf16 v[0:3], v[220:223], v[184:187], v[0:3]
	v_mfma_f32_16x16x32_bf16 v[52:55], v[196:199], v[164:167], v[52:55]
	v_mfma_f32_16x16x32_bf16 v[48:51], v[224:227], v[164:167], v[48:51]
	v_mfma_f32_16x16x32_bf16 v[36:39], v[196:199], v[172:175], v[36:39]
	v_mfma_f32_16x16x32_bf16 v[32:35], v[224:227], v[172:175], v[32:35]
	v_mfma_f32_16x16x32_bf16 v[20:23], v[196:199], v[180:183], v[20:23]
	v_mfma_f32_16x16x32_bf16 v[16:19], v[224:227], v[180:183], v[16:19]
	v_mfma_f32_16x16x32_bf16 v[4:7], v[196:199], v[188:191], v[4:7]
	v_mfma_f32_16x16x32_bf16 v[0:3], v[224:227], v[188:191], v[0:3]
	s_setprio 1
	s_add_i32 s28, 0, 0x18000
	v_add_u32_e32 v156, s28, v142
	s_barrier
	ds_read_b128 v[144:147], v156
	ds_read_b128 v[148:151], v156 offset:1024
	ds_read_b128 v[152:155], v156 offset:2048
	ds_read_b128 v[156:159], v156 offset:3072
	s_add_u32 s2, s2, 0x84000
	s_addc_u32 s3, s3, 0
	s_mov_b32 m0, s22
	v_lshl_add_u64 v[192:193], s[2:3], 0, v[134:135]
	ds_read_b128 v[160:163], v143 offset:32768
	ds_read_b128 v[164:167], v143 offset:33792
	ds_read_b128 v[168:171], v143 offset:34816
	ds_read_b128 v[172:175], v143 offset:35840
	ds_read_b128 v[176:179], v143 offset:36864
	ds_read_b128 v[180:183], v143 offset:37888
	ds_read_b128 v[184:187], v143 offset:38912
	ds_read_b128 v[188:191], v143 offset:39936
	global_load_lds_dwordx4 v[192:193], off
	v_lshl_add_u64 v[192:193], s[2:3], 0, v[132:133]
	s_mov_b32 m0, s23
	s_nop 0
	global_load_lds_dwordx4 v[192:193], off
	s_waitcnt lgkmcnt(8)
	s_barrier
	s_waitcnt lgkmcnt(0)
	s_setprio 0
	s_waitcnt lgkmcnt(0)
	v_mfma_f32_16x16x32_bf16 v[126:129], v[144:147], v[160:163], v[126:129]
	v_mfma_f32_16x16x32_bf16 v[122:125], v[152:155], v[160:163], v[122:125]
	v_mfma_f32_16x16x32_bf16 v[110:113], v[144:147], v[168:171], v[110:113]
	v_mfma_f32_16x16x32_bf16 v[106:109], v[152:155], v[168:171], v[106:109]
	v_mfma_f32_16x16x32_bf16 v[94:97], v[144:147], v[176:179], v[94:97]
	v_mfma_f32_16x16x32_bf16 v[90:93], v[152:155], v[176:179], v[90:93]
	v_mfma_f32_16x16x32_bf16 v[78:81], v[144:147], v[184:187], v[78:81]
	v_mfma_f32_16x16x32_bf16 v[74:77], v[152:155], v[184:187], v[74:77]
	v_mfma_f32_16x16x32_bf16 v[126:129], v[148:151], v[164:167], v[126:129]
	v_mfma_f32_16x16x32_bf16 v[122:125], v[156:159], v[164:167], v[122:125]
	v_mfma_f32_16x16x32_bf16 v[110:113], v[148:151], v[172:175], v[110:113]
	v_mfma_f32_16x16x32_bf16 v[106:109], v[156:159], v[172:175], v[106:109]
	v_mfma_f32_16x16x32_bf16 v[94:97], v[148:151], v[180:183], v[94:97]
	v_mfma_f32_16x16x32_bf16 v[90:93], v[156:159], v[180:183], v[90:93]
	v_mfma_f32_16x16x32_bf16 v[78:81], v[148:151], v[188:191], v[78:81]
	v_mfma_f32_16x16x32_bf16 v[74:77], v[156:159], v[188:191], v[74:77]
	s_setprio 1
	s_barrier
	s_add_i32 s29, 0, 0x1c000
	s_add_i32 s2, s28, s15
	v_add_u32_e32 v208, s29, v142
	v_lshl_add_u64 v[228:229], v[228:229], 0, s[16:17]
	s_mov_b32 m0, s2
	ds_read_b128 v[192:195], v208
	ds_read_b128 v[196:199], v208 offset:1024
	ds_read_b128 v[220:223], v208 offset:2048
	ds_read_b128 v[224:227], v208 offset:3072
	global_load_lds_dwordx4 v[228:229], off
	v_lshl_add_u64 v[228:229], v[230:231], 0, s[16:17]
	s_add_i32 m0, s2, 0x2000
	s_nop 0
	global_load_lds_dwordx4 v[228:229], off
	s_barrier
	s_waitcnt lgkmcnt(0)
	s_setprio 0
	s_waitcnt lgkmcnt(0)
	v_mfma_f32_16x16x32_bf16 v[118:121], v[192:195], v[160:163], v[118:121]
	v_mfma_f32_16x16x32_bf16 v[114:117], v[220:223], v[160:163], v[114:117]
	v_mfma_f32_16x16x32_bf16 v[102:105], v[192:195], v[168:171], v[102:105]
	v_mfma_f32_16x16x32_bf16 v[98:101], v[220:223], v[168:171], v[98:101]
	v_mfma_f32_16x16x32_bf16 v[86:89], v[192:195], v[176:179], v[86:89]
	v_mfma_f32_16x16x32_bf16 v[82:85], v[220:223], v[176:179], v[82:85]
	v_mfma_f32_16x16x32_bf16 v[70:73], v[192:195], v[184:187], v[70:73]
	v_mfma_f32_16x16x32_bf16 v[66:69], v[220:223], v[184:187], v[66:69]
	v_mfma_f32_16x16x32_bf16 v[118:121], v[196:199], v[164:167], v[118:121]
	v_mfma_f32_16x16x32_bf16 v[114:117], v[224:227], v[164:167], v[114:117]
	v_mfma_f32_16x16x32_bf16 v[102:105], v[196:199], v[172:175], v[102:105]
	v_mfma_f32_16x16x32_bf16 v[98:101], v[224:227], v[172:175], v[98:101]
	v_mfma_f32_16x16x32_bf16 v[86:89], v[196:199], v[180:183], v[86:89]
	v_mfma_f32_16x16x32_bf16 v[82:85], v[224:227], v[180:183], v[82:85]
	v_mfma_f32_16x16x32_bf16 v[70:73], v[196:199], v[188:191], v[70:73]
	v_mfma_f32_16x16x32_bf16 v[66:69], v[224:227], v[188:191], v[66:69]
	s_setprio 1
	s_mov_b32 m0, s25
	v_lshl_add_u64 v[228:229], v[232:233], 0, s[16:17]
	s_barrier
	ds_read_b128 v[160:163], v143 offset:49152
	ds_read_b128 v[164:167], v143 offset:50176
	ds_read_b128 v[168:171], v143 offset:51200
	ds_read_b128 v[172:175], v143 offset:52224
	ds_read_b128 v[176:179], v143 offset:53248
	ds_read_b128 v[180:183], v143 offset:54272
	ds_read_b128 v[184:187], v143 offset:55296
	ds_read_b128 v[188:191], v143 offset:56320
	global_load_lds_dwordx4 v[228:229], off
	v_lshl_add_u64 v[228:229], v[234:235], 0, s[16:17]
	s_mov_b32 m0, s26
	s_nop 0
	global_load_lds_dwordx4 v[228:229], off
	s_barrier
; __device__ __forceinline__ unsigned cvt_pk_bf16(float lo, float hi) { unsigned r; asm volatile("v_cvt_pk_bf16_f32 %0, %1, %2" : "=v"(r) : "v"(lo), "v"(hi)); return r; }
; #define PG8_STAGE(bufoff, gbase, voff) do { _Pragma("unroll") for (int _i = 0; _i < 2; ++_i) \
;         __builtin_amdgcn_global_load_lds((const unsigned*)((const char*)(gbase) + (voff)[_i]), (LAS unsigned*)(lds + (bufoff) + ldsw + _i * 8192), 16, 0, 0); } while (0)
; #define PG8_LDA(dst, b, h) do { _Pragma("unroll") for (int m = 0; m < 4; ++m) _Pragma("unroll") for (int k = 0; k < 2; ++k) dst[m][k] = *(const LAS bf16x8*)(lds + PG8_SA(b, h) + aoff + m * 2048 + k * 1024); } while (0)
; #define PG8_MMA(ai, bj, At, Bt) do { __builtin_amdgcn_s_setprio(1); _Pragma("unroll") for (int m = 0; m < 4; ++m) _Pragma("unroll") for (int n = 0; n < 2; ++n) _Pragma("unroll") for (int k = 0; k < 2; ++k) \
;         acc[ai][bj][m][n] = __builtin_amdgcn_mfma_f32_16x16x32_bf16(Bt[n][k], At[m][k], acc[ai][bj][m][n], 0, 0, 0); __builtin_amdgcn_s_setprio(0); } while (0)
; #define PG8_WAIT_V(n) asm volatile("s_waitcnt vmcnt(" #n ")" ::: "memory")
; #define PG8_WAIT_L(n) asm volatile("s_waitcnt lgkmcnt(" #n ")" ::: "memory")
;     __device__ __forceinline__ void operator()(const f32x4 (&acc)[2][2][4][2], const Unit& u, int wr, int wc, int fr, int fq) const {
;         const int row0 = u.pm * BM + wr * 64 + fr, col0 = u.pn * BM + wc * 32 + 8 * fq;
; #pragma unroll
;         for (int ai = 0; ai < 2; ++ai)
; #pragma unroll
;             for (int m = 0; m < 4; ++m) { bf16_t* rowp = O + (size_t)(row0 + ai * HALF + m * 16) * LDF + col0;
; #pragma unroll
;                 for (int bj = 0; bj < 2; ++bj) { f32x4 v0 = acc[ai][bj][m][0], v1 = acc[ai][bj][m][1];
; #pragma unroll
;                     for (int j = 0; j < 4; ++j) { const float a = fmaxf(v0[j], 0.f), b = fmaxf(v1[j], 0.f); v0[j] = a * a; v1[j] = b * b; }
;                     u32x4 w; w.x = cvt_pk_bf16(v0[0], v0[1]); w.y = cvt_pk_bf16(v0[2], v0[3]); w.z = cvt_pk_bf16(v1[0], v1[1]); w.w = cvt_pk_bf16(v1[2], v1[3]);
;                     *(u32x4*)(rowp + bj * HALF) = w; } }
;     ...
;             PG8_LDA(At, 1, 1); PG8_STAGE(PG8_SA(1, 0), a3, voffA);
;             PG8_BAR; PG8_WAIT_L(0); PG8_MMA(1, 0, At, B0); PG8_BAR; PG8_SCHED;
;             PG8_STAGE(PG8_SB(1, 1), b3 + hstep, voffB);
;             PG8_WAIT_V(6); PG8_BAR; PG8_MMA(1, 1, At, B1); PG8_BAR;
	s_waitcnt lgkmcnt(0)
	s_setprio 0
	s_waitcnt lgkmcnt(0)
	v_mfma_f32_16x16x32_bf16 v[60:63], v[144:147], v[160:163], v[60:63]
	v_mfma_f32_16x16x32_bf16 v[56:59], v[152:155], v[160:163], v[56:59]
	v_mfma_f32_16x16x32_bf16 v[44:47], v[144:147], v[168:171], v[44:47]
	v_mfma_f32_16x16x32_bf16 v[40:43], v[152:155], v[168:171], v[40:43]
	v_mfma_f32_16x16x32_bf16 v[28:31], v[144:147], v[176:179], v[28:31]
	v_mfma_f32_16x16x32_bf16 v[24:27], v[152:155], v[176:179], v[24:27]
	v_mfma_f32_16x16x32_bf16 v[12:15], v[144:147], v[184:187], v[12:15]
	v_mfma_f32_16x16x32_bf16 v[8:11], v[152:155], v[184:187], v[8:11]
	v_mfma_f32_16x16x32_bf16 v[60:63], v[148:151], v[164:167], v[60:63]
	v_mfma_f32_16x16x32_bf16 v[56:59], v[156:159], v[164:167], v[56:59]
	v_mfma_f32_16x16x32_bf16 v[44:47], v[148:151], v[172:175], v[44:47]
	v_mfma_f32_16x16x32_bf16 v[40:43], v[156:159], v[172:175], v[40:43]
	v_mfma_f32_16x16x32_bf16 v[28:31], v[148:151], v[180:183], v[28:31]
	v_mfma_f32_16x16x32_bf16 v[24:27], v[156:159], v[180:183], v[24:27]
	v_mfma_f32_16x16x32_bf16 v[12:15], v[148:151], v[188:191], v[12:15]
	v_mfma_f32_16x16x32_bf16 v[8:11], v[156:159], v[188:191], v[8:11]
	s_setprio 1
	s_barrier
	s_add_u32 s2, s10, 0x84080
	s_addc_u32 s3, s11, 0
	s_add_i32 s10, s29, s15
	v_lshl_add_u64 v[144:145], s[2:3], 0, v[64:65]
	s_mov_b32 m0, s10
	s_nop 0
	global_load_lds_dwordx4 v[144:145], off
	v_lshl_add_u64 v[144:145], s[2:3], 0, v[130:131]
	s_add_i32 m0, s10, 0x2000
	s_nop 0
	global_load_lds_dwordx4 v[144:145], off
	s_waitcnt vmcnt(6)
	s_barrier
	s_setprio 0
	v_mfma_f32_16x16x32_bf16 v[52:55], v[192:195], v[160:163], v[52:55]
	v_mfma_f32_16x16x32_bf16 v[48:51], v[220:223], v[160:163], v[48:51]
	v_mfma_f32_16x16x32_bf16 v[36:39], v[192:195], v[168:171], v[36:39]
	v_mfma_f32_16x16x32_bf16 v[32:35], v[220:223], v[168:171], v[32:35]
	v_mfma_f32_16x16x32_bf16 v[20:23], v[192:195], v[176:179], v[20:23]
	v_mfma_f32_16x16x32_bf16 v[16:19], v[220:223], v[176:179], v[16:19]
	v_mfma_f32_16x16x32_bf16 v[4:7], v[192:195], v[184:187], v[4:7]
	v_mfma_f32_16x16x32_bf16 v[0:3], v[220:223], v[184:187], v[0:3]
	v_mfma_f32_16x16x32_bf16 v[52:55], v[196:199], v[164:167], v[52:55]
	v_mfma_f32_16x16x32_bf16 v[48:51], v[224:227], v[164:167], v[48:51]
	v_mfma_f32_16x16x32_bf16 v[36:39], v[196:199], v[172:175], v[36:39]
	v_mfma_f32_16x16x32_bf16 v[32:35], v[224:227], v[172:175], v[32:35]
	v_mfma_f32_16x16x32_bf16 v[20:23], v[196:199], v[180:183], v[20:23]
	v_mfma_f32_16x16x32_bf16 v[16:19], v[224:227], v[180:183], v[16:19]
	v_mfma_f32_16x16x32_bf16 v[4:7], v[196:199], v[188:191], v[4:7]
	v_mfma_f32_16x16x32_bf16 v[0:3], v[224:227], v[188:191], v[0:3]
	s_setprio 1
	s_add_i32 s27, s27, 2
	s_add_u32 s8, s8, 0x100
	s_addc_u32 s9, s9, 0
	s_cmp_gt_u32 s27, 29
	s_barrier
	s_cbranch_scc0 .LBB0_146
	s_lshl_b32 s2, s19, 8
	v_max_f32_e32 v122, 0, v122
	s_or_b32 s2, s24, s2
	v_mul_f32_e32 v135, v122, v122
	v_max_f32_e32 v122, v127, v127
	v_max_f32_e32 v123, 0, v123
	v_max_f32_e32 v124, 0, v124
	v_lshl_add_u32 v134, s18, 8, v141
	v_or_b32_e32 v64, s2, v140
	v_mov_b64_e32 v[130:131], s[80:81]
	s_movk_i32 s4, 0x4080
	v_max_f32_e32 v122, 0, v122
	v_mul_f32_e32 v127, v123, v123
	v_max_f32_e32 v123, v128, v128
	v_mul_f32_e32 v128, v124, v124
	v_max_f32_e32 v124, v129, v129
	v_mad_i64_i32 v[132:133], s[2:3], v134, s4, v[130:131]
	v_lshlrev_b32_e32 v64, 1, v64
	v_max_f32_e32 v126, 0, v126
	v_mul_f32_e32 v122, v122, v122
	v_max_f32_e32 v123, 0, v123
	v_max_f32_e32 v124, 0, v124
	v_max_f32_e32 v125, 0, v125
	v_lshl_add_u64 v[132:133], v[132:133], 0, v[64:65]
	v_mul_f32_e32 v126, v126, v126
	v_mul_f32_e32 v123, v123, v123
	v_mul_f32_e32 v124, v124, v124
	v_mul_f32_e32 v125, v125, v125
	v_cvt_pk_bf16_f32 v122, v126, v122
	v_max_f32_e32 v114, 0, v114
	v_max_f32_e32 v115, 0, v115
	v_max_f32_e32 v116, 0, v116
	v_cvt_pk_bf16_f32 v123, v123, v124
	v_cvt_pk_bf16_f32 v124, v135, v127
	v_cvt_pk_bf16_f32 v125, v128, v125
	global_store_dwordx4 v[132:133], v[122:125], off
	s_nop 1
	v_mul_f32_e32 v122, v114, v114
	v_max_f32_e32 v114, v119, v119
	v_mul_f32_e32 v119, v115, v115
	v_max_f32_e32 v115, v120, v120
	v_mul_f32_e32 v120, v116, v116
	v_max_f32_e32 v116, v121, v121
	v_max_f32_e32 v114, 0, v114
	v_max_f32_e32 v115, 0, v115
	v_max_f32_e32 v116, 0, v116
	v_max_f32_e32 v118, 0, v118
	v_mul_f32_e32 v114, v114, v114
	v_mul_f32_e32 v115, v115, v115
	v_max_f32_e32 v117, 0, v117
	v_mul_f32_e32 v116, v116, v116
	v_mul_f32_e32 v118, v118, v118
	v_mul_f32_e32 v117, v117, v117
	v_cvt_pk_bf16_f32 v114, v118, v114
	v_cvt_pk_bf16_f32 v115, v115, v116
	v_cvt_pk_bf16_f32 v116, v122, v119
	v_max_f32_e32 v106, 0, v106
	v_cvt_pk_bf16_f32 v117, v120, v117
	global_store_dwordx4 v[132:133], v[114:117], off offset:256
	s_nop 1
	v_max_f32_e32 v107, 0, v107
	v_max_f32_e32 v108, 0, v108
	v_mul_f32_e32 v116, v106, v106
	v_max_f32_e32 v106, v111, v111
	v_or_b32_e32 v114, 16, v134
	v_max_f32_e32 v106, 0, v106
	v_mul_f32_e32 v111, v107, v107
	v_max_f32_e32 v107, v112, v112
	v_mul_f32_e32 v112, v108, v108
	v_max_f32_e32 v108, v113, v113
	v_mad_i64_i32 v[114:115], s[2:3], v114, s4, v[130:131]
	v_max_f32_e32 v110, 0, v110
	v_mul_f32_e32 v106, v106, v106
	v_max_f32_e32 v107, 0, v107
	v_max_f32_e32 v108, 0, v108
	v_max_f32_e32 v109, 0, v109
	v_lshl_add_u64 v[114:115], v[114:115], 0, v[64:65]
	v_mul_f32_e32 v110, v110, v110
	v_mul_f32_e32 v107, v107, v107
	v_mul_f32_e32 v108, v108, v108
	v_mul_f32_e32 v109, v109, v109
	v_cvt_pk_bf16_f32 v106, v110, v106
	v_max_f32_e32 v98, 0, v98
	v_max_f32_e32 v99, 0, v99
	v_max_f32_e32 v100, 0, v100
	v_cvt_pk_bf16_f32 v107, v107, v108
	v_cvt_pk_bf16_f32 v108, v116, v111
	v_cvt_pk_bf16_f32 v109, v112, v109
	global_store_dwordx4 v[114:115], v[106:109], off
; __device__ __forceinline__ unsigned cvt_pk_bf16(float lo, float hi) { unsigned r; asm volatile("v_cvt_pk_bf16_f32 %0, %1, %2" : "=v"(r) : "v"(lo), "v"(hi)); return r; }
;     __device__ __forceinline__ void operator()(const f32x4 (&acc)[2][2][4][2], const Unit& u, int wr, int wc, int fr, int fq) const {
;     ...
;         for (int ai = 0; ai < 2; ++ai)
; #pragma unroll
;             for (int m = 0; m < 4; ++m) { bf16_t* rowp = O + (size_t)(row0 + ai * HALF + m * 16) * LDF + col0;
; #pragma unroll
;                 for (int bj = 0; bj < 2; ++bj) { f32x4 v0 = acc[ai][bj][m][0], v1 = acc[ai][bj][m][1];
; #pragma unroll
;                     for (int j = 0; j < 4; ++j) { const float a = fmaxf(v0[j], 0.f), b = fmaxf(v1[j], 0.f); v0[j] = a * a; v1[j] = b * b; }
;                     u32x4 w; w.x = cvt_pk_bf16(v0[0], v0[1]); w.y = cvt_pk_bf16(v0[2], v0[3]); w.z = cvt_pk_bf16(v1[0], v1[1]); w.w = cvt_pk_bf16(v1[2], v1[3]);
;                     *(u32x4*)(rowp + bj * HALF) = w; } }
	s_nop 1
	v_mul_f32_e32 v106, v98, v98
	v_max_f32_e32 v98, v103, v103
	v_mul_f32_e32 v103, v99, v99
	v_max_f32_e32 v99, v104, v104
	v_mul_f32_e32 v104, v100, v100
	v_max_f32_e32 v100, v105, v105
	v_max_f32_e32 v98, 0, v98
	v_max_f32_e32 v99, 0, v99
	v_max_f32_e32 v100, 0, v100
	v_max_f32_e32 v102, 0, v102
	v_mul_f32_e32 v98, v98, v98
	v_mul_f32_e32 v99, v99, v99
	v_max_f32_e32 v101, 0, v101
	v_mul_f32_e32 v100, v100, v100
	v_mul_f32_e32 v102, v102, v102
	v_mul_f32_e32 v101, v101, v101
	v_cvt_pk_bf16_f32 v98, v102, v98
	v_cvt_pk_bf16_f32 v99, v99, v100
	v_cvt_pk_bf16_f32 v100, v106, v103
	v_max_f32_e32 v90, 0, v90
	v_cvt_pk_bf16_f32 v101, v104, v101
	global_store_dwordx4 v[114:115], v[98:101], off offset:256
	s_nop 1
	v_max_f32_e32 v91, 0, v91
	v_max_f32_e32 v92, 0, v92
	v_mul_f32_e32 v100, v90, v90
	v_max_f32_e32 v90, v95, v95
	v_or_b32_e32 v98, 32, v134
	v_max_f32_e32 v90, 0, v90
	v_mul_f32_e32 v95, v91, v91
	v_max_f32_e32 v91, v96, v96
	v_mul_f32_e32 v96, v92, v92
	v_max_f32_e32 v92, v97, v97
	v_mad_i64_i32 v[98:99], s[2:3], v98, s4, v[130:131]
	v_max_f32_e32 v94, 0, v94
	v_mul_f32_e32 v90, v90, v90
	v_max_f32_e32 v91, 0, v91
	v_max_f32_e32 v92, 0, v92
	v_max_f32_e32 v93, 0, v93
	v_lshl_add_u64 v[98:99], v[98:99], 0, v[64:65]
	v_mul_f32_e32 v94, v94, v94
	v_mul_f32_e32 v91, v91, v91
	v_mul_f32_e32 v92, v92, v92
	v_mul_f32_e32 v93, v93, v93
	v_cvt_pk_bf16_f32 v90, v94, v90
	v_max_f32_e32 v82, 0, v82
	v_max_f32_e32 v83, 0, v83
	v_max_f32_e32 v84, 0, v84
	v_cvt_pk_bf16_f32 v91, v91, v92
	v_cvt_pk_bf16_f32 v92, v100, v95
	v_cvt_pk_bf16_f32 v93, v96, v93
	global_store_dwordx4 v[98:99], v[90:93], off
	s_nop 1
	v_mul_f32_e32 v90, v82, v82
	v_max_f32_e32 v82, v87, v87
	v_mul_f32_e32 v87, v83, v83
	v_max_f32_e32 v83, v88, v88
	v_mul_f32_e32 v88, v84, v84
	v_max_f32_e32 v84, v89, v89
	v_max_f32_e32 v82, 0, v82
	v_max_f32_e32 v83, 0, v83
	v_max_f32_e32 v84, 0, v84
	v_max_f32_e32 v86, 0, v86
	v_mul_f32_e32 v82, v82, v82
	v_mul_f32_e32 v83, v83, v83
	v_max_f32_e32 v85, 0, v85
	v_mul_f32_e32 v84, v84, v84
	v_mul_f32_e32 v86, v86, v86
	v_mul_f32_e32 v85, v85, v85
	v_cvt_pk_bf16_f32 v82, v86, v82
	v_cvt_pk_bf16_f32 v83, v83, v84
	v_cvt_pk_bf16_f32 v84, v90, v87
	v_max_f32_e32 v74, 0, v74
	v_cvt_pk_bf16_f32 v85, v88, v85
	global_store_dwordx4 v[98:99], v[82:85], off offset:256
	s_nop 1
	v_max_f32_e32 v75, 0, v75
	v_max_f32_e32 v76, 0, v76
	v_mul_f32_e32 v84, v74, v74
	v_max_f32_e32 v74, v79, v79
	v_or_b32_e32 v82, 48, v134
	v_max_f32_e32 v74, 0, v74
	v_mul_f32_e32 v79, v75, v75
	v_max_f32_e32 v75, v80, v80
	v_mul_f32_e32 v80, v76, v76
	v_max_f32_e32 v76, v81, v81
	v_mad_i64_i32 v[82:83], s[2:3], v82, s4, v[130:131]
	v_max_f32_e32 v78, 0, v78
	v_mul_f32_e32 v74, v74, v74
	v_max_f32_e32 v75, 0, v75
	v_max_f32_e32 v76, 0, v76
	v_max_f32_e32 v77, 0, v77
	v_lshl_add_u64 v[82:83], v[82:83], 0, v[64:65]
	v_mul_f32_e32 v78, v78, v78
	v_mul_f32_e32 v75, v75, v75
	v_mul_f32_e32 v76, v76, v76
	v_mul_f32_e32 v77, v77, v77
	v_cvt_pk_bf16_f32 v74, v78, v74
	v_max_f32_e32 v66, 0, v66
	v_max_f32_e32 v67, 0, v67
	v_max_f32_e32 v68, 0, v68
	v_cvt_pk_bf16_f32 v75, v75, v76
	v_cvt_pk_bf16_f32 v76, v84, v79
	v_cvt_pk_bf16_f32 v77, v80, v77
	global_store_dwordx4 v[82:83], v[74:77], off
	s_nop 1
	v_mul_f32_e32 v74, v66, v66
	v_max_f32_e32 v66, v71, v71
	v_mul_f32_e32 v71, v67, v67
	v_max_f32_e32 v67, v72, v72
	v_mul_f32_e32 v72, v68, v68
	v_max_f32_e32 v68, v73, v73
	v_max_f32_e32 v66, 0, v66
	v_max_f32_e32 v67, 0, v67
	v_max_f32_e32 v68, 0, v68
	v_max_f32_e32 v70, 0, v70
	v_mul_f32_e32 v66, v66, v66
	v_mul_f32_e32 v67, v67, v67
	v_max_f32_e32 v69, 0, v69
	v_mul_f32_e32 v68, v68, v68
	v_mul_f32_e32 v70, v70, v70
	v_mul_f32_e32 v69, v69, v69
	v_cvt_pk_bf16_f32 v66, v70, v66
	v_cvt_pk_bf16_f32 v67, v67, v68
	v_cvt_pk_bf16_f32 v68, v74, v71
	v_max_f32_e32 v56, 0, v56
	v_cvt_pk_bf16_f32 v69, v72, v69
	global_store_dwordx4 v[82:83], v[66:69], off offset:256
	s_nop 1
	v_max_f32_e32 v57, 0, v57
	v_max_f32_e32 v58, 0, v58
	v_mul_f32_e32 v68, v56, v56
	v_max_f32_e32 v56, v61, v61
	v_add_u32_e32 v66, 0x80, v134
	v_max_f32_e32 v56, 0, v56
	v_mul_f32_e32 v61, v57, v57
	v_max_f32_e32 v57, v62, v62
	v_mul_f32_e32 v62, v58, v58
	v_max_f32_e32 v58, v63, v63
	v_mad_i64_i32 v[66:67], s[2:3], v66, s4, v[130:131]
	v_max_f32_e32 v60, 0, v60
	v_mul_f32_e32 v56, v56, v56
	v_max_f32_e32 v57, 0, v57
	v_max_f32_e32 v58, 0, v58
	v_max_f32_e32 v59, 0, v59
	v_lshl_add_u64 v[66:67], v[66:67], 0, v[64:65]
	v_mul_f32_e32 v60, v60, v60
	v_mul_f32_e32 v57, v57, v57
	v_mul_f32_e32 v58, v58, v58
	v_mul_f32_e32 v59, v59, v59
	v_cvt_pk_bf16_f32 v56, v60, v56
	v_max_f32_e32 v48, 0, v48
	v_max_f32_e32 v49, 0, v49
	v_max_f32_e32 v50, 0, v50
	v_cvt_pk_bf16_f32 v57, v57, v58
	v_cvt_pk_bf16_f32 v58, v68, v61
	v_cvt_pk_bf16_f32 v59, v62, v59
	global_store_dwordx4 v[66:67], v[56:59], off
	s_nop 1
	v_mul_f32_e32 v56, v48, v48
	v_max_f32_e32 v48, v53, v53
	v_mul_f32_e32 v53, v49, v49
	v_max_f32_e32 v49, v54, v54
	v_mul_f32_e32 v54, v50, v50
	v_max_f32_e32 v50, v55, v55
	v_max_f32_e32 v48, 0, v48
	v_max_f32_e32 v49, 0, v49
	v_max_f32_e32 v50, 0, v50
	v_max_f32_e32 v52, 0, v52
	v_mul_f32_e32 v48, v48, v48
; __device__ __forceinline__ unsigned cvt_pk_bf16(float lo, float hi) { unsigned r; asm volatile("v_cvt_pk_bf16_f32 %0, %1, %2" : "=v"(r) : "v"(lo), "v"(hi)); return r; }
; #define PG8_WAIT_V(n) asm volatile("s_waitcnt vmcnt(" #n ")" ::: "memory")
; #define PG8_BAR __builtin_amdgcn_s_barrier()
;     __device__ __forceinline__ void operator()(const f32x4 (&acc)[2][2][4][2], const Unit& u, int wr, int wc, int fr, int fq) const {
;     ...
;         for (int ai = 0; ai < 2; ++ai)
; #pragma unroll
;             for (int m = 0; m < 4; ++m) { bf16_t* rowp = O + (size_t)(row0 + ai * HALF + m * 16) * LDF + col0;
; #pragma unroll
;                 for (int bj = 0; bj < 2; ++bj) { f32x4 v0 = acc[ai][bj][m][0], v1 = acc[ai][bj][m][1];
; #pragma unroll
;                     for (int j = 0; j < 4; ++j) { const float a = fmaxf(v0[j], 0.f), b = fmaxf(v1[j], 0.f); v0[j] = a * a; v1[j] = b * b; }
;                     u32x4 w; w.x = cvt_pk_bf16(v0[0], v0[1]); w.y = cvt_pk_bf16(v0[2], v0[3]); w.z = cvt_pk_bf16(v1[0], v1[1]); w.w = cvt_pk_bf16(v1[2], v1[3]);
;                     *(u32x4*)(rowp + bj * HALF) = w; } }
;     ...
;     PG8_WAIT_V(0);
;     if (wr == 0) PG8_BAR;
;     PG8_BAR;
	v_mul_f32_e32 v49, v49, v49
	v_max_f32_e32 v51, 0, v51
	v_mul_f32_e32 v50, v50, v50
	v_mul_f32_e32 v52, v52, v52
	v_mul_f32_e32 v51, v51, v51
	v_cvt_pk_bf16_f32 v48, v52, v48
	v_cvt_pk_bf16_f32 v49, v49, v50
	v_cvt_pk_bf16_f32 v50, v56, v53
	v_max_f32_e32 v40, 0, v40
	v_cvt_pk_bf16_f32 v51, v54, v51
	global_store_dwordx4 v[66:67], v[48:51], off offset:256
	s_nop 1
	v_max_f32_e32 v41, 0, v41
	v_max_f32_e32 v42, 0, v42
	v_mul_f32_e32 v50, v40, v40
	v_max_f32_e32 v40, v45, v45
	v_add_u32_e32 v48, 0x90, v134
	v_max_f32_e32 v40, 0, v40
	v_mul_f32_e32 v45, v41, v41
	v_max_f32_e32 v41, v46, v46
	v_mul_f32_e32 v46, v42, v42
	v_max_f32_e32 v42, v47, v47
	v_mad_i64_i32 v[48:49], s[2:3], v48, s4, v[130:131]
	v_max_f32_e32 v44, 0, v44
	v_mul_f32_e32 v40, v40, v40
	v_max_f32_e32 v41, 0, v41
	v_max_f32_e32 v42, 0, v42
	v_max_f32_e32 v43, 0, v43
	v_lshl_add_u64 v[48:49], v[48:49], 0, v[64:65]
	v_mul_f32_e32 v44, v44, v44
	v_mul_f32_e32 v41, v41, v41
	v_mul_f32_e32 v42, v42, v42
	v_mul_f32_e32 v43, v43, v43
	v_cvt_pk_bf16_f32 v40, v44, v40
	v_max_f32_e32 v32, 0, v32
	v_max_f32_e32 v33, 0, v33
	v_max_f32_e32 v34, 0, v34
	v_cvt_pk_bf16_f32 v41, v41, v42
	v_cvt_pk_bf16_f32 v42, v50, v45
	v_cvt_pk_bf16_f32 v43, v46, v43
	global_store_dwordx4 v[48:49], v[40:43], off
	s_nop 1
	v_mul_f32_e32 v40, v32, v32
	v_max_f32_e32 v32, v37, v37
	v_mul_f32_e32 v37, v33, v33
	v_max_f32_e32 v33, v38, v38
	v_mul_f32_e32 v38, v34, v34
	v_max_f32_e32 v34, v39, v39
	v_max_f32_e32 v32, 0, v32
	v_max_f32_e32 v33, 0, v33
	v_max_f32_e32 v34, 0, v34
	v_max_f32_e32 v36, 0, v36
	v_mul_f32_e32 v32, v32, v32
	v_mul_f32_e32 v33, v33, v33
	v_max_f32_e32 v35, 0, v35
	v_mul_f32_e32 v34, v34, v34
	v_mul_f32_e32 v36, v36, v36
	v_mul_f32_e32 v35, v35, v35
	v_cvt_pk_bf16_f32 v32, v36, v32
	v_cvt_pk_bf16_f32 v33, v33, v34
	v_cvt_pk_bf16_f32 v34, v40, v37
	v_max_f32_e32 v24, 0, v24
	v_cvt_pk_bf16_f32 v35, v38, v35
	global_store_dwordx4 v[48:49], v[32:35], off offset:256
	s_nop 1
	v_max_f32_e32 v25, 0, v25
	v_max_f32_e32 v26, 0, v26
	v_mul_f32_e32 v34, v24, v24
	v_max_f32_e32 v24, v29, v29
	v_add_u32_e32 v32, 0xa0, v134
	v_max_f32_e32 v24, 0, v24
	v_mul_f32_e32 v29, v25, v25
	v_max_f32_e32 v25, v30, v30
	v_mul_f32_e32 v30, v26, v26
	v_max_f32_e32 v26, v31, v31
	v_mad_i64_i32 v[32:33], s[2:3], v32, s4, v[130:131]
	v_max_f32_e32 v28, 0, v28
	v_mul_f32_e32 v24, v24, v24
	v_max_f32_e32 v25, 0, v25
	v_max_f32_e32 v26, 0, v26
	v_max_f32_e32 v27, 0, v27
	v_lshl_add_u64 v[32:33], v[32:33], 0, v[64:65]
	v_mul_f32_e32 v28, v28, v28
	v_mul_f32_e32 v25, v25, v25
	v_mul_f32_e32 v26, v26, v26
	v_mul_f32_e32 v27, v27, v27
	v_cvt_pk_bf16_f32 v24, v28, v24
	v_max_f32_e32 v16, 0, v16
	v_max_f32_e32 v17, 0, v17
	v_max_f32_e32 v18, 0, v18
	v_cvt_pk_bf16_f32 v25, v25, v26
	v_cvt_pk_bf16_f32 v26, v34, v29
	v_cvt_pk_bf16_f32 v27, v30, v27
	global_store_dwordx4 v[32:33], v[24:27], off
	s_nop 1
	v_mul_f32_e32 v24, v16, v16
	v_max_f32_e32 v16, v21, v21
	v_mul_f32_e32 v21, v17, v17
	v_max_f32_e32 v17, v22, v22
	v_mul_f32_e32 v22, v18, v18
	v_max_f32_e32 v18, v23, v23
	v_max_f32_e32 v16, 0, v16
	v_max_f32_e32 v17, 0, v17
	v_max_f32_e32 v18, 0, v18
	v_max_f32_e32 v20, 0, v20
	v_mul_f32_e32 v16, v16, v16
	v_mul_f32_e32 v17, v17, v17
	v_max_f32_e32 v19, 0, v19
	v_mul_f32_e32 v18, v18, v18
	v_mul_f32_e32 v20, v20, v20
	v_mul_f32_e32 v19, v19, v19
	v_cvt_pk_bf16_f32 v16, v20, v16
	v_cvt_pk_bf16_f32 v17, v17, v18
	v_cvt_pk_bf16_f32 v18, v24, v21
	v_max_f32_e32 v8, 0, v8
	v_cvt_pk_bf16_f32 v19, v22, v19
	global_store_dwordx4 v[32:33], v[16:19], off offset:256
	s_nop 1
	v_max_f32_e32 v9, 0, v9
	v_max_f32_e32 v10, 0, v10
	v_mul_f32_e32 v18, v8, v8
	v_max_f32_e32 v8, v13, v13
	v_add_u32_e32 v16, 0xb0, v134
	v_max_f32_e32 v8, 0, v8
	v_mul_f32_e32 v13, v9, v9
	v_max_f32_e32 v9, v14, v14
	v_mul_f32_e32 v14, v10, v10
	v_max_f32_e32 v10, v15, v15
	v_mad_i64_i32 v[16:17], s[2:3], v16, s4, v[130:131]
	v_max_f32_e32 v12, 0, v12
	v_mul_f32_e32 v8, v8, v8
	v_max_f32_e32 v9, 0, v9
	v_max_f32_e32 v10, 0, v10
	v_max_f32_e32 v11, 0, v11
	v_lshl_add_u64 v[16:17], v[16:17], 0, v[64:65]
	v_mul_f32_e32 v12, v12, v12
	v_mul_f32_e32 v9, v9, v9
	v_mul_f32_e32 v10, v10, v10
	v_mul_f32_e32 v11, v11, v11
	v_cvt_pk_bf16_f32 v8, v12, v8
	v_max_f32_e32 v0, 0, v0
	v_max_f32_e32 v1, 0, v1
	v_max_f32_e32 v2, 0, v2
	v_cvt_pk_bf16_f32 v9, v9, v10
	v_cvt_pk_bf16_f32 v10, v18, v13
	v_cvt_pk_bf16_f32 v11, v14, v11
	global_store_dwordx4 v[16:17], v[8:11], off
	s_nop 1
	v_mul_f32_e32 v8, v0, v0
	v_max_f32_e32 v0, v5, v5
	v_mul_f32_e32 v5, v1, v1
	v_max_f32_e32 v1, v6, v6
	v_mul_f32_e32 v6, v2, v2
	v_max_f32_e32 v2, v7, v7
	v_max_f32_e32 v0, 0, v0
	v_max_f32_e32 v1, 0, v1
	v_max_f32_e32 v2, 0, v2
	v_max_f32_e32 v3, 0, v3
	v_max_f32_e32 v4, 0, v4
	v_mul_f32_e32 v0, v0, v0
	v_mul_f32_e32 v1, v1, v1
	v_mul_f32_e32 v2, v2, v2
	v_mul_f32_e32 v3, v3, v3
	v_mul_f32_e32 v4, v4, v4
	v_cvt_pk_bf16_f32 v0, v4, v0
	v_cvt_pk_bf16_f32 v1, v1, v2
	v_cvt_pk_bf16_f32 v2, v8, v5
	v_cvt_pk_bf16_f32 v3, v6, v3
	global_store_dwordx4 v[16:17], v[0:3], off offset:256
	s_nop 1
	s_waitcnt vmcnt(0)
	s_cmpk_lt_u32 s14, 0x100
	s_movk_i32 s27, 0x1000
	s_cbranch_scc0 .LBB0_149
	s_barrier

; #define PG8_STAGE(bufoff, gbase, voff) do { _Pragma("unroll") for (int _i = 0; _i < 2; ++_i) \
;         __builtin_amdgcn_global_load_lds((const unsigned*)((const char*)(gbase) + (voff)[_i]), (LAS unsigned*)(lds + (bufoff) + ldsw + _i * 8192), 16, 0, 0); } while (0)
; #define PG8_LDA(dst, b, h) do { _Pragma("unroll") for (int m = 0; m < 4; ++m) _Pragma("unroll") for (int k = 0; k < 2; ++k) dst[m][k] = *(const LAS bf16x8*)(lds + PG8_SA(b, h) + aoff + m * 2048 + k * 1024); } while (0)
; #define PG8_LDB(dst, b, h) do { _Pragma("unroll") for (int n = 0; n < 2; ++n) _Pragma("unroll") for (int k = 0; k < 2; ++k) dst[n][k] = *(const LAS bf16x8*)(lds + PG8_SB(b, h) + boff + n * 2048 + k * 1024); } while (0)
; #define PG8_MMA(ai, bj, At, Bt) do { __builtin_amdgcn_s_setprio(1); _Pragma("unroll") for (int m = 0; m < 4; ++m) _Pragma("unroll") for (int n = 0; n < 2; ++n) _Pragma("unroll") for (int k = 0; k < 2; ++k) \
;         acc[ai][bj][m][n] = __builtin_amdgcn_mfma_f32_16x16x32_bf16(Bt[n][k], At[m][k], acc[ai][bj][m][n], 0, 0, 0); __builtin_amdgcn_s_setprio(0); } while (0)
; #define PG8_WAIT_V(n) asm volatile("s_waitcnt vmcnt(" #n ")" ::: "memory")
; #define PG8_WAIT_L(n) asm volatile("s_waitcnt lgkmcnt(" #n ")" ::: "memory")
; #define PG8_BAR __builtin_amdgcn_s_barrier()
; #define PG8_SCHED __builtin_amdgcn_sched_barrier(0)
;     ...
;             const char* a1 = cA + (size_t)(t + 1) * kstep;
;             const char* a2 = last ? nA : cA + (size_t)(t + 2) * kstep; const char* b2 = last ? nB : cB + (size_t)(t + 2) * kstep;
;             const char* a3 = a2 + kstep; const char* b3 = b2 + kstep;
;             PG8_LDB(B0, 0, 0); PG8_SCHED; PG8_LDA(At, 0, 0); PG8_STAGE(PG8_SA(1, 1), a1 + hstep, voffA);
;             PG8_WAIT_L(8); PG8_BAR; PG8_WAIT_L(0); PG8_MMA(0, 0, At, B0); PG8_BAR; PG8_SCHED;
;             PG8_LDB(B1, 0, 1); PG8_STAGE(PG8_SB(0, 0), b2, voffB);
;             PG8_BAR; PG8_WAIT_L(0); PG8_MMA(0, 1, At, B1); PG8_BAR;
;             PG8_LDA(At, 0, 1); PG8_STAGE(PG8_SA(0, 0), a2, voffA);
;             PG8_BAR; PG8_WAIT_L(0); PG8_MMA(1, 0, At, B0); PG8_BAR; PG8_SCHED;
;             PG8_STAGE(PG8_SB(0, 1), b2 + hstep, voffB);
;             PG8_WAIT_V(6); PG8_BAR; PG8_MMA(1, 1, At, B1); PG8_BAR;
.LBB0_475:
	s_or_b32 s94, s12, 1
	s_add_i32 s12, s12, 2
	s_mov_b32 s13, s95
	s_lshl_b64 s[2:3], s[12:13], 7
	s_add_u32 s7, s24, s2
	s_addc_u32 s13, s25, s3
	s_and_b64 vcc, s[44:45], exec
	s_cselect_b32 vcc_hi, s85, s13
	s_cselect_b32 vcc_lo, s84, s7
	s_add_u32 s7, s42, s2
	s_addc_u32 s13, s43, s3
	s_add_i32 s35, 0, 0x10000
	v_add_u32_e32 v64, s35, v220
	ds_read_b128 v[134:137], v64
	ds_read_b128 v[138:141], v64 offset:1024
	ds_read_b128 v[142:145], v64 offset:2048
	ds_read_b128 v[146:149], v64 offset:3072
	s_and_b64 s[2:3], s[44:45], exec
	s_cselect_b32 s45, s9, s13
	s_cselect_b32 s44, s8, s7
	s_lshl_b64 s[2:3], s[94:95], 7
	s_add_u32 s2, s47, s2
	s_addc_u32 s3, s89, s3
	v_lshl_add_u64 v[182:183], s[2:3], 0, v[130:131]
	s_add_i32 m0, s19, 0xc000
	ds_read_b128 v[150:153], v229
	ds_read_b128 v[154:157], v229 offset:1024
	ds_read_b128 v[158:161], v229 offset:2048
	ds_read_b128 v[162:165], v229 offset:3072
	ds_read_b128 v[166:169], v229 offset:4096
	ds_read_b128 v[170:173], v229 offset:5120
	ds_read_b128 v[174:177], v229 offset:6144
	ds_read_b128 v[178:181], v229 offset:7168
	global_load_lds_dwordx4 v[182:183], off
	v_lshl_add_u64 v[182:183], s[2:3], 0, v[132:133]
	s_add_i32 m0, s19, 0xe000
	s_nop 0
	global_load_lds_dwordx4 v[182:183], off
	s_waitcnt lgkmcnt(8)
	s_barrier
	s_waitcnt lgkmcnt(0)
	s_setprio 0
	s_waitcnt lgkmcnt(0)
	v_mfma_f32_16x16x32_bf16 v[118:121], v[134:137], v[150:153], v[118:121]
	v_mfma_f32_16x16x32_bf16 v[114:117], v[142:145], v[150:153], v[114:117]
	v_mfma_f32_16x16x32_bf16 v[102:105], v[134:137], v[158:161], v[102:105]
	v_mfma_f32_16x16x32_bf16 v[98:101], v[142:145], v[158:161], v[98:101]
	v_mfma_f32_16x16x32_bf16 v[86:89], v[134:137], v[166:169], v[86:89]
	v_mfma_f32_16x16x32_bf16 v[82:85], v[142:145], v[166:169], v[82:85]
	v_mfma_f32_16x16x32_bf16 v[70:73], v[134:137], v[174:177], v[70:73]
	v_mfma_f32_16x16x32_bf16 v[66:69], v[142:145], v[174:177], v[66:69]
	v_mfma_f32_16x16x32_bf16 v[118:121], v[138:141], v[154:157], v[118:121]
	v_mfma_f32_16x16x32_bf16 v[114:117], v[146:149], v[154:157], v[114:117]
	v_mfma_f32_16x16x32_bf16 v[102:105], v[138:141], v[162:165], v[102:105]
	v_mfma_f32_16x16x32_bf16 v[98:101], v[146:149], v[162:165], v[98:101]
	v_mfma_f32_16x16x32_bf16 v[86:89], v[138:141], v[170:173], v[86:89]
	v_mfma_f32_16x16x32_bf16 v[82:85], v[146:149], v[170:173], v[82:85]
	v_mfma_f32_16x16x32_bf16 v[70:73], v[138:141], v[178:181], v[70:73]
	v_mfma_f32_16x16x32_bf16 v[66:69], v[146:149], v[178:181], v[66:69]
	s_setprio 1
	s_barrier
	s_add_i32 s7, 0, 0x14000
	s_add_i32 s2, s35, s18
	v_add_u32_e32 v64, s7, v220
	v_lshl_add_u64 v[198:199], s[44:45], 0, v[130:131]
	s_mov_b32 m0, s2
	ds_read_b128 v[182:185], v64
	ds_read_b128 v[186:189], v64 offset:1024
	ds_read_b128 v[190:193], v64 offset:2048
	ds_read_b128 v[194:197], v64 offset:3072
	global_load_lds_dwordx4 v[198:199], off
	v_lshl_add_u64 v[246:247], s[44:45], 0, v[132:133]
	s_add_i32 m0, s2, 0x2000
	s_nop 0
	global_load_lds_dwordx4 v[246:247], off
	s_barrier
	s_waitcnt lgkmcnt(0)
	s_setprio 0
	s_waitcnt lgkmcnt(0)
	v_mfma_f32_16x16x32_bf16 v[126:129], v[182:185], v[150:153], v[126:129]
	v_mfma_f32_16x16x32_bf16 v[122:125], v[190:193], v[150:153], v[122:125]
	v_mfma_f32_16x16x32_bf16 v[110:113], v[182:185], v[158:161], v[110:113]
	v_mfma_f32_16x16x32_bf16 v[106:109], v[190:193], v[158:161], v[106:109]
	v_mfma_f32_16x16x32_bf16 v[94:97], v[182:185], v[166:169], v[94:97]
	v_mfma_f32_16x16x32_bf16 v[90:93], v[190:193], v[166:169], v[90:93]
	v_mfma_f32_16x16x32_bf16 v[78:81], v[182:185], v[174:177], v[78:81]
	v_mfma_f32_16x16x32_bf16 v[74:77], v[190:193], v[174:177], v[74:77]
	v_mfma_f32_16x16x32_bf16 v[126:129], v[186:189], v[154:157], v[126:129]
	v_mfma_f32_16x16x32_bf16 v[122:125], v[194:197], v[154:157], v[122:125]
	v_mfma_f32_16x16x32_bf16 v[110:113], v[186:189], v[162:165], v[110:113]
	v_mfma_f32_16x16x32_bf16 v[106:109], v[194:197], v[162:165], v[106:109]
	v_mfma_f32_16x16x32_bf16 v[94:97], v[186:189], v[170:173], v[94:97]
	v_mfma_f32_16x16x32_bf16 v[90:93], v[194:197], v[170:173], v[90:93]
	v_mfma_f32_16x16x32_bf16 v[78:81], v[186:189], v[178:181], v[78:81]
	v_mfma_f32_16x16x32_bf16 v[74:77], v[194:197], v[178:181], v[74:77]
	s_setprio 1
	s_mov_b32 m0, s19
	v_lshl_add_u64 v[212:213], vcc, 0, v[130:131]
	s_barrier
	ds_read_b128 v[150:153], v229 offset:16384
	ds_read_b128 v[154:157], v229 offset:17408
	ds_read_b128 v[158:161], v229 offset:18432
	ds_read_b128 v[162:165], v229 offset:19456
	ds_read_b128 v[166:169], v229 offset:20480
	ds_read_b128 v[170:173], v229 offset:21504
	ds_read_b128 v[174:177], v229 offset:22528
	ds_read_b128 v[178:181], v229 offset:23552
	global_load_lds_dwordx4 v[212:213], off
	v_lshl_add_u64 v[208:209], vcc, 0, v[132:133]
	s_mov_b32 m0, s21
	s_nop 0
	global_load_lds_dwordx4 v[208:209], off
	s_barrier
	s_waitcnt lgkmcnt(0)
	s_setprio 0
	s_waitcnt lgkmcnt(0)
	v_mfma_f32_16x16x32_bf16 v[52:55], v[134:137], v[150:153], v[52:55]
	v_mfma_f32_16x16x32_bf16 v[48:51], v[142:145], v[150:153], v[48:51]
	v_mfma_f32_16x16x32_bf16 v[36:39], v[134:137], v[158:161], v[36:39]
	v_mfma_f32_16x16x32_bf16 v[32:35], v[142:145], v[158:161], v[32:35]
	v_mfma_f32_16x16x32_bf16 v[20:23], v[134:137], v[166:169], v[20:23]
	v_mfma_f32_16x16x32_bf16 v[16:19], v[142:145], v[166:169], v[16:19]
	v_mfma_f32_16x16x32_bf16 v[4:7], v[134:137], v[174:177], v[4:7]
	v_mfma_f32_16x16x32_bf16 v[0:3], v[142:145], v[174:177], v[0:3]
	v_mfma_f32_16x16x32_bf16 v[52:55], v[138:141], v[154:157], v[52:55]
	v_mfma_f32_16x16x32_bf16 v[48:51], v[146:149], v[154:157], v[48:51]
	v_mfma_f32_16x16x32_bf16 v[36:39], v[138:141], v[162:165], v[36:39]
	v_mfma_f32_16x16x32_bf16 v[32:35], v[146:149], v[162:165], v[32:35]
	v_mfma_f32_16x16x32_bf16 v[20:23], v[138:141], v[170:173], v[20:23]
	v_mfma_f32_16x16x32_bf16 v[16:19], v[146:149], v[170:173], v[16:19]
	v_mfma_f32_16x16x32_bf16 v[4:7], v[138:141], v[178:181], v[4:7]
	v_mfma_f32_16x16x32_bf16 v[0:3], v[146:149], v[178:181], v[0:3]
	s_setprio 1
	s_barrier
; #define PG8_STAGE(bufoff, gbase, voff) do { _Pragma("unroll") for (int _i = 0; _i < 2; ++_i) \
;         __builtin_amdgcn_global_load_lds((const unsigned*)((const char*)(gbase) + (voff)[_i]), (LAS unsigned*)(lds + (bufoff) + ldsw + _i * 8192), 16, 0, 0); } while (0)
; #define PG8_LDA(dst, b, h) do { _Pragma("unroll") for (int m = 0; m < 4; ++m) _Pragma("unroll") for (int k = 0; k < 2; ++k) dst[m][k] = *(const LAS bf16x8*)(lds + PG8_SA(b, h) + aoff + m * 2048 + k * 1024); } while (0)
; #define PG8_LDB(dst, b, h) do { _Pragma("unroll") for (int n = 0; n < 2; ++n) _Pragma("unroll") for (int k = 0; k < 2; ++k) dst[n][k] = *(const LAS bf16x8*)(lds + PG8_SB(b, h) + boff + n * 2048 + k * 1024); } while (0)
; #define PG8_MMA(ai, bj, At, Bt) do { __builtin_amdgcn_s_setprio(1); _Pragma("unroll") for (int m = 0; m < 4; ++m) _Pragma("unroll") for (int n = 0; n < 2; ++n) _Pragma("unroll") for (int k = 0; k < 2; ++k) \
;         acc[ai][bj][m][n] = __builtin_amdgcn_mfma_f32_16x16x32_bf16(Bt[n][k], At[m][k], acc[ai][bj][m][n], 0, 0, 0); __builtin_amdgcn_s_setprio(0); } while (0)
; #define PG8_WAIT_V(n) asm volatile("s_waitcnt vmcnt(" #n ")" ::: "memory")
; #define PG8_WAIT_L(n) asm volatile("s_waitcnt lgkmcnt(" #n ")" ::: "memory")
; #define PG8_BAR __builtin_amdgcn_s_barrier()
; #define PG8_SCHED __builtin_amdgcn_sched_barrier(0)
;     ...
;             PG8_STAGE(PG8_SB(0, 1), b2 + hstep, voffB);
;             PG8_WAIT_V(6); PG8_BAR; PG8_MMA(1, 1, At, B1); PG8_BAR;
;             PG8_LDB(B0, 1, 0); PG8_SCHED; PG8_LDA(At, 1, 0); PG8_STAGE(PG8_SA(0, 1), a2 + hstep, voffA);
;             PG8_WAIT_L(8); PG8_BAR; PG8_WAIT_L(0); PG8_MMA(0, 0, At, B0); PG8_BAR; PG8_SCHED;
;             PG8_LDB(B1, 1, 1); PG8_STAGE(PG8_SB(1, 0), b3, voffB);
;             PG8_BAR; PG8_WAIT_L(0); PG8_MMA(0, 1, At, B1); PG8_BAR;
;             PG8_LDA(At, 1, 1); PG8_STAGE(PG8_SA(1, 0), a3, voffA);
;             PG8_BAR; PG8_WAIT_L(0); PG8_MMA(1, 0, At, B0); PG8_BAR; PG8_SCHED;
;             PG8_STAGE(PG8_SB(1, 1), b3 + hstep, voffB);
	s_add_u32 s2, s44, s82
	s_addc_u32 s3, s45, 0
	s_add_i32 s7, s7, s18
	v_lshl_add_u64 v[210:211], s[2:3], 0, v[130:131]
	s_mov_b32 m0, s7
	v_lshl_add_u64 v[214:215], s[2:3], 0, v[132:133]
	global_load_lds_dwordx4 v[210:211], off
	s_add_i32 m0, s7, 0x2000
	s_nop 0
	global_load_lds_dwordx4 v[214:215], off
	s_waitcnt vmcnt(6)
	s_barrier
	s_setprio 0
	v_mfma_f32_16x16x32_bf16 v[60:63], v[182:185], v[150:153], v[60:63]
	v_mfma_f32_16x16x32_bf16 v[56:59], v[190:193], v[150:153], v[56:59]
	v_mfma_f32_16x16x32_bf16 v[44:47], v[182:185], v[158:161], v[44:47]
	v_mfma_f32_16x16x32_bf16 v[40:43], v[190:193], v[158:161], v[40:43]
	v_mfma_f32_16x16x32_bf16 v[28:31], v[182:185], v[166:169], v[28:31]
	v_mfma_f32_16x16x32_bf16 v[24:27], v[190:193], v[166:169], v[24:27]
	v_mfma_f32_16x16x32_bf16 v[12:15], v[182:185], v[174:177], v[12:15]
	v_mfma_f32_16x16x32_bf16 v[8:11], v[190:193], v[174:177], v[8:11]
	v_mfma_f32_16x16x32_bf16 v[60:63], v[186:189], v[154:157], v[60:63]
	v_mfma_f32_16x16x32_bf16 v[56:59], v[194:197], v[154:157], v[56:59]
	v_mfma_f32_16x16x32_bf16 v[44:47], v[186:189], v[162:165], v[44:47]
	v_mfma_f32_16x16x32_bf16 v[40:43], v[194:197], v[162:165], v[40:43]
	v_mfma_f32_16x16x32_bf16 v[28:31], v[186:189], v[170:173], v[28:31]
	v_mfma_f32_16x16x32_bf16 v[24:27], v[194:197], v[170:173], v[24:27]
	v_mfma_f32_16x16x32_bf16 v[12:15], v[186:189], v[178:181], v[12:15]
	v_mfma_f32_16x16x32_bf16 v[8:11], v[194:197], v[178:181], v[8:11]
	s_setprio 1
	s_add_i32 s7, 0, 0x18000
	v_add_u32_e32 v64, s7, v220
	s_barrier
	ds_read_b128 v[134:137], v64
	ds_read_b128 v[138:141], v64 offset:1024
	ds_read_b128 v[142:145], v64 offset:2048
	ds_read_b128 v[146:149], v64 offset:3072
	s_add_u32 s2, vcc_lo, s82
	s_addc_u32 s3, vcc_hi, 0
	s_mov_b32 m0, s31
	v_lshl_add_u64 v[182:183], s[2:3], 0, v[130:131]
	ds_read_b128 v[150:153], v229 offset:32768
	ds_read_b128 v[154:157], v229 offset:33792
	ds_read_b128 v[158:161], v229 offset:34816
	ds_read_b128 v[162:165], v229 offset:35840
	ds_read_b128 v[166:169], v229 offset:36864
	ds_read_b128 v[170:173], v229 offset:37888
	ds_read_b128 v[174:177], v229 offset:38912
	ds_read_b128 v[178:181], v229 offset:39936
	global_load_lds_dwordx4 v[182:183], off
	v_lshl_add_u64 v[182:183], s[2:3], 0, v[132:133]
	s_mov_b32 m0, s83
	s_nop 0
	global_load_lds_dwordx4 v[182:183], off
	s_waitcnt lgkmcnt(8)
	s_barrier
	s_waitcnt lgkmcnt(0)
	s_setprio 0
	s_waitcnt lgkmcnt(0)
	v_mfma_f32_16x16x32_bf16 v[118:121], v[134:137], v[150:153], v[118:121]
	v_mfma_f32_16x16x32_bf16 v[114:117], v[142:145], v[150:153], v[114:117]
	v_mfma_f32_16x16x32_bf16 v[102:105], v[134:137], v[158:161], v[102:105]
	v_mfma_f32_16x16x32_bf16 v[98:101], v[142:145], v[158:161], v[98:101]
	v_mfma_f32_16x16x32_bf16 v[86:89], v[134:137], v[166:169], v[86:89]
	v_mfma_f32_16x16x32_bf16 v[82:85], v[142:145], v[166:169], v[82:85]
	v_mfma_f32_16x16x32_bf16 v[70:73], v[134:137], v[174:177], v[70:73]
	v_mfma_f32_16x16x32_bf16 v[66:69], v[142:145], v[174:177], v[66:69]
	v_mfma_f32_16x16x32_bf16 v[118:121], v[138:141], v[154:157], v[118:121]
	v_mfma_f32_16x16x32_bf16 v[114:117], v[146:149], v[154:157], v[114:117]
	v_mfma_f32_16x16x32_bf16 v[102:105], v[138:141], v[162:165], v[102:105]
	v_mfma_f32_16x16x32_bf16 v[98:101], v[146:149], v[162:165], v[98:101]
	v_mfma_f32_16x16x32_bf16 v[86:89], v[138:141], v[170:173], v[86:89]
	v_mfma_f32_16x16x32_bf16 v[82:85], v[146:149], v[170:173], v[82:85]
	v_mfma_f32_16x16x32_bf16 v[70:73], v[138:141], v[178:181], v[70:73]
	v_mfma_f32_16x16x32_bf16 v[66:69], v[146:149], v[178:181], v[66:69]
	s_setprio 1
	s_barrier
	s_add_i32 s2, 0, 0x1c000
	s_add_i32 s3, s7, s18
	v_add_u32_e32 v64, s2, v220
	v_lshl_add_u64 v[198:199], v[198:199], 0, s[16:17]
	s_mov_b32 m0, s3
	ds_read_b128 v[182:185], v64
	ds_read_b128 v[186:189], v64 offset:1024
	ds_read_b128 v[190:193], v64 offset:2048
	ds_read_b128 v[194:197], v64 offset:3072
	global_load_lds_dwordx4 v[198:199], off
	v_lshl_add_u64 v[198:199], v[246:247], 0, s[16:17]
	s_add_i32 m0, s3, 0x2000
	s_nop 0
	global_load_lds_dwordx4 v[198:199], off
	s_barrier
; #define PG8_STAGE(bufoff, gbase, voff) do { _Pragma("unroll") for (int _i = 0; _i < 2; ++_i) \
;         __builtin_amdgcn_global_load_lds((const unsigned*)((const char*)(gbase) + (voff)[_i]), (LAS unsigned*)(lds + (bufoff) + ldsw + _i * 8192), 16, 0, 0); } while (0)
; #define PG8_LDA(dst, b, h) do { _Pragma("unroll") for (int m = 0; m < 4; ++m) _Pragma("unroll") for (int k = 0; k < 2; ++k) dst[m][k] = *(const LAS bf16x8*)(lds + PG8_SA(b, h) + aoff + m * 2048 + k * 1024); } while (0)
; #define PG8_MMA(ai, bj, At, Bt) do { __builtin_amdgcn_s_setprio(1); _Pragma("unroll") for (int m = 0; m < 4; ++m) _Pragma("unroll") for (int n = 0; n < 2; ++n) _Pragma("unroll") for (int k = 0; k < 2; ++k) \
;         acc[ai][bj][m][n] = __builtin_amdgcn_mfma_f32_16x16x32_bf16(Bt[n][k], At[m][k], acc[ai][bj][m][n], 0, 0, 0); __builtin_amdgcn_s_setprio(0); } while (0)
; #define PG8_WAIT_V(n) asm volatile("s_waitcnt vmcnt(" #n ")" ::: "memory")
; #define PG8_WAIT_L(n) asm volatile("s_waitcnt lgkmcnt(" #n ")" ::: "memory")
; #define PG8_BAR __builtin_amdgcn_s_barrier()
; #define PG8_SCHED __builtin_amdgcn_sched_barrier(0)
;     ...
;             PG8_BAR; PG8_WAIT_L(0); PG8_MMA(0, 1, At, B1); PG8_BAR;
;             PG8_LDA(At, 1, 1); PG8_STAGE(PG8_SA(1, 0), a3, voffA);
;             PG8_BAR; PG8_WAIT_L(0); PG8_MMA(1, 0, At, B0); PG8_BAR; PG8_SCHED;
;             PG8_STAGE(PG8_SB(1, 1), b3 + hstep, voffB);
;             PG8_WAIT_V(6); PG8_BAR; PG8_MMA(1, 1, At, B1); PG8_BAR;
	s_waitcnt lgkmcnt(0)
	s_setprio 0
	s_waitcnt lgkmcnt(0)
	v_mfma_f32_16x16x32_bf16 v[126:129], v[182:185], v[150:153], v[126:129]
	v_mfma_f32_16x16x32_bf16 v[122:125], v[190:193], v[150:153], v[122:125]
	v_mfma_f32_16x16x32_bf16 v[110:113], v[182:185], v[158:161], v[110:113]
	v_mfma_f32_16x16x32_bf16 v[106:109], v[190:193], v[158:161], v[106:109]
	v_mfma_f32_16x16x32_bf16 v[94:97], v[182:185], v[166:169], v[94:97]
	v_mfma_f32_16x16x32_bf16 v[90:93], v[190:193], v[166:169], v[90:93]
	v_mfma_f32_16x16x32_bf16 v[78:81], v[182:185], v[174:177], v[78:81]
	v_mfma_f32_16x16x32_bf16 v[74:77], v[190:193], v[174:177], v[74:77]
	v_mfma_f32_16x16x32_bf16 v[126:129], v[186:189], v[154:157], v[126:129]
	v_mfma_f32_16x16x32_bf16 v[122:125], v[194:197], v[154:157], v[122:125]
	v_mfma_f32_16x16x32_bf16 v[110:113], v[186:189], v[162:165], v[110:113]
	v_mfma_f32_16x16x32_bf16 v[106:109], v[194:197], v[162:165], v[106:109]
	v_mfma_f32_16x16x32_bf16 v[94:97], v[186:189], v[170:173], v[94:97]
	v_mfma_f32_16x16x32_bf16 v[90:93], v[194:197], v[170:173], v[90:93]
	v_mfma_f32_16x16x32_bf16 v[78:81], v[186:189], v[178:181], v[78:81]
	v_mfma_f32_16x16x32_bf16 v[74:77], v[194:197], v[178:181], v[74:77]
	s_setprio 1
	s_mov_b32 m0, s36
	v_lshl_add_u64 v[198:199], v[212:213], 0, s[16:17]
	s_barrier
	ds_read_b128 v[150:153], v229 offset:49152
	ds_read_b128 v[154:157], v229 offset:50176
	ds_read_b128 v[158:161], v229 offset:51200
	ds_read_b128 v[162:165], v229 offset:52224
	ds_read_b128 v[166:169], v229 offset:53248
	ds_read_b128 v[170:173], v229 offset:54272
	ds_read_b128 v[174:177], v229 offset:55296
	ds_read_b128 v[178:181], v229 offset:56320
	global_load_lds_dwordx4 v[198:199], off
	v_lshl_add_u64 v[198:199], v[208:209], 0, s[16:17]
	s_mov_b32 m0, s37
	s_nop 0
	global_load_lds_dwordx4 v[198:199], off
	s_barrier
	s_waitcnt lgkmcnt(0)
	s_setprio 0
	s_waitcnt lgkmcnt(0)
	v_mfma_f32_16x16x32_bf16 v[52:55], v[134:137], v[150:153], v[52:55]
	v_mfma_f32_16x16x32_bf16 v[48:51], v[142:145], v[150:153], v[48:51]
	v_mfma_f32_16x16x32_bf16 v[36:39], v[134:137], v[158:161], v[36:39]
	v_mfma_f32_16x16x32_bf16 v[32:35], v[142:145], v[158:161], v[32:35]
	v_mfma_f32_16x16x32_bf16 v[20:23], v[134:137], v[166:169], v[20:23]
	v_mfma_f32_16x16x32_bf16 v[16:19], v[142:145], v[166:169], v[16:19]
	v_mfma_f32_16x16x32_bf16 v[4:7], v[134:137], v[174:177], v[4:7]
	v_mfma_f32_16x16x32_bf16 v[0:3], v[142:145], v[174:177], v[0:3]
	v_mfma_f32_16x16x32_bf16 v[52:55], v[138:141], v[154:157], v[52:55]
	v_mfma_f32_16x16x32_bf16 v[48:51], v[146:149], v[154:157], v[48:51]
	v_mfma_f32_16x16x32_bf16 v[36:39], v[138:141], v[162:165], v[36:39]
	v_mfma_f32_16x16x32_bf16 v[32:35], v[146:149], v[162:165], v[32:35]
	v_mfma_f32_16x16x32_bf16 v[20:23], v[138:141], v[170:173], v[20:23]
	v_mfma_f32_16x16x32_bf16 v[16:19], v[146:149], v[170:173], v[16:19]
	v_mfma_f32_16x16x32_bf16 v[4:7], v[138:141], v[178:181], v[4:7]
	v_mfma_f32_16x16x32_bf16 v[0:3], v[146:149], v[178:181], v[0:3]
	s_setprio 1
	s_barrier
	s_add_i32 s2, s2, s18
	v_lshl_add_u64 v[134:135], v[210:211], 0, s[16:17]
	s_mov_b32 m0, s2
	s_nop 0
	global_load_lds_dwordx4 v[134:135], off
	v_lshl_add_u64 v[134:135], v[214:215], 0, s[16:17]
	s_add_i32 m0, s2, 0x2000
	s_nop 0
	global_load_lds_dwordx4 v[134:135], off
	s_waitcnt vmcnt(6)
	s_barrier
	s_setprio 0
	v_mfma_f32_16x16x32_bf16 v[60:63], v[182:185], v[150:153], v[60:63]
	v_mfma_f32_16x16x32_bf16 v[56:59], v[190:193], v[150:153], v[56:59]
	v_mfma_f32_16x16x32_bf16 v[44:47], v[182:185], v[158:161], v[44:47]
	v_mfma_f32_16x16x32_bf16 v[40:43], v[190:193], v[158:161], v[40:43]
	v_mfma_f32_16x16x32_bf16 v[28:31], v[182:185], v[166:169], v[28:31]
	v_mfma_f32_16x16x32_bf16 v[24:27], v[190:193], v[166:169], v[24:27]
	v_mfma_f32_16x16x32_bf16 v[12:15], v[182:185], v[174:177], v[12:15]
	v_mfma_f32_16x16x32_bf16 v[8:11], v[190:193], v[174:177], v[8:11]
	v_mfma_f32_16x16x32_bf16 v[60:63], v[186:189], v[154:157], v[60:63]
	v_mfma_f32_16x16x32_bf16 v[56:59], v[194:197], v[154:157], v[56:59]
	v_mfma_f32_16x16x32_bf16 v[44:47], v[186:189], v[162:165], v[44:47]
	v_mfma_f32_16x16x32_bf16 v[40:43], v[194:197], v[162:165], v[40:43]
	v_mfma_f32_16x16x32_bf16 v[28:31], v[186:189], v[170:173], v[28:31]
	v_mfma_f32_16x16x32_bf16 v[24:27], v[194:197], v[170:173], v[24:27]
	v_mfma_f32_16x16x32_bf16 v[12:15], v[186:189], v[178:181], v[12:15]
	v_mfma_f32_16x16x32_bf16 v[8:11], v[194:197], v[178:181], v[8:11]
	s_setprio 1
	s_cmp_ge_u32 s12, s6
	s_barrier
	s_cbranch_scc1 .LBB0_482

; #define PG8_STAGE(bufoff, gbase, voff) do { _Pragma("unroll") for (int _i = 0; _i < 2; ++_i) \
;         __builtin_amdgcn_global_load_lds((const unsigned*)((const char*)(gbase) + (voff)[_i]), (LAS unsigned*)(lds + (bufoff) + ldsw + _i * 8192), 16, 0, 0); } while (0)
; #define PG8_LDA(dst, b, h) do { _Pragma("unroll") for (int m = 0; m < 4; ++m) _Pragma("unroll") for (int k = 0; k < 2; ++k) dst[m][k] = *(const LAS bf16x8*)(lds + PG8_SA(b, h) + aoff + m * 2048 + k * 1024); } while (0)
; #define PG8_LDB(dst, b, h) do { _Pragma("unroll") for (int n = 0; n < 2; ++n) _Pragma("unroll") for (int k = 0; k < 2; ++k) dst[n][k] = *(const LAS bf16x8*)(lds + PG8_SB(b, h) + boff + n * 2048 + k * 1024); } while (0)
; #define PG8_MMA(ai, bj, At, Bt) do { __builtin_amdgcn_s_setprio(1); _Pragma("unroll") for (int m = 0; m < 4; ++m) _Pragma("unroll") for (int n = 0; n < 2; ++n) _Pragma("unroll") for (int k = 0; k < 2; ++k) \
;         acc[ai][bj][m][n] = __builtin_amdgcn_mfma_f32_16x16x32_bf16(Bt[n][k], At[m][k], acc[ai][bj][m][n], 0, 0, 0); __builtin_amdgcn_s_setprio(0); } while (0)
; #define PG8_WAIT_V(n) asm volatile("s_waitcnt vmcnt(" #n ")" ::: "memory")
; #define PG8_WAIT_L(n) asm volatile("s_waitcnt lgkmcnt(" #n ")" ::: "memory")
; #define PG8_BAR __builtin_amdgcn_s_barrier()
; #define PG8_SCHED __builtin_amdgcn_sched_barrier(0)
;     ...
;             const char* a1 = cA + (size_t)(t + 1) * kstep;
;             const char* a2 = last ? nA : cA + (size_t)(t + 2) * kstep; const char* b2 = last ? nB : cB + (size_t)(t + 2) * kstep;
;             const char* a3 = a2 + kstep; const char* b3 = b2 + kstep;
;             PG8_LDB(B0, 0, 0); PG8_SCHED; PG8_LDA(At, 0, 0); PG8_STAGE(PG8_SA(1, 1), a1 + hstep, voffA);
;             PG8_WAIT_L(8); PG8_BAR; PG8_WAIT_L(0); PG8_MMA(0, 0, At, B0); PG8_BAR; PG8_SCHED;
;             PG8_LDB(B1, 0, 1); PG8_STAGE(PG8_SB(0, 0), b2, voffB);
;             PG8_BAR; PG8_WAIT_L(0); PG8_MMA(0, 1, At, B1); PG8_BAR;
;             PG8_LDA(At, 0, 1); PG8_STAGE(PG8_SA(0, 0), a2, voffA);
;             PG8_BAR; PG8_WAIT_L(0); PG8_MMA(1, 0, At, B0); PG8_BAR; PG8_SCHED;
;             PG8_STAGE(PG8_SB(0, 1), b2 + hstep, voffB);
;             PG8_WAIT_V(6); PG8_BAR; PG8_MMA(1, 1, At, B1); PG8_BAR;
.LBB0_1275:
	s_add_u32 s2, s6, 0xe767c080
	s_addc_u32 s3, s7, -1
	s_cmp_lg_u32 s23, 28
	s_cselect_b32 s8, s2, 0
	s_cselect_b32 s9, s3, 0
	s_add_u32 s2, s4, s8
	s_addc_u32 s3, s5, s9
	s_add_i32 s24, 0, 0x10000
	v_add_u32_e32 v152, s24, v138
	ds_read_b128 v[140:143], v152
	ds_read_b128 v[144:147], v152 offset:1024
	ds_read_b128 v[148:151], v152 offset:2048
	ds_read_b128 v[152:155], v152 offset:3072
	s_add_u32 s8, s0, s8
	s_addc_u32 s9, s1, s9
	v_lshl_add_u64 v[188:189], v[132:133], 0, s[6:7]
	s_add_i32 m0, s15, 0xc000
	ds_read_b128 v[156:159], v139
	ds_read_b128 v[160:163], v139 offset:1024
	ds_read_b128 v[164:167], v139 offset:2048
	ds_read_b128 v[168:171], v139 offset:3072
	ds_read_b128 v[172:175], v139 offset:4096
	ds_read_b128 v[176:179], v139 offset:5120
	ds_read_b128 v[180:183], v139 offset:6144
	ds_read_b128 v[184:187], v139 offset:7168
	global_load_lds_dwordx4 v[188:189], off
	v_lshl_add_u64 v[188:189], v[134:135], 0, s[6:7]
	s_add_i32 m0, s15, 0xe000
	s_nop 0
	global_load_lds_dwordx4 v[188:189], off
	s_waitcnt lgkmcnt(8)
	s_barrier
	s_waitcnt lgkmcnt(0)
	s_setprio 0
	s_waitcnt lgkmcnt(0)
	v_mfma_f32_16x16x32_bf16 v[126:129], v[140:143], v[156:159], v[126:129]
	v_mfma_f32_16x16x32_bf16 v[122:125], v[148:151], v[156:159], v[122:125]
	v_mfma_f32_16x16x32_bf16 v[110:113], v[140:143], v[164:167], v[110:113]
	v_mfma_f32_16x16x32_bf16 v[106:109], v[148:151], v[164:167], v[106:109]
	v_mfma_f32_16x16x32_bf16 v[94:97], v[140:143], v[172:175], v[94:97]
	v_mfma_f32_16x16x32_bf16 v[90:93], v[148:151], v[172:175], v[90:93]
	v_mfma_f32_16x16x32_bf16 v[78:81], v[140:143], v[180:183], v[78:81]
	v_mfma_f32_16x16x32_bf16 v[74:77], v[148:151], v[180:183], v[74:77]
	v_mfma_f32_16x16x32_bf16 v[126:129], v[144:147], v[160:163], v[126:129]
	v_mfma_f32_16x16x32_bf16 v[122:125], v[152:155], v[160:163], v[122:125]
	v_mfma_f32_16x16x32_bf16 v[110:113], v[144:147], v[168:171], v[110:113]
	v_mfma_f32_16x16x32_bf16 v[106:109], v[152:155], v[168:171], v[106:109]
	v_mfma_f32_16x16x32_bf16 v[94:97], v[144:147], v[176:179], v[94:97]
	v_mfma_f32_16x16x32_bf16 v[90:93], v[152:155], v[176:179], v[90:93]
	v_mfma_f32_16x16x32_bf16 v[78:81], v[144:147], v[184:187], v[78:81]
	v_mfma_f32_16x16x32_bf16 v[74:77], v[152:155], v[184:187], v[74:77]
	s_setprio 1
	s_barrier
	s_add_i32 s26, 0, 0x14000
	s_add_i32 s24, s24, s14
	v_add_u32_e32 v208, s26, v138
	v_lshl_add_u64 v[224:225], s[8:9], 0, v[64:65]
	s_mov_b32 m0, s24
	ds_read_b128 v[188:191], v208
	ds_read_b128 v[192:195], v208 offset:1024
	ds_read_b128 v[196:199], v208 offset:2048
	ds_read_b128 v[220:223], v208 offset:3072
	global_load_lds_dwordx4 v[224:225], off
	v_lshl_add_u64 v[226:227], s[8:9], 0, v[130:131]
	s_add_i32 m0, s24, 0x2000
	s_nop 0
	global_load_lds_dwordx4 v[226:227], off
	s_barrier
	s_waitcnt lgkmcnt(0)
	s_setprio 0
	s_waitcnt lgkmcnt(0)
	v_mfma_f32_16x16x32_bf16 v[118:121], v[188:191], v[156:159], v[118:121]
	v_mfma_f32_16x16x32_bf16 v[114:117], v[196:199], v[156:159], v[114:117]
	v_mfma_f32_16x16x32_bf16 v[102:105], v[188:191], v[164:167], v[102:105]
	v_mfma_f32_16x16x32_bf16 v[98:101], v[196:199], v[164:167], v[98:101]
	v_mfma_f32_16x16x32_bf16 v[86:89], v[188:191], v[172:175], v[86:89]
	v_mfma_f32_16x16x32_bf16 v[82:85], v[196:199], v[172:175], v[82:85]
	v_mfma_f32_16x16x32_bf16 v[70:73], v[188:191], v[180:183], v[70:73]
	v_mfma_f32_16x16x32_bf16 v[66:69], v[196:199], v[180:183], v[66:69]
	v_mfma_f32_16x16x32_bf16 v[118:121], v[192:195], v[160:163], v[118:121]
	v_mfma_f32_16x16x32_bf16 v[114:117], v[220:223], v[160:163], v[114:117]
	v_mfma_f32_16x16x32_bf16 v[102:105], v[192:195], v[168:171], v[102:105]
	v_mfma_f32_16x16x32_bf16 v[98:101], v[220:223], v[168:171], v[98:101]
	v_mfma_f32_16x16x32_bf16 v[86:89], v[192:195], v[176:179], v[86:89]
	v_mfma_f32_16x16x32_bf16 v[82:85], v[220:223], v[176:179], v[82:85]
	v_mfma_f32_16x16x32_bf16 v[70:73], v[192:195], v[184:187], v[70:73]
	v_mfma_f32_16x16x32_bf16 v[66:69], v[220:223], v[184:187], v[66:69]
	s_setprio 1
	s_mov_b32 m0, s15
	v_lshl_add_u64 v[228:229], s[2:3], 0, v[64:65]
	s_barrier
	ds_read_b128 v[156:159], v139 offset:16384
	ds_read_b128 v[160:163], v139 offset:17408
	ds_read_b128 v[164:167], v139 offset:18432
	ds_read_b128 v[168:171], v139 offset:19456
	ds_read_b128 v[172:175], v139 offset:20480
	ds_read_b128 v[176:179], v139 offset:21504
	ds_read_b128 v[180:183], v139 offset:22528
	ds_read_b128 v[184:187], v139 offset:23552
	global_load_lds_dwordx4 v[228:229], off
	v_lshl_add_u64 v[230:231], s[2:3], 0, v[130:131]
	s_mov_b32 m0, s18
	s_nop 0
	global_load_lds_dwordx4 v[230:231], off
	s_barrier
	s_waitcnt lgkmcnt(0)
	s_setprio 0
	s_waitcnt lgkmcnt(0)
	v_mfma_f32_16x16x32_bf16 v[60:63], v[140:143], v[156:159], v[60:63]
	v_mfma_f32_16x16x32_bf16 v[56:59], v[148:151], v[156:159], v[56:59]
	v_mfma_f32_16x16x32_bf16 v[44:47], v[140:143], v[164:167], v[44:47]
	v_mfma_f32_16x16x32_bf16 v[40:43], v[148:151], v[164:167], v[40:43]
	v_mfma_f32_16x16x32_bf16 v[28:31], v[140:143], v[172:175], v[28:31]
	v_mfma_f32_16x16x32_bf16 v[24:27], v[148:151], v[172:175], v[24:27]
	v_mfma_f32_16x16x32_bf16 v[12:15], v[140:143], v[180:183], v[12:15]
	v_mfma_f32_16x16x32_bf16 v[8:11], v[148:151], v[180:183], v[8:11]
	v_mfma_f32_16x16x32_bf16 v[60:63], v[144:147], v[160:163], v[60:63]
	v_mfma_f32_16x16x32_bf16 v[56:59], v[152:155], v[160:163], v[56:59]
	v_mfma_f32_16x16x32_bf16 v[44:47], v[144:147], v[168:171], v[44:47]
	v_mfma_f32_16x16x32_bf16 v[40:43], v[152:155], v[168:171], v[40:43]
	v_mfma_f32_16x16x32_bf16 v[28:31], v[144:147], v[176:179], v[28:31]
	v_mfma_f32_16x16x32_bf16 v[24:27], v[152:155], v[176:179], v[24:27]
	v_mfma_f32_16x16x32_bf16 v[12:15], v[144:147], v[184:187], v[12:15]
	v_mfma_f32_16x16x32_bf16 v[8:11], v[152:155], v[184:187], v[8:11]
	s_setprio 1
	s_barrier
; #define PG8_STAGE(bufoff, gbase, voff) do { _Pragma("unroll") for (int _i = 0; _i < 2; ++_i) \
;         __builtin_amdgcn_global_load_lds((const unsigned*)((const char*)(gbase) + (voff)[_i]), (LAS unsigned*)(lds + (bufoff) + ldsw + _i * 8192), 16, 0, 0); } while (0)
; #define PG8_LDA(dst, b, h) do { _Pragma("unroll") for (int m = 0; m < 4; ++m) _Pragma("unroll") for (int k = 0; k < 2; ++k) dst[m][k] = *(const LAS bf16x8*)(lds + PG8_SA(b, h) + aoff + m * 2048 + k * 1024); } while (0)
; #define PG8_LDB(dst, b, h) do { _Pragma("unroll") for (int n = 0; n < 2; ++n) _Pragma("unroll") for (int k = 0; k < 2; ++k) dst[n][k] = *(const LAS bf16x8*)(lds + PG8_SB(b, h) + boff + n * 2048 + k * 1024); } while (0)
; #define PG8_MMA(ai, bj, At, Bt) do { __builtin_amdgcn_s_setprio(1); _Pragma("unroll") for (int m = 0; m < 4; ++m) _Pragma("unroll") for (int n = 0; n < 2; ++n) _Pragma("unroll") for (int k = 0; k < 2; ++k) \
;         acc[ai][bj][m][n] = __builtin_amdgcn_mfma_f32_16x16x32_bf16(Bt[n][k], At[m][k], acc[ai][bj][m][n], 0, 0, 0); __builtin_amdgcn_s_setprio(0); } while (0)
; #define PG8_WAIT_V(n) asm volatile("s_waitcnt vmcnt(" #n ")" ::: "memory")
; #define PG8_WAIT_L(n) asm volatile("s_waitcnt lgkmcnt(" #n ")" ::: "memory")
; #define PG8_BAR __builtin_amdgcn_s_barrier()
; #define PG8_SCHED __builtin_amdgcn_sched_barrier(0)
;     ...
;             PG8_STAGE(PG8_SB(0, 1), b2 + hstep, voffB);
;             PG8_WAIT_V(6); PG8_BAR; PG8_MMA(1, 1, At, B1); PG8_BAR;
;             PG8_LDB(B0, 1, 0); PG8_SCHED; PG8_LDA(At, 1, 0); PG8_STAGE(PG8_SA(0, 1), a2 + hstep, voffA);
;             PG8_WAIT_L(8); PG8_BAR; PG8_WAIT_L(0); PG8_MMA(0, 0, At, B0); PG8_BAR; PG8_SCHED;
;             PG8_LDB(B1, 1, 1); PG8_STAGE(PG8_SB(1, 0), b3, voffB);
;             PG8_BAR; PG8_WAIT_L(0); PG8_MMA(0, 1, At, B1); PG8_BAR;
;             PG8_LDA(At, 1, 1); PG8_STAGE(PG8_SA(1, 0), a3, voffA);
;             PG8_BAR; PG8_WAIT_L(0); PG8_MMA(1, 0, At, B0); PG8_BAR; PG8_SCHED;
;             PG8_STAGE(PG8_SB(1, 1), b3 + hstep, voffB);
	s_add_u32 s24, s8, 0x84000
	s_addc_u32 s25, s9, 0
	s_add_i32 s26, s26, s14
	v_lshl_add_u64 v[140:141], s[24:25], 0, v[64:65]
	s_mov_b32 m0, s26
	s_nop 0
	global_load_lds_dwordx4 v[140:141], off
	v_lshl_add_u64 v[140:141], s[24:25], 0, v[130:131]
	s_add_i32 m0, s26, 0x2000
	s_nop 0
	global_load_lds_dwordx4 v[140:141], off
	s_waitcnt vmcnt(6)
	s_barrier
	s_setprio 0
	v_mfma_f32_16x16x32_bf16 v[52:55], v[188:191], v[156:159], v[52:55]
	v_mfma_f32_16x16x32_bf16 v[48:51], v[196:199], v[156:159], v[48:51]
	v_mfma_f32_16x16x32_bf16 v[36:39], v[188:191], v[164:167], v[36:39]
	v_mfma_f32_16x16x32_bf16 v[32:35], v[196:199], v[164:167], v[32:35]
	v_mfma_f32_16x16x32_bf16 v[20:23], v[188:191], v[172:175], v[20:23]
	v_mfma_f32_16x16x32_bf16 v[16:19], v[196:199], v[172:175], v[16:19]
	v_mfma_f32_16x16x32_bf16 v[4:7], v[188:191], v[180:183], v[4:7]
	v_mfma_f32_16x16x32_bf16 v[0:3], v[196:199], v[180:183], v[0:3]
	v_mfma_f32_16x16x32_bf16 v[52:55], v[192:195], v[160:163], v[52:55]
	v_mfma_f32_16x16x32_bf16 v[48:51], v[220:223], v[160:163], v[48:51]
	v_mfma_f32_16x16x32_bf16 v[36:39], v[192:195], v[168:171], v[36:39]
	v_mfma_f32_16x16x32_bf16 v[32:35], v[220:223], v[168:171], v[32:35]
	v_mfma_f32_16x16x32_bf16 v[20:23], v[192:195], v[176:179], v[20:23]
	v_mfma_f32_16x16x32_bf16 v[16:19], v[220:223], v[176:179], v[16:19]
	v_mfma_f32_16x16x32_bf16 v[4:7], v[192:195], v[184:187], v[4:7]
	v_mfma_f32_16x16x32_bf16 v[0:3], v[220:223], v[184:187], v[0:3]
	s_setprio 1
	s_add_i32 s24, 0, 0x18000
	v_add_u32_e32 v152, s24, v138
	s_barrier
	ds_read_b128 v[140:143], v152
	ds_read_b128 v[144:147], v152 offset:1024
	ds_read_b128 v[148:151], v152 offset:2048
	ds_read_b128 v[152:155], v152 offset:3072
	s_add_u32 s2, s2, 0x84000
	s_addc_u32 s3, s3, 0
	s_mov_b32 m0, s19
	v_lshl_add_u64 v[188:189], s[2:3], 0, v[64:65]
	ds_read_b128 v[156:159], v139 offset:32768
	ds_read_b128 v[160:163], v139 offset:33792
	ds_read_b128 v[164:167], v139 offset:34816
	ds_read_b128 v[168:171], v139 offset:35840
	ds_read_b128 v[172:175], v139 offset:36864
	ds_read_b128 v[176:179], v139 offset:37888
	ds_read_b128 v[180:183], v139 offset:38912
	ds_read_b128 v[184:187], v139 offset:39936
	global_load_lds_dwordx4 v[188:189], off
	v_lshl_add_u64 v[188:189], s[2:3], 0, v[130:131]
	s_mov_b32 m0, s20
	s_nop 0
	global_load_lds_dwordx4 v[188:189], off
	s_waitcnt lgkmcnt(8)
	s_barrier
	s_waitcnt lgkmcnt(0)
	s_setprio 0
	s_waitcnt lgkmcnt(0)
	v_mfma_f32_16x16x32_bf16 v[126:129], v[140:143], v[156:159], v[126:129]
	v_mfma_f32_16x16x32_bf16 v[122:125], v[148:151], v[156:159], v[122:125]
	v_mfma_f32_16x16x32_bf16 v[110:113], v[140:143], v[164:167], v[110:113]
	v_mfma_f32_16x16x32_bf16 v[106:109], v[148:151], v[164:167], v[106:109]
	v_mfma_f32_16x16x32_bf16 v[94:97], v[140:143], v[172:175], v[94:97]
	v_mfma_f32_16x16x32_bf16 v[90:93], v[148:151], v[172:175], v[90:93]
	v_mfma_f32_16x16x32_bf16 v[78:81], v[140:143], v[180:183], v[78:81]
	v_mfma_f32_16x16x32_bf16 v[74:77], v[148:151], v[180:183], v[74:77]
	v_mfma_f32_16x16x32_bf16 v[126:129], v[144:147], v[160:163], v[126:129]
	v_mfma_f32_16x16x32_bf16 v[122:125], v[152:155], v[160:163], v[122:125]
	v_mfma_f32_16x16x32_bf16 v[110:113], v[144:147], v[168:171], v[110:113]
	v_mfma_f32_16x16x32_bf16 v[106:109], v[152:155], v[168:171], v[106:109]
	v_mfma_f32_16x16x32_bf16 v[94:97], v[144:147], v[176:179], v[94:97]
	v_mfma_f32_16x16x32_bf16 v[90:93], v[152:155], v[176:179], v[90:93]
	v_mfma_f32_16x16x32_bf16 v[78:81], v[144:147], v[184:187], v[78:81]
	v_mfma_f32_16x16x32_bf16 v[74:77], v[152:155], v[184:187], v[74:77]
	s_setprio 1
	s_barrier
	s_add_i32 s25, 0, 0x1c000
	s_add_i32 s2, s24, s14
	v_add_u32_e32 v208, s25, v138
	v_lshl_add_u64 v[224:225], v[224:225], 0, s[16:17]
	s_mov_b32 m0, s2
	ds_read_b128 v[188:191], v208
	ds_read_b128 v[192:195], v208 offset:1024
	ds_read_b128 v[196:199], v208 offset:2048
	ds_read_b128 v[220:223], v208 offset:3072
	global_load_lds_dwordx4 v[224:225], off
	v_lshl_add_u64 v[224:225], v[226:227], 0, s[16:17]
	s_add_i32 m0, s2, 0x2000
	s_nop 0
	global_load_lds_dwordx4 v[224:225], off
	s_barrier
	s_waitcnt lgkmcnt(0)
	s_setprio 0
	s_waitcnt lgkmcnt(0)
	v_mfma_f32_16x16x32_bf16 v[118:121], v[188:191], v[156:159], v[118:121]
	v_mfma_f32_16x16x32_bf16 v[114:117], v[196:199], v[156:159], v[114:117]
	v_mfma_f32_16x16x32_bf16 v[102:105], v[188:191], v[164:167], v[102:105]
	v_mfma_f32_16x16x32_bf16 v[98:101], v[196:199], v[164:167], v[98:101]
	v_mfma_f32_16x16x32_bf16 v[86:89], v[188:191], v[172:175], v[86:89]
	v_mfma_f32_16x16x32_bf16 v[82:85], v[196:199], v[172:175], v[82:85]
	v_mfma_f32_16x16x32_bf16 v[70:73], v[188:191], v[180:183], v[70:73]
	v_mfma_f32_16x16x32_bf16 v[66:69], v[196:199], v[180:183], v[66:69]
	v_mfma_f32_16x16x32_bf16 v[118:121], v[192:195], v[160:163], v[118:121]
	v_mfma_f32_16x16x32_bf16 v[114:117], v[220:223], v[160:163], v[114:117]
	v_mfma_f32_16x16x32_bf16 v[102:105], v[192:195], v[168:171], v[102:105]
	v_mfma_f32_16x16x32_bf16 v[98:101], v[220:223], v[168:171], v[98:101]
	v_mfma_f32_16x16x32_bf16 v[86:89], v[192:195], v[176:179], v[86:89]
	v_mfma_f32_16x16x32_bf16 v[82:85], v[220:223], v[176:179], v[82:85]
	v_mfma_f32_16x16x32_bf16 v[70:73], v[192:195], v[184:187], v[70:73]
	v_mfma_f32_16x16x32_bf16 v[66:69], v[220:223], v[184:187], v[66:69]
	s_setprio 1
	s_mov_b32 m0, s21
	v_lshl_add_u64 v[224:225], v[228:229], 0, s[16:17]
	s_barrier
; #define PG8_STAGE(bufoff, gbase, voff) do { _Pragma("unroll") for (int _i = 0; _i < 2; ++_i) \
;         __builtin_amdgcn_global_load_lds((const unsigned*)((const char*)(gbase) + (voff)[_i]), (LAS unsigned*)(lds + (bufoff) + ldsw + _i * 8192), 16, 0, 0); } while (0)
; #define PG8_LDA(dst, b, h) do { _Pragma("unroll") for (int m = 0; m < 4; ++m) _Pragma("unroll") for (int k = 0; k < 2; ++k) dst[m][k] = *(const LAS bf16x8*)(lds + PG8_SA(b, h) + aoff + m * 2048 + k * 1024); } while (0)
; #define PG8_MMA(ai, bj, At, Bt) do { __builtin_amdgcn_s_setprio(1); _Pragma("unroll") for (int m = 0; m < 4; ++m) _Pragma("unroll") for (int n = 0; n < 2; ++n) _Pragma("unroll") for (int k = 0; k < 2; ++k) \
;         acc[ai][bj][m][n] = __builtin_amdgcn_mfma_f32_16x16x32_bf16(Bt[n][k], At[m][k], acc[ai][bj][m][n], 0, 0, 0); __builtin_amdgcn_s_setprio(0); } while (0)
; #define PG8_WAIT_V(n) asm volatile("s_waitcnt vmcnt(" #n ")" ::: "memory")
; #define PG8_WAIT_L(n) asm volatile("s_waitcnt lgkmcnt(" #n ")" ::: "memory")
; #define PG8_BAR __builtin_amdgcn_s_barrier()
; #define PG8_SCHED __builtin_amdgcn_sched_barrier(0)
; __device__ __forceinline__ f32x4 gelu4(const f32x4 x) {
;     const f32x4 t = x * x, a = x * (t * -0.10294324f + -2.3022082f);
;     f32x4 e; e[0] = __builtin_amdgcn_exp2f(a[0]); e[1] = __builtin_amdgcn_exp2f(a[1]); e[2] = __builtin_amdgcn_exp2f(a[2]); e[3] = __builtin_amdgcn_exp2f(a[3]);
;     const f32x4 d = e + 1.0f;
;     f32x4 r; r[0] = __builtin_amdgcn_rcpf(d[0]); r[1] = __builtin_amdgcn_rcpf(d[1]); r[2] = __builtin_amdgcn_rcpf(d[2]); r[3] = __builtin_amdgcn_rcpf(d[3]);
;     return x * r;
; }
;     ...
;             PG8_LDA(At, 1, 1); PG8_STAGE(PG8_SA(1, 0), a3, voffA);
;             PG8_BAR; PG8_WAIT_L(0); PG8_MMA(1, 0, At, B0); PG8_BAR; PG8_SCHED;
;             PG8_STAGE(PG8_SB(1, 1), b3 + hstep, voffB);
;             PG8_WAIT_V(6); PG8_BAR; PG8_MMA(1, 1, At, B1); PG8_BAR;
	ds_read_b128 v[156:159], v139 offset:49152
	ds_read_b128 v[160:163], v139 offset:50176
	ds_read_b128 v[164:167], v139 offset:51200
	ds_read_b128 v[168:171], v139 offset:52224
	ds_read_b128 v[172:175], v139 offset:53248
	ds_read_b128 v[176:179], v139 offset:54272
	ds_read_b128 v[180:183], v139 offset:55296
	ds_read_b128 v[184:187], v139 offset:56320
	global_load_lds_dwordx4 v[224:225], off
	v_lshl_add_u64 v[224:225], v[230:231], 0, s[16:17]
	s_mov_b32 m0, s22
	s_nop 0
	global_load_lds_dwordx4 v[224:225], off
	s_barrier
	s_waitcnt lgkmcnt(0)
	s_setprio 0
	s_waitcnt lgkmcnt(0)
	v_mfma_f32_16x16x32_bf16 v[60:63], v[140:143], v[156:159], v[60:63]
	v_mfma_f32_16x16x32_bf16 v[56:59], v[148:151], v[156:159], v[56:59]
	v_mfma_f32_16x16x32_bf16 v[44:47], v[140:143], v[164:167], v[44:47]
	v_mfma_f32_16x16x32_bf16 v[40:43], v[148:151], v[164:167], v[40:43]
	v_mfma_f32_16x16x32_bf16 v[28:31], v[140:143], v[172:175], v[28:31]
	v_mfma_f32_16x16x32_bf16 v[24:27], v[148:151], v[172:175], v[24:27]
	v_mfma_f32_16x16x32_bf16 v[12:15], v[140:143], v[180:183], v[12:15]
	v_mfma_f32_16x16x32_bf16 v[8:11], v[148:151], v[180:183], v[8:11]
	v_mfma_f32_16x16x32_bf16 v[60:63], v[144:147], v[160:163], v[60:63]
	v_mfma_f32_16x16x32_bf16 v[56:59], v[152:155], v[160:163], v[56:59]
	v_mfma_f32_16x16x32_bf16 v[44:47], v[144:147], v[168:171], v[44:47]
	v_mfma_f32_16x16x32_bf16 v[40:43], v[152:155], v[168:171], v[40:43]
	v_mfma_f32_16x16x32_bf16 v[28:31], v[144:147], v[176:179], v[28:31]
	v_mfma_f32_16x16x32_bf16 v[24:27], v[152:155], v[176:179], v[24:27]
	v_mfma_f32_16x16x32_bf16 v[12:15], v[144:147], v[184:187], v[12:15]
	v_mfma_f32_16x16x32_bf16 v[8:11], v[152:155], v[184:187], v[8:11]
	s_setprio 1
	s_barrier
	s_add_u32 s2, s8, 0x84080
	s_addc_u32 s3, s9, 0
	s_add_i32 s8, s25, s14
	v_lshl_add_u64 v[140:141], s[2:3], 0, v[64:65]
	s_mov_b32 m0, s8
	s_nop 0
	global_load_lds_dwordx4 v[140:141], off
	v_lshl_add_u64 v[140:141], s[2:3], 0, v[130:131]
	s_add_i32 m0, s8, 0x2000
	s_nop 0
	global_load_lds_dwordx4 v[140:141], off
	s_waitcnt vmcnt(6)
	s_barrier
	s_setprio 0
	v_mfma_f32_16x16x32_bf16 v[52:55], v[188:191], v[156:159], v[52:55]
	v_mfma_f32_16x16x32_bf16 v[48:51], v[196:199], v[156:159], v[48:51]
	v_mfma_f32_16x16x32_bf16 v[36:39], v[188:191], v[164:167], v[36:39]
	v_mfma_f32_16x16x32_bf16 v[32:35], v[196:199], v[164:167], v[32:35]
	v_mfma_f32_16x16x32_bf16 v[20:23], v[188:191], v[172:175], v[20:23]
	v_mfma_f32_16x16x32_bf16 v[16:19], v[196:199], v[172:175], v[16:19]
	v_mfma_f32_16x16x32_bf16 v[4:7], v[188:191], v[180:183], v[4:7]
	v_mfma_f32_16x16x32_bf16 v[0:3], v[196:199], v[180:183], v[0:3]
	v_mfma_f32_16x16x32_bf16 v[52:55], v[192:195], v[160:163], v[52:55]
	v_mfma_f32_16x16x32_bf16 v[48:51], v[220:223], v[160:163], v[48:51]
	v_mfma_f32_16x16x32_bf16 v[36:39], v[192:195], v[168:171], v[36:39]
	v_mfma_f32_16x16x32_bf16 v[32:35], v[220:223], v[168:171], v[32:35]
	v_mfma_f32_16x16x32_bf16 v[20:23], v[192:195], v[176:179], v[20:23]
	v_mfma_f32_16x16x32_bf16 v[16:19], v[220:223], v[176:179], v[16:19]
	v_mfma_f32_16x16x32_bf16 v[4:7], v[192:195], v[184:187], v[4:7]
	v_mfma_f32_16x16x32_bf16 v[0:3], v[220:223], v[184:187], v[0:3]
	s_setprio 1
	s_add_i32 s23, s23, 2
	s_add_u32 s6, s6, 0x100
	s_addc_u32 s7, s7, 0
	s_cmp_gt_u32 s23, 29
	s_barrier
	s_cbranch_scc0 .LBB0_1275
	s_add_i32 s0, s11, -2
	s_cmp_lt_u32 s0, 8
	s_cselect_b64 s[2:3], -1, 0
	s_cmp_gt_u32 s0, 7
	s_cbranch_scc1 .LBB0_1278
	s_mov_b32 s0, 0xc0135761
	v_pk_mul_f32 v[130:131], v[128:129], v[128:129]
	v_pk_mul_f32 v[132:133], v[126:127], v[126:127]
	v_mov_b64_e32 v[134:135], s[0:1]
	s_mov_b32 s0, 0xbdd2d3e8
	v_pk_fma_f32 v[130:131], v[130:131], s[0:1], v[134:135] op_sel_hi:[1,0,0]
	v_pk_fma_f32 v[132:133], v[132:133], s[0:1], v[134:135] op_sel_hi:[1,0,0]
	v_pk_mul_f32 v[130:131], v[128:129], v[130:131]
	v_pk_mul_f32 v[132:133], v[126:127], v[132:133]
	v_exp_f32_e32 v130, v130
	v_exp_f32_e32 v132, v132
	v_exp_f32_e32 v131, v131
	v_exp_f32_e32 v133, v133
	v_pk_add_f32 v[130:131], v[130:131], 1.0 op_sel_hi:[1,0]
	v_pk_add_f32 v[132:133], v[132:133], 1.0 op_sel_hi:[1,0]
	v_rcp_f32_e32 v130, v130
	v_rcp_f32_e32 v132, v132
	v_rcp_f32_e32 v131, v131
	v_rcp_f32_e32 v133, v133
	v_pk_mul_f32 v[128:129], v[128:129], v[130:131]
	v_pk_mul_f32 v[126:127], v[126:127], v[132:133]

; #define PG8_STAGE(bufoff, gbase, voff) do { _Pragma("unroll") for (int _i = 0; _i < 2; ++_i) \
;         __builtin_amdgcn_global_load_lds((const unsigned*)((const char*)(gbase) + (voff)[_i]), (LAS unsigned*)(lds + (bufoff) + ldsw + _i * 8192), 16, 0, 0); } while (0)
; #define PG8_LDA(dst, b, h) do { _Pragma("unroll") for (int m = 0; m < 4; ++m) _Pragma("unroll") for (int k = 0; k < 2; ++k) dst[m][k] = *(const LAS bf16x8*)(lds + PG8_SA(b, h) + aoff + m * 2048 + k * 1024); } while (0)
; #define PG8_LDB(dst, b, h) do { _Pragma("unroll") for (int n = 0; n < 2; ++n) _Pragma("unroll") for (int k = 0; k < 2; ++k) dst[n][k] = *(const LAS bf16x8*)(lds + PG8_SB(b, h) + boff + n * 2048 + k * 1024); } while (0)
; #define PG8_MMA(ai, bj, At, Bt) do { __builtin_amdgcn_s_setprio(1); _Pragma("unroll") for (int m = 0; m < 4; ++m) _Pragma("unroll") for (int n = 0; n < 2; ++n) _Pragma("unroll") for (int k = 0; k < 2; ++k) \
;         acc[ai][bj][m][n] = __builtin_amdgcn_mfma_f32_16x16x32_bf16(Bt[n][k], At[m][k], acc[ai][bj][m][n], 0, 0, 0); __builtin_amdgcn_s_setprio(0); } while (0)
; #define PG8_WAIT_V(n) asm volatile("s_waitcnt vmcnt(" #n ")" ::: "memory")
; #define PG8_WAIT_L(n) asm volatile("s_waitcnt lgkmcnt(" #n ")" ::: "memory")
; #define PG8_BAR __builtin_amdgcn_s_barrier()
; #define PG8_SCHED __builtin_amdgcn_sched_barrier(0)
;     ...
;             const char* a1 = cA + (size_t)(t + 1) * kstep;
;             const char* a2 = last ? nA : cA + (size_t)(t + 2) * kstep; const char* b2 = last ? nB : cB + (size_t)(t + 2) * kstep;
;             const char* a3 = a2 + kstep; const char* b3 = b2 + kstep;
;             PG8_LDB(B0, 0, 0); PG8_SCHED; PG8_LDA(At, 0, 0); PG8_STAGE(PG8_SA(1, 1), a1 + hstep, voffA);
;             PG8_WAIT_L(8); PG8_BAR; PG8_WAIT_L(0); PG8_MMA(0, 0, At, B0); PG8_BAR; PG8_SCHED;
;             PG8_LDB(B1, 0, 1); PG8_STAGE(PG8_SB(0, 0), b2, voffB);
;             PG8_BAR; PG8_WAIT_L(0); PG8_MMA(0, 1, At, B1); PG8_BAR;
;             PG8_LDA(At, 0, 1); PG8_STAGE(PG8_SA(0, 0), a2, voffA);
;             PG8_BAR; PG8_WAIT_L(0); PG8_MMA(1, 0, At, B0); PG8_BAR; PG8_SCHED;
;             PG8_STAGE(PG8_SB(0, 1), b2 + hstep, voffB);
;             PG8_WAIT_V(6); PG8_BAR; PG8_MMA(1, 1, At, B1); PG8_BAR;
.LBB0_1441:
	s_add_u32 s4, s0, 0x100
	s_addc_u32 s5, s1, 0
	s_add_i32 s43, 0, 0x10000
	v_add_u32_e32 v140, s43, v143
	ds_read_b128 v[136:139], v140
	ds_read_b128 v[146:149], v140 offset:1024
	ds_read_b128 v[150:153], v140 offset:2048
	ds_read_b128 v[154:157], v140 offset:3072
	s_cmp_eq_u32 s42, 28
	s_cselect_b32 s3, s21, s5
	s_cselect_b32 s2, s20, s4
	s_cselect_b32 s9, s23, s41
	s_cselect_b32 s8, s22, s40
	v_lshl_add_u64 v[140:141], s[0:1], 0, v[132:133]
	s_add_i32 m0, s12, 0xc000
	ds_read_b128 v[158:161], v145
	ds_read_b128 v[162:165], v145 offset:1024
	ds_read_b128 v[166:169], v145 offset:2048
	ds_read_b128 v[170:173], v145 offset:3072
	ds_read_b128 v[174:177], v145 offset:4096
	ds_read_b128 v[178:181], v145 offset:5120
	ds_read_b128 v[182:185], v145 offset:6144
	ds_read_b128 v[186:189], v145 offset:7168
	global_load_lds_dwordx4 v[140:141], off
	v_lshl_add_u64 v[140:141], s[0:1], 0, v[134:135]
	s_add_i32 m0, s12, 0xe000
	s_nop 0
	global_load_lds_dwordx4 v[140:141], off
	s_waitcnt lgkmcnt(8)
	s_barrier
	s_waitcnt lgkmcnt(0)
	s_setprio 0
	s_waitcnt lgkmcnt(0)
	v_mfma_f32_16x16x32_bf16 v[126:129], v[136:139], v[158:161], v[126:129]
	v_mfma_f32_16x16x32_bf16 v[122:125], v[150:153], v[158:161], v[122:125]
	v_mfma_f32_16x16x32_bf16 v[110:113], v[136:139], v[166:169], v[110:113]
	v_mfma_f32_16x16x32_bf16 v[106:109], v[150:153], v[166:169], v[106:109]
	v_mfma_f32_16x16x32_bf16 v[94:97], v[136:139], v[174:177], v[94:97]
	v_mfma_f32_16x16x32_bf16 v[90:93], v[150:153], v[174:177], v[90:93]
	v_mfma_f32_16x16x32_bf16 v[78:81], v[136:139], v[182:185], v[78:81]
	v_mfma_f32_16x16x32_bf16 v[74:77], v[150:153], v[182:185], v[74:77]
	v_mfma_f32_16x16x32_bf16 v[126:129], v[146:149], v[162:165], v[126:129]
	v_mfma_f32_16x16x32_bf16 v[122:125], v[154:157], v[162:165], v[122:125]
	v_mfma_f32_16x16x32_bf16 v[110:113], v[146:149], v[170:173], v[110:113]
	v_mfma_f32_16x16x32_bf16 v[106:109], v[154:157], v[170:173], v[106:109]
	v_mfma_f32_16x16x32_bf16 v[94:97], v[146:149], v[178:181], v[94:97]
	v_mfma_f32_16x16x32_bf16 v[90:93], v[154:157], v[178:181], v[90:93]
	v_mfma_f32_16x16x32_bf16 v[78:81], v[146:149], v[186:189], v[78:81]
	v_mfma_f32_16x16x32_bf16 v[74:77], v[154:157], v[186:189], v[74:77]
	s_setprio 1
	s_barrier
	s_add_i32 s44, 0, 0x14000
	v_add_u32_e32 v140, s44, v143
	s_add_i32 s0, s43, s11
	ds_read_b128 v[190:193], v140
	ds_read_b128 v[194:197], v140 offset:1024
	ds_read_b128 v[220:223], v140 offset:2048
	ds_read_b128 v[224:227], v140 offset:3072
	v_lshl_add_u64 v[140:141], s[8:9], 0, v[64:65]
	s_mov_b32 m0, s0
	v_lshl_add_u64 v[198:199], s[8:9], 0, v[130:131]
	global_load_lds_dwordx4 v[140:141], off
	s_add_i32 m0, s0, 0x2000
	s_nop 0
	global_load_lds_dwordx4 v[198:199], off
	s_barrier
	s_waitcnt lgkmcnt(0)
	s_setprio 0
	s_waitcnt lgkmcnt(0)
	v_mfma_f32_16x16x32_bf16 v[118:121], v[190:193], v[158:161], v[118:121]
	v_mfma_f32_16x16x32_bf16 v[114:117], v[220:223], v[158:161], v[114:117]
	v_mfma_f32_16x16x32_bf16 v[102:105], v[190:193], v[166:169], v[102:105]
	v_mfma_f32_16x16x32_bf16 v[98:101], v[220:223], v[166:169], v[98:101]
	v_mfma_f32_16x16x32_bf16 v[86:89], v[190:193], v[174:177], v[86:89]
	v_mfma_f32_16x16x32_bf16 v[82:85], v[220:223], v[174:177], v[82:85]
	v_mfma_f32_16x16x32_bf16 v[70:73], v[190:193], v[182:185], v[70:73]
	v_mfma_f32_16x16x32_bf16 v[66:69], v[220:223], v[182:185], v[66:69]
	v_mfma_f32_16x16x32_bf16 v[118:121], v[194:197], v[162:165], v[118:121]
	v_mfma_f32_16x16x32_bf16 v[114:117], v[224:227], v[162:165], v[114:117]
	v_mfma_f32_16x16x32_bf16 v[102:105], v[194:197], v[170:173], v[102:105]
	v_mfma_f32_16x16x32_bf16 v[98:101], v[224:227], v[170:173], v[98:101]
	v_mfma_f32_16x16x32_bf16 v[86:89], v[194:197], v[178:181], v[86:89]
	v_mfma_f32_16x16x32_bf16 v[82:85], v[224:227], v[178:181], v[82:85]
	v_mfma_f32_16x16x32_bf16 v[70:73], v[194:197], v[186:189], v[70:73]
	v_mfma_f32_16x16x32_bf16 v[66:69], v[224:227], v[186:189], v[66:69]
	s_setprio 1
	s_mov_b32 m0, s12
	v_lshl_add_u64 v[228:229], s[2:3], 0, v[64:65]
	s_barrier
	ds_read_b128 v[158:161], v145 offset:16384
	ds_read_b128 v[162:165], v145 offset:17408
	ds_read_b128 v[166:169], v145 offset:18432
	ds_read_b128 v[170:173], v145 offset:19456
	ds_read_b128 v[174:177], v145 offset:20480
	ds_read_b128 v[178:181], v145 offset:21504
	ds_read_b128 v[182:185], v145 offset:22528
	ds_read_b128 v[186:189], v145 offset:23552
	global_load_lds_dwordx4 v[228:229], off
	v_lshl_add_u64 v[230:231], s[2:3], 0, v[130:131]
	s_mov_b32 m0, s13
	s_nop 0
	global_load_lds_dwordx4 v[230:231], off
	s_barrier
	s_waitcnt lgkmcnt(0)
	s_setprio 0
	s_waitcnt lgkmcnt(0)
	v_mfma_f32_16x16x32_bf16 v[60:63], v[136:139], v[158:161], v[60:63]
	v_mfma_f32_16x16x32_bf16 v[56:59], v[150:153], v[158:161], v[56:59]
	v_mfma_f32_16x16x32_bf16 v[44:47], v[136:139], v[166:169], v[44:47]
	v_mfma_f32_16x16x32_bf16 v[40:43], v[150:153], v[166:169], v[40:43]
	v_mfma_f32_16x16x32_bf16 v[28:31], v[136:139], v[174:177], v[28:31]
	v_mfma_f32_16x16x32_bf16 v[24:27], v[150:153], v[174:177], v[24:27]
	v_mfma_f32_16x16x32_bf16 v[12:15], v[136:139], v[182:185], v[12:15]
	v_mfma_f32_16x16x32_bf16 v[8:11], v[150:153], v[182:185], v[8:11]
	v_mfma_f32_16x16x32_bf16 v[60:63], v[146:149], v[162:165], v[60:63]
	v_mfma_f32_16x16x32_bf16 v[56:59], v[154:157], v[162:165], v[56:59]
	v_mfma_f32_16x16x32_bf16 v[44:47], v[146:149], v[170:173], v[44:47]
	v_mfma_f32_16x16x32_bf16 v[40:43], v[154:157], v[170:173], v[40:43]
	v_mfma_f32_16x16x32_bf16 v[28:31], v[146:149], v[178:181], v[28:31]
	v_mfma_f32_16x16x32_bf16 v[24:27], v[154:157], v[178:181], v[24:27]
	v_mfma_f32_16x16x32_bf16 v[12:15], v[146:149], v[186:189], v[12:15]
	v_mfma_f32_16x16x32_bf16 v[8:11], v[154:157], v[186:189], v[8:11]
	s_setprio 1
	s_barrier
; #define PG8_STAGE(bufoff, gbase, voff) do { _Pragma("unroll") for (int _i = 0; _i < 2; ++_i) \
;         __builtin_amdgcn_global_load_lds((const unsigned*)((const char*)(gbase) + (voff)[_i]), (LAS unsigned*)(lds + (bufoff) + ldsw + _i * 8192), 16, 0, 0); } while (0)
; #define PG8_LDA(dst, b, h) do { _Pragma("unroll") for (int m = 0; m < 4; ++m) _Pragma("unroll") for (int k = 0; k < 2; ++k) dst[m][k] = *(const LAS bf16x8*)(lds + PG8_SA(b, h) + aoff + m * 2048 + k * 1024); } while (0)
; #define PG8_LDB(dst, b, h) do { _Pragma("unroll") for (int n = 0; n < 2; ++n) _Pragma("unroll") for (int k = 0; k < 2; ++k) dst[n][k] = *(const LAS bf16x8*)(lds + PG8_SB(b, h) + boff + n * 2048 + k * 1024); } while (0)
; #define PG8_MMA(ai, bj, At, Bt) do { __builtin_amdgcn_s_setprio(1); _Pragma("unroll") for (int m = 0; m < 4; ++m) _Pragma("unroll") for (int n = 0; n < 2; ++n) _Pragma("unroll") for (int k = 0; k < 2; ++k) \
;         acc[ai][bj][m][n] = __builtin_amdgcn_mfma_f32_16x16x32_bf16(Bt[n][k], At[m][k], acc[ai][bj][m][n], 0, 0, 0); __builtin_amdgcn_s_setprio(0); } while (0)
; #define PG8_WAIT_V(n) asm volatile("s_waitcnt vmcnt(" #n ")" ::: "memory")
; #define PG8_WAIT_L(n) asm volatile("s_waitcnt lgkmcnt(" #n ")" ::: "memory")
; #define PG8_BAR __builtin_amdgcn_s_barrier()
; #define PG8_SCHED __builtin_amdgcn_sched_barrier(0)
;     ...
;             PG8_STAGE(PG8_SB(0, 1), b2 + hstep, voffB);
;             PG8_WAIT_V(6); PG8_BAR; PG8_MMA(1, 1, At, B1); PG8_BAR;
;             PG8_LDB(B0, 1, 0); PG8_SCHED; PG8_LDA(At, 1, 0); PG8_STAGE(PG8_SA(0, 1), a2 + hstep, voffA);
;             PG8_WAIT_L(8); PG8_BAR; PG8_WAIT_L(0); PG8_MMA(0, 0, At, B0); PG8_BAR; PG8_SCHED;
;             PG8_LDB(B1, 1, 1); PG8_STAGE(PG8_SB(1, 0), b3, voffB);
;             PG8_BAR; PG8_WAIT_L(0); PG8_MMA(0, 1, At, B1); PG8_BAR;
;             PG8_LDA(At, 1, 1); PG8_STAGE(PG8_SA(1, 0), a3, voffA);
;             PG8_BAR; PG8_WAIT_L(0); PG8_MMA(1, 0, At, B0); PG8_BAR; PG8_SCHED;
;             PG8_STAGE(PG8_SB(1, 1), b3 + hstep, voffB);
	s_add_u32 s0, s8, 0x84000
	s_addc_u32 s1, s9, 0
	s_add_i32 s43, s44, s11
	v_lshl_add_u64 v[136:137], s[0:1], 0, v[64:65]
	s_mov_b32 m0, s43
	s_nop 0
	global_load_lds_dwordx4 v[136:137], off
	v_lshl_add_u64 v[136:137], s[0:1], 0, v[130:131]
	s_add_i32 m0, s43, 0x2000
	s_nop 0
	global_load_lds_dwordx4 v[136:137], off
	s_waitcnt vmcnt(6)
	s_barrier
	s_setprio 0
	v_mfma_f32_16x16x32_bf16 v[52:55], v[190:193], v[158:161], v[52:55]
	v_mfma_f32_16x16x32_bf16 v[48:51], v[220:223], v[158:161], v[48:51]
	v_mfma_f32_16x16x32_bf16 v[36:39], v[190:193], v[166:169], v[36:39]
	v_mfma_f32_16x16x32_bf16 v[32:35], v[220:223], v[166:169], v[32:35]
	v_mfma_f32_16x16x32_bf16 v[20:23], v[190:193], v[174:177], v[20:23]
	v_mfma_f32_16x16x32_bf16 v[16:19], v[220:223], v[174:177], v[16:19]
	v_mfma_f32_16x16x32_bf16 v[4:7], v[190:193], v[182:185], v[4:7]
	v_mfma_f32_16x16x32_bf16 v[0:3], v[220:223], v[182:185], v[0:3]
	v_mfma_f32_16x16x32_bf16 v[52:55], v[194:197], v[162:165], v[52:55]
	v_mfma_f32_16x16x32_bf16 v[48:51], v[224:227], v[162:165], v[48:51]
	v_mfma_f32_16x16x32_bf16 v[36:39], v[194:197], v[170:173], v[36:39]
	v_mfma_f32_16x16x32_bf16 v[32:35], v[224:227], v[170:173], v[32:35]
	v_mfma_f32_16x16x32_bf16 v[20:23], v[194:197], v[178:181], v[20:23]
	v_mfma_f32_16x16x32_bf16 v[16:19], v[224:227], v[178:181], v[16:19]
	v_mfma_f32_16x16x32_bf16 v[4:7], v[194:197], v[186:189], v[4:7]
	v_mfma_f32_16x16x32_bf16 v[0:3], v[224:227], v[186:189], v[0:3]
	s_setprio 1
	s_add_i32 s43, 0, 0x18000
	v_add_u32_e32 v154, s43, v143
	s_barrier
	ds_read_b128 v[136:139], v154
	ds_read_b128 v[146:149], v154 offset:1024
	ds_read_b128 v[150:153], v154 offset:2048
	ds_read_b128 v[154:157], v154 offset:3072
	s_add_u32 s0, s2, 0x84000
	s_addc_u32 s1, s3, 0
	s_mov_b32 m0, s14
	v_lshl_add_u64 v[190:191], s[0:1], 0, v[64:65]
	ds_read_b128 v[158:161], v145 offset:32768
	ds_read_b128 v[162:165], v145 offset:33792
	ds_read_b128 v[166:169], v145 offset:34816
	ds_read_b128 v[170:173], v145 offset:35840
	ds_read_b128 v[174:177], v145 offset:36864
	ds_read_b128 v[178:181], v145 offset:37888
	ds_read_b128 v[182:185], v145 offset:38912
	ds_read_b128 v[186:189], v145 offset:39936
	global_load_lds_dwordx4 v[190:191], off
	v_lshl_add_u64 v[190:191], s[0:1], 0, v[130:131]
	s_mov_b32 m0, s15
	s_nop 0
	global_load_lds_dwordx4 v[190:191], off
	s_waitcnt lgkmcnt(8)
	s_barrier
	s_waitcnt lgkmcnt(0)
	s_setprio 0
	s_waitcnt lgkmcnt(0)
	v_mfma_f32_16x16x32_bf16 v[126:129], v[136:139], v[158:161], v[126:129]
	v_mfma_f32_16x16x32_bf16 v[122:125], v[150:153], v[158:161], v[122:125]
	v_mfma_f32_16x16x32_bf16 v[110:113], v[136:139], v[166:169], v[110:113]
	v_mfma_f32_16x16x32_bf16 v[106:109], v[150:153], v[166:169], v[106:109]
	v_mfma_f32_16x16x32_bf16 v[94:97], v[136:139], v[174:177], v[94:97]
	v_mfma_f32_16x16x32_bf16 v[90:93], v[150:153], v[174:177], v[90:93]
	v_mfma_f32_16x16x32_bf16 v[78:81], v[136:139], v[182:185], v[78:81]
	v_mfma_f32_16x16x32_bf16 v[74:77], v[150:153], v[182:185], v[74:77]
	v_mfma_f32_16x16x32_bf16 v[126:129], v[146:149], v[162:165], v[126:129]
	v_mfma_f32_16x16x32_bf16 v[122:125], v[154:157], v[162:165], v[122:125]
	v_mfma_f32_16x16x32_bf16 v[110:113], v[146:149], v[170:173], v[110:113]
	v_mfma_f32_16x16x32_bf16 v[106:109], v[154:157], v[170:173], v[106:109]
	v_mfma_f32_16x16x32_bf16 v[94:97], v[146:149], v[178:181], v[94:97]
	v_mfma_f32_16x16x32_bf16 v[90:93], v[154:157], v[178:181], v[90:93]
	v_mfma_f32_16x16x32_bf16 v[78:81], v[146:149], v[186:189], v[78:81]
	v_mfma_f32_16x16x32_bf16 v[74:77], v[154:157], v[186:189], v[74:77]
	s_setprio 1
	s_barrier
	s_add_i32 s2, 0, 0x1c000
	s_add_i32 s0, s43, s11
	v_add_u32_e32 v208, s2, v143
	v_lshl_add_u64 v[140:141], v[140:141], 0, s[16:17]
	s_mov_b32 m0, s0
	ds_read_b128 v[190:193], v208
	ds_read_b128 v[194:197], v208 offset:1024
	ds_read_b128 v[220:223], v208 offset:2048
	ds_read_b128 v[224:227], v208 offset:3072
	global_load_lds_dwordx4 v[140:141], off
	v_lshl_add_u64 v[140:141], v[198:199], 0, s[16:17]
	s_add_i32 m0, s0, 0x2000
	s_nop 0
	global_load_lds_dwordx4 v[140:141], off
	s_barrier
	s_waitcnt lgkmcnt(0)
	s_setprio 0
	s_waitcnt lgkmcnt(0)
	v_mfma_f32_16x16x32_bf16 v[118:121], v[190:193], v[158:161], v[118:121]
	v_mfma_f32_16x16x32_bf16 v[114:117], v[220:223], v[158:161], v[114:117]
	v_mfma_f32_16x16x32_bf16 v[102:105], v[190:193], v[166:169], v[102:105]
	v_mfma_f32_16x16x32_bf16 v[98:101], v[220:223], v[166:169], v[98:101]
	v_mfma_f32_16x16x32_bf16 v[86:89], v[190:193], v[174:177], v[86:89]
	v_mfma_f32_16x16x32_bf16 v[82:85], v[220:223], v[174:177], v[82:85]
	v_mfma_f32_16x16x32_bf16 v[70:73], v[190:193], v[182:185], v[70:73]
	v_mfma_f32_16x16x32_bf16 v[66:69], v[220:223], v[182:185], v[66:69]
	v_mfma_f32_16x16x32_bf16 v[118:121], v[194:197], v[162:165], v[118:121]
	v_mfma_f32_16x16x32_bf16 v[114:117], v[224:227], v[162:165], v[114:117]
	v_mfma_f32_16x16x32_bf16 v[102:105], v[194:197], v[170:173], v[102:105]
	v_mfma_f32_16x16x32_bf16 v[98:101], v[224:227], v[170:173], v[98:101]
	v_mfma_f32_16x16x32_bf16 v[86:89], v[194:197], v[178:181], v[86:89]
	v_mfma_f32_16x16x32_bf16 v[82:85], v[224:227], v[178:181], v[82:85]
	v_mfma_f32_16x16x32_bf16 v[70:73], v[194:197], v[186:189], v[70:73]
	v_mfma_f32_16x16x32_bf16 v[66:69], v[224:227], v[186:189], v[66:69]
	s_setprio 1
	s_mov_b32 m0, s24
	v_lshl_add_u64 v[140:141], v[228:229], 0, s[16:17]
	s_barrier
; #define PG8_STAGE(bufoff, gbase, voff) do { _Pragma("unroll") for (int _i = 0; _i < 2; ++_i) \
;         __builtin_amdgcn_global_load_lds((const unsigned*)((const char*)(gbase) + (voff)[_i]), (LAS unsigned*)(lds + (bufoff) + ldsw + _i * 8192), 16, 0, 0); } while (0)
; #define PG8_LDA(dst, b, h) do { _Pragma("unroll") for (int m = 0; m < 4; ++m) _Pragma("unroll") for (int k = 0; k < 2; ++k) dst[m][k] = *(const LAS bf16x8*)(lds + PG8_SA(b, h) + aoff + m * 2048 + k * 1024); } while (0)
; #define PG8_MMA(ai, bj, At, Bt) do { __builtin_amdgcn_s_setprio(1); _Pragma("unroll") for (int m = 0; m < 4; ++m) _Pragma("unroll") for (int n = 0; n < 2; ++n) _Pragma("unroll") for (int k = 0; k < 2; ++k) \
;         acc[ai][bj][m][n] = __builtin_amdgcn_mfma_f32_16x16x32_bf16(Bt[n][k], At[m][k], acc[ai][bj][m][n], 0, 0, 0); __builtin_amdgcn_s_setprio(0); } while (0)
; #define PG8_WAIT_V(n) asm volatile("s_waitcnt vmcnt(" #n ")" ::: "memory")
; #define PG8_WAIT_L(n) asm volatile("s_waitcnt lgkmcnt(" #n ")" ::: "memory")
; #define PG8_BAR __builtin_amdgcn_s_barrier()
; #define PG8_SCHED __builtin_amdgcn_sched_barrier(0)
; __device__ __forceinline__ f32x4 gelu4(const f32x4 x) {
;     const f32x4 t = x * x, a = x * (t * -0.10294324f + -2.3022082f);
;     f32x4 e; e[0] = __builtin_amdgcn_exp2f(a[0]); e[1] = __builtin_amdgcn_exp2f(a[1]); e[2] = __builtin_amdgcn_exp2f(a[2]); e[3] = __builtin_amdgcn_exp2f(a[3]);
;     const f32x4 d = e + 1.0f;
;     f32x4 r; r[0] = __builtin_amdgcn_rcpf(d[0]); r[1] = __builtin_amdgcn_rcpf(d[1]); r[2] = __builtin_amdgcn_rcpf(d[2]); r[3] = __builtin_amdgcn_rcpf(d[3]);
;     return x * r;
; }
;     ...
;             PG8_LDA(At, 1, 1); PG8_STAGE(PG8_SA(1, 0), a3, voffA);
;             PG8_BAR; PG8_WAIT_L(0); PG8_MMA(1, 0, At, B0); PG8_BAR; PG8_SCHED;
;             PG8_STAGE(PG8_SB(1, 1), b3 + hstep, voffB);
;             PG8_WAIT_V(6); PG8_BAR; PG8_MMA(1, 1, At, B1); PG8_BAR;
	ds_read_b128 v[158:161], v145 offset:49152
	ds_read_b128 v[162:165], v145 offset:50176
	ds_read_b128 v[166:169], v145 offset:51200
	ds_read_b128 v[170:173], v145 offset:52224
	ds_read_b128 v[174:177], v145 offset:53248
	ds_read_b128 v[178:181], v145 offset:54272
	ds_read_b128 v[182:185], v145 offset:55296
	ds_read_b128 v[186:189], v145 offset:56320
	global_load_lds_dwordx4 v[140:141], off
	v_lshl_add_u64 v[140:141], v[230:231], 0, s[16:17]
	s_mov_b32 m0, s25
	s_nop 0
	global_load_lds_dwordx4 v[140:141], off
	s_barrier
	s_waitcnt lgkmcnt(0)
	s_setprio 0
	s_waitcnt lgkmcnt(0)
	v_mfma_f32_16x16x32_bf16 v[60:63], v[136:139], v[158:161], v[60:63]
	v_mfma_f32_16x16x32_bf16 v[56:59], v[150:153], v[158:161], v[56:59]
	v_mfma_f32_16x16x32_bf16 v[44:47], v[136:139], v[166:169], v[44:47]
	v_mfma_f32_16x16x32_bf16 v[40:43], v[150:153], v[166:169], v[40:43]
	v_mfma_f32_16x16x32_bf16 v[28:31], v[136:139], v[174:177], v[28:31]
	v_mfma_f32_16x16x32_bf16 v[24:27], v[150:153], v[174:177], v[24:27]
	v_mfma_f32_16x16x32_bf16 v[12:15], v[136:139], v[182:185], v[12:15]
	v_mfma_f32_16x16x32_bf16 v[8:11], v[150:153], v[182:185], v[8:11]
	v_mfma_f32_16x16x32_bf16 v[60:63], v[146:149], v[162:165], v[60:63]
	v_mfma_f32_16x16x32_bf16 v[56:59], v[154:157], v[162:165], v[56:59]
	v_mfma_f32_16x16x32_bf16 v[44:47], v[146:149], v[170:173], v[44:47]
	v_mfma_f32_16x16x32_bf16 v[40:43], v[154:157], v[170:173], v[40:43]
	v_mfma_f32_16x16x32_bf16 v[28:31], v[146:149], v[178:181], v[28:31]
	v_mfma_f32_16x16x32_bf16 v[24:27], v[154:157], v[178:181], v[24:27]
	v_mfma_f32_16x16x32_bf16 v[12:15], v[146:149], v[186:189], v[12:15]
	v_mfma_f32_16x16x32_bf16 v[8:11], v[154:157], v[186:189], v[8:11]
	s_setprio 1
	s_barrier
	s_add_u32 s0, s8, 0x84080
	s_addc_u32 s1, s9, 0
	s_add_i32 s2, s2, s11
	v_lshl_add_u64 v[136:137], s[0:1], 0, v[64:65]
	s_mov_b32 m0, s2
	s_nop 0
	global_load_lds_dwordx4 v[136:137], off
	v_lshl_add_u64 v[136:137], s[0:1], 0, v[130:131]
	s_add_i32 m0, s2, 0x2000
	s_nop 0
	global_load_lds_dwordx4 v[136:137], off
	s_waitcnt vmcnt(6)
	s_barrier
	s_setprio 0
	v_mfma_f32_16x16x32_bf16 v[52:55], v[190:193], v[158:161], v[52:55]
	v_mfma_f32_16x16x32_bf16 v[48:51], v[220:223], v[158:161], v[48:51]
	v_mfma_f32_16x16x32_bf16 v[36:39], v[190:193], v[166:169], v[36:39]
	v_mfma_f32_16x16x32_bf16 v[32:35], v[220:223], v[166:169], v[32:35]
	v_mfma_f32_16x16x32_bf16 v[20:23], v[190:193], v[174:177], v[20:23]
	v_mfma_f32_16x16x32_bf16 v[16:19], v[220:223], v[174:177], v[16:19]
	v_mfma_f32_16x16x32_bf16 v[4:7], v[190:193], v[182:185], v[4:7]
	v_mfma_f32_16x16x32_bf16 v[0:3], v[220:223], v[182:185], v[0:3]
	v_mfma_f32_16x16x32_bf16 v[52:55], v[194:197], v[162:165], v[52:55]
	v_mfma_f32_16x16x32_bf16 v[48:51], v[224:227], v[162:165], v[48:51]
	v_mfma_f32_16x16x32_bf16 v[36:39], v[194:197], v[170:173], v[36:39]
	v_mfma_f32_16x16x32_bf16 v[32:35], v[224:227], v[170:173], v[32:35]
	v_mfma_f32_16x16x32_bf16 v[20:23], v[194:197], v[178:181], v[20:23]
	v_mfma_f32_16x16x32_bf16 v[16:19], v[224:227], v[178:181], v[16:19]
	v_mfma_f32_16x16x32_bf16 v[4:7], v[194:197], v[186:189], v[4:7]
	v_mfma_f32_16x16x32_bf16 v[0:3], v[224:227], v[186:189], v[0:3]
	s_setprio 1
	s_add_i32 s42, s42, 2
	s_add_u32 s40, s40, 0x100
	s_addc_u32 s41, s41, 0
	s_cmp_gt_u32 s42, 29
	s_mov_b64 s[0:1], s[4:5]
	s_barrier
	s_cbranch_scc0 .LBB0_1441
	s_add_i32 s0, s38, -2
	s_cmp_lt_u32 s0, 8
	s_cselect_b64 s[2:3], -1, 0
	s_cmp_gt_u32 s0, 7
	s_cbranch_scc1 .LBB0_1444
	s_mov_b32 s40, 0xc0135761
	v_pk_mul_f32 v[136:137], v[128:129], v[128:129]
	v_pk_mul_f32 v[138:139], v[126:127], v[126:127]
	v_mov_b64_e32 v[140:141], s[40:41]
	s_mov_b32 s0, 0xbdd2d3e8
	v_pk_fma_f32 v[136:137], v[136:137], s[0:1], v[140:141] op_sel_hi:[1,0,0]
	v_pk_fma_f32 v[138:139], v[138:139], s[0:1], v[140:141] op_sel_hi:[1,0,0]
	v_pk_mul_f32 v[136:137], v[128:129], v[136:137]
	v_pk_mul_f32 v[138:139], v[126:127], v[138:139]
	v_exp_f32_e32 v136, v136
	v_exp_f32_e32 v138, v138
	v_exp_f32_e32 v137, v137
	v_exp_f32_e32 v139, v139
	v_pk_add_f32 v[136:137], v[136:137], 1.0 op_sel_hi:[1,0]
	v_pk_add_f32 v[138:139], v[138:139], 1.0 op_sel_hi:[1,0]
	v_rcp_f32_e32 v136, v136
	v_rcp_f32_e32 v138, v138
	v_rcp_f32_e32 v137, v137
	v_rcp_f32_e32 v139, v139
	v_pk_mul_f32 v[128:129], v[128:129], v[136:137]
	v_pk_mul_f32 v[126:127], v[126:127], v[138:139]
	s_branch .LBB0_1445
